# write-through (sc1) stores in prologue/in-proj/qk-norm/conv+attention/out-proj phases so the grid-barrier L2 writeback has less dirty data
# baseline (speedup 1.0000x reference)
; #define LAS __attribute__((address_space(3)))
; __device__ __forceinline__ unsigned pk2(float lo, float hi) { return pg8::cvt_pk_bf16(lo, hi); }
; #define LDS_WAIT() asm volatile("s_waitcnt lgkmcnt(0)" ::: "memory")
; __device__ __forceinline__ void transpose_item(const float* W, int K, int N, int k0, int n0, bf16* dst, const float* kscale, LAS unsigned char* scr, int lane) {
;     ...
;     for (int j = 0; j < 8; ++j) { const int k = 8 * j + 2 * r; float s0 = 1.0f, s1 = 1.0f; if (kscale) { const f32x2 sc = *(const f32x2*)(kscale + k0 + k); s0 = sc.x; s1 = sc.y; }
; #pragma unroll
;         for (int i = 0; i < 4; ++i) { const int n = 4 * c + i; *(LAS unsigned*)(scr + n * 128 + ((j ^ (c & 7)) << 4) + 4 * r) = pk2(v[2 * j][i] * s0, v[2 * j + 1][i] * s1); } }
;     LDS_WAIT(); asm volatile("" ::: "memory");
;     const int rr = lane >> 3, cc = lane & 7;
; #pragma unroll
;     for (int j = 0; j < 8; ++j) { const int n = 8 * j + rr; const v4u o = *(const LAS v4u*)(scr + n * 128 + ((cc ^ ((n >> 2) & 7)) << 4)); *(v4u*)(dst + (size_t)n * K + k0 + 8 * cc) = o; }
;     LDS_WAIT(); asm volatile("" ::: "memory");
.LBB0_9:
	s_waitcnt vmcnt(0)
	v_mul_f32_e32 v2, v2, v18
	v_mul_f32_e32 v6, v6, v19
	v_cvt_pk_bf16_f32 v2, v2, v6
	v_add_u32_e32 v6, v69, v107
	ds_write_b32 v6, v2
	v_mul_f32_e32 v2, v3, v18
	v_mul_f32_e32 v3, v7, v19
	v_cvt_pk_bf16_f32 v2, v2, v3
	ds_write_b32 v6, v2 offset:128
	v_mul_f32_e32 v2, v4, v18
	v_mul_f32_e32 v3, v8, v19
	v_cvt_pk_bf16_f32 v2, v2, v3
	ds_write_b32 v6, v2 offset:256
	v_mul_f32_e32 v2, v5, v18
	v_mul_f32_e32 v3, v9, v19
	v_cvt_pk_bf16_f32 v2, v2, v3
	ds_write_b32 v6, v2 offset:384
	s_lshl_b64 s[2:3], s[40:41], 12
	s_waitcnt lgkmcnt(0)
	s_add_u32 s40, s54, s2
	v_add_u32_e32 v2, v112, v113
	s_addc_u32 s41, s55, s3
	s_lshl_b64 s[2:3], s[56:57], 1
	ds_read_b128 v[2:5], v2
	s_add_u32 s2, s40, s2
	s_addc_u32 s3, s41, s3
	v_lshlrev_b32_e32 v70, 1, v68
	v_lshl_add_u64 v[6:7], s[2:3], 0, v[70:71]
	v_lshlrev_b32_e32 v70, 1, v92
	v_lshl_add_u64 v[8:9], v[6:7], 0, v[70:71]
	s_waitcnt lgkmcnt(0)
	flat_store_dwordx4 v[8:9], v[2:5] sc1
	v_lshlrev_b32_e32 v70, 1, v94
	v_lshl_add_u64 v[8:9], v[6:7], 0, v[70:71]
	v_add_u32_e32 v2, v114, v115
	ds_read_b128 v[2:5], v2
	v_lshlrev_b32_e32 v70, 1, v96
	s_waitcnt lgkmcnt(0)
	flat_store_dwordx4 v[8:9], v[2:5] sc1
	s_nop 1
	v_add_u32_e32 v2, v116, v117
	ds_read_b128 v[2:5], v2
	v_lshl_add_u64 v[8:9], v[6:7], 0, v[70:71]
	v_lshlrev_b32_e32 v70, 1, v98
	s_waitcnt lgkmcnt(0)
	flat_store_dwordx4 v[8:9], v[2:5] sc1
	s_nop 1
	v_add_u32_e32 v2, v118, v119
	ds_read_b128 v[2:5], v2
	v_lshl_add_u64 v[8:9], v[6:7], 0, v[70:71]
	v_lshlrev_b32_e32 v70, 1, v100
	s_waitcnt lgkmcnt(0)
	flat_store_dwordx4 v[8:9], v[2:5] sc1
	s_nop 1
	v_add_u32_e32 v2, v120, v113
	ds_read_b128 v[2:5], v2
	v_lshl_add_u64 v[8:9], v[6:7], 0, v[70:71]
	v_lshlrev_b32_e32 v70, 1, v102
	s_waitcnt lgkmcnt(0)
	flat_store_dwordx4 v[8:9], v[2:5] sc1
	s_nop 1
	v_add_u32_e32 v2, v121, v122
	ds_read_b128 v[2:5], v2
	v_lshl_add_u64 v[8:9], v[6:7], 0, v[70:71]
	v_lshlrev_b32_e32 v70, 1, v104
	s_waitcnt lgkmcnt(0)
	flat_store_dwordx4 v[8:9], v[2:5] sc1
	s_nop 1
	v_add_u32_e32 v2, v123, v124
	ds_read_b128 v[2:5], v2
	v_lshl_add_u64 v[8:9], v[6:7], 0, v[70:71]
	v_lshlrev_b32_e32 v70, 1, v106
	v_lshl_add_u64 v[6:7], v[6:7], 0, v[70:71]
	s_waitcnt lgkmcnt(0)
	flat_store_dwordx4 v[8:9], v[2:5] sc1
	s_nop 1
	v_add_u32_e32 v2, v125, v126
	ds_read_b128 v[2:5], v2
	s_waitcnt lgkmcnt(0)
	flat_store_dwordx4 v[6:7], v[2:5] sc1
	s_waitcnt lgkmcnt(0)

; #define LAS __attribute__((address_space(3)))
; __device__ __forceinline__ void transpose_item(const float* W, int K, int N, int k0, int n0, bf16* dst, const float* kscale, LAS unsigned char* scr, int lane) {
;     const int r = lane >> 4, c = lane & 15;
;     f32x4 v[16];
; #pragma unroll
;     for (int j = 0; j < 8; ++j)
; #pragma unroll
;         for (int p = 0; p < 2; ++p) v[2 * j + p] = *(const f32x4*)(W + (size_t)(k0 + 8 * j + 2 * r + p) * N + n0 + 4 * c);
; #pragma unroll
; __device__ __forceinline__ void p0_prologue(const Ptrs& P, LAS unsigned char* lds, int gw, int NGW, int wave, int lane) {
;     ...
;     for (int it = gw; it < NITEMS; it += NGW) {
;         int r = it;
;         if (r < I_IN) { const int kb = r / 80, n0 = (r % 80) * 64; bf16* dst;
;             if (n0 < 2048) dst = P.Wt_in + (size_t)n0 * DM;
;             else if (n0 < 3072) dst = P.Wt_v + (size_t)(n0 - 2048) * DM;
;             else if (n0 < 4096) { const int ch = n0 - 3072; dst = P.Wt_in + (size_t)(2048 + (ch >> 7) * 256 + (ch & 127)) * DM; }
;             else { const int ch = n0 - 4096; dst = P.Wt_in + (size_t)(2048 + (ch >> 7) * 256 + 128 + (ch & 127)) * DM; }
;             transpose_item(P.w_in, DM, IN_COLS, kb * 64, n0, dst, P.norm1_g, scr, lane); continue; }
;         r -= I_IN;
;         if (r < I_OUT) { const int kb = r / 32, n0 = (r % 32) * 64; transpose_item(P.w_out, DM, DM, kb * 64, n0, P.Wt_out + (size_t)n0 * DM, nullptr, scr, lane); continue; }
;         r -= I_OUT;
;         if (r < I_G) { const int kb = r / 88, n0 = (r % 88) * 64; transpose_item(P.w_gate, DM, FFN, kb * 64, n0, P.Wt_gu + (size_t)((n0 >> 7) * 256 + (n0 & 127)) * DM, P.norm2_g, scr, lane); continue; }
;         r -= I_G;
;         if (r < I_G) { const int kb = r / 88, n0 = (r % 88) * 64; transpose_item(P.w_up, DM, FFN, kb * 64, n0, P.Wt_gu + (size_t)((n0 >> 7) * 256 + 128 + (n0 & 127)) * DM, P.norm2_g, scr, lane); continue; }
;         r -= I_G;
;         { const int kb = r / 32, n0 = (r % 32) * 64; transpose_item(P.w_down, FFN, DM, kb * 64, n0, P.Wt_dn + (size_t)n0 * FFN, nullptr, scr, lane); }
.LBB0_11:
	s_cmpk_gt_i32 s99, 0x9ff
	s_mov_b64 s[2:3], -1
	s_cbranch_scc0 .LBB0_57
	s_cmpk_gt_u32 s99, 0xdff
	s_cbranch_scc0 .LBB0_54
	s_cmpk_gt_u32 s99, 0x18ff
	s_cbranch_scc0 .LBB0_35
	s_cmpk_gt_u32 s99, 0x23ff
	s_cbranch_scc0 .LBB0_16
	s_and_b32 s3, s79, 0x7c0
	s_and_b32 s2, s83, 0x7fffffc0
	s_addk_i32 s2, 0xb800
	s_mul_i32 s40, s3, 0x2c00
	s_add_u32 s40, s72, s40
	v_or_b32_e32 v70, s2, v66
	s_addc_u32 s41, s73, 0
	s_lshl_b32 s66, s3, 2
	v_or_b32_e32 v4, 1, v70
	v_mov_b32_e32 v5, v71
	v_lshl_add_u64 v[58:59], v[72:73], 0, s[66:67]
	v_lshlrev_b64 v[2:3], 13, v[70:71]
	v_lshlrev_b64 v[4:5], 13, v[4:5]
	v_lshl_add_u64 v[2:3], v[58:59], 0, v[2:3]
	v_lshl_add_u64 v[6:7], v[58:59], 0, v[4:5]
	global_load_dwordx4 v[2:5], v[2:3], off
	s_nop 0
	global_load_dwordx4 v[6:9], v[6:7], off
	v_or_b32_e32 v10, 8, v70
	v_mov_b32_e32 v11, v71
	v_or_b32_e32 v12, 9, v70
	v_mov_b32_e32 v13, v71
	v_lshlrev_b64 v[10:11], 13, v[10:11]
	v_lshlrev_b64 v[12:13], 13, v[12:13]
	v_lshl_add_u64 v[10:11], v[58:59], 0, v[10:11]
	v_lshl_add_u64 v[14:15], v[58:59], 0, v[12:13]
	global_load_dwordx4 v[10:13], v[10:11], off
	s_nop 0
	global_load_dwordx4 v[14:17], v[14:15], off
	v_or_b32_e32 v18, 16, v70
	v_mov_b32_e32 v19, v71
	v_or_b32_e32 v20, 17, v70
	v_mov_b32_e32 v21, v71
	v_lshlrev_b64 v[18:19], 13, v[18:19]
	v_lshlrev_b64 v[20:21], 13, v[20:21]
	v_lshl_add_u64 v[18:19], v[58:59], 0, v[18:19]
	v_lshl_add_u64 v[22:23], v[58:59], 0, v[20:21]
	global_load_dwordx4 v[18:21], v[18:19], off
	s_nop 0
	global_load_dwordx4 v[22:25], v[22:23], off
	v_or_b32_e32 v26, 24, v70
	v_mov_b32_e32 v27, v71
	v_or_b32_e32 v28, 25, v70
	v_mov_b32_e32 v29, v71
	v_lshlrev_b64 v[26:27], 13, v[26:27]
	v_lshlrev_b64 v[28:29], 13, v[28:29]
	v_lshl_add_u64 v[26:27], v[58:59], 0, v[26:27]
	v_lshl_add_u64 v[30:31], v[58:59], 0, v[28:29]
	global_load_dwordx4 v[26:29], v[26:27], off
	s_nop 0
	global_load_dwordx4 v[30:33], v[30:31], off
	v_or_b32_e32 v34, 32, v70
	v_mov_b32_e32 v35, v71
	v_or_b32_e32 v36, 33, v70
	v_mov_b32_e32 v37, v71
	v_lshlrev_b64 v[34:35], 13, v[34:35]
	v_lshlrev_b64 v[36:37], 13, v[36:37]
	v_lshl_add_u64 v[34:35], v[58:59], 0, v[34:35]
	v_lshl_add_u64 v[38:39], v[58:59], 0, v[36:37]
	global_load_dwordx4 v[34:37], v[34:35], off
	s_nop 0
	global_load_dwordx4 v[38:41], v[38:39], off
	v_or_b32_e32 v42, 40, v70
	v_mov_b32_e32 v43, v71
	v_or_b32_e32 v44, 41, v70
	v_mov_b32_e32 v45, v71
	v_lshlrev_b64 v[42:43], 13, v[42:43]
	v_lshlrev_b64 v[44:45], 13, v[44:45]
	v_lshl_add_u64 v[42:43], v[58:59], 0, v[42:43]
	v_lshl_add_u64 v[46:47], v[58:59], 0, v[44:45]
	global_load_dwordx4 v[42:45], v[42:43], off
	s_nop 0
	global_load_dwordx4 v[46:49], v[46:47], off
	v_or_b32_e32 v50, 48, v70
	v_mov_b32_e32 v51, v71
	v_or_b32_e32 v52, 49, v70
	v_mov_b32_e32 v53, v71
	v_lshlrev_b64 v[50:51], 13, v[50:51]
	v_lshlrev_b64 v[52:53], 13, v[52:53]
	v_lshl_add_u64 v[50:51], v[58:59], 0, v[50:51]
	v_lshl_add_u64 v[54:55], v[58:59], 0, v[52:53]
	global_load_dwordx4 v[50:53], v[50:51], off
	s_nop 0
	global_load_dwordx4 v[54:57], v[54:55], off
	v_or_b32_e32 v60, 56, v70
	v_mov_b32_e32 v61, v71
	v_or_b32_e32 v70, 57, v70
	v_lshlrev_b64 v[60:61], 13, v[60:61]
	v_lshlrev_b64 v[62:63], 13, v[70:71]
	v_lshl_add_u64 v[60:61], v[58:59], 0, v[60:61]
	v_lshl_add_u64 v[62:63], v[58:59], 0, v[62:63]
	global_load_dwordx4 v[58:61], v[60:61], off
	s_nop 0
	global_load_dwordx4 v[62:65], v[62:63], off
	s_mov_b32 s3, s67
	s_lshl_b64 s[2:3], s[2:3], 1
	s_add_u32 s2, s40, s2
	s_addc_u32 s3, s41, s3
	v_lshlrev_b32_e32 v70, 1, v68
	v_mov_b32_e32 v81, v71
	v_mov_b32_e32 v83, v71
	v_mov_b32_e32 v85, v71
	s_waitcnt vmcnt(0)
	v_cvt_pk_bf16_f32 v2, v2, v6
	v_add_u32_e32 v6, v69, v93
	ds_write_b32 v6, v2
	v_cvt_pk_bf16_f32 v2, v3, v7
	ds_write_b32 v6, v2 offset:128
	v_cvt_pk_bf16_f32 v2, v4, v8
	ds_write_b32 v6, v2 offset:256
	v_cvt_pk_bf16_f32 v2, v5, v9
	ds_write_b32 v6, v2 offset:384
	s_waitcnt vmcnt(12)
; #define LAS __attribute__((address_space(3)))
; __device__ __forceinline__ unsigned pk2(float lo, float hi) { return pg8::cvt_pk_bf16(lo, hi); }
; #define LDS_WAIT() asm volatile("s_waitcnt lgkmcnt(0)" ::: "memory")
; __device__ __forceinline__ void transpose_item(const float* W, int K, int N, int k0, int n0, bf16* dst, const float* kscale, LAS unsigned char* scr, int lane) {
;     ...
;     for (int j = 0; j < 8; ++j) { const int k = 8 * j + 2 * r; float s0 = 1.0f, s1 = 1.0f; if (kscale) { const f32x2 sc = *(const f32x2*)(kscale + k0 + k); s0 = sc.x; s1 = sc.y; }
; #pragma unroll
;         for (int i = 0; i < 4; ++i) { const int n = 4 * c + i; *(LAS unsigned*)(scr + n * 128 + ((j ^ (c & 7)) << 4) + 4 * r) = pk2(v[2 * j][i] * s0, v[2 * j + 1][i] * s1); } }
;     LDS_WAIT(); asm volatile("" ::: "memory");
;     const int rr = lane >> 3, cc = lane & 7;
; #pragma unroll
;     for (int j = 0; j < 8; ++j) { const int n = 8 * j + rr; const v4u o = *(const LAS v4u*)(scr + n * 128 + ((cc ^ ((n >> 2) & 7)) << 4)); *(v4u*)(dst + (size_t)n * K + k0 + 8 * cc) = o; }
;     LDS_WAIT(); asm volatile("" ::: "memory");
	v_cvt_pk_bf16_f32 v2, v10, v14
	v_add_u32_e32 v3, v69, v95
	ds_write_b32 v3, v2
	v_cvt_pk_bf16_f32 v2, v11, v15
	ds_write_b32 v3, v2 offset:128
	v_cvt_pk_bf16_f32 v2, v12, v16
	ds_write_b32 v3, v2 offset:256
	v_cvt_pk_bf16_f32 v2, v13, v17
	ds_write_b32 v3, v2 offset:384
	s_waitcnt vmcnt(10)
	v_cvt_pk_bf16_f32 v2, v18, v22
	v_add_u32_e32 v3, v69, v97
	ds_write_b32 v3, v2
	v_cvt_pk_bf16_f32 v2, v19, v23
	ds_write_b32 v3, v2 offset:128
	v_cvt_pk_bf16_f32 v2, v20, v24
	ds_write_b32 v3, v2 offset:256
	v_cvt_pk_bf16_f32 v2, v21, v25
	ds_write_b32 v3, v2 offset:384
	s_waitcnt vmcnt(8)
	v_cvt_pk_bf16_f32 v2, v26, v30
	v_add_u32_e32 v3, v69, v99
	ds_write_b32 v3, v2
	v_cvt_pk_bf16_f32 v2, v27, v31
	ds_write_b32 v3, v2 offset:128
	v_cvt_pk_bf16_f32 v2, v28, v32
	ds_write_b32 v3, v2 offset:256
	v_cvt_pk_bf16_f32 v2, v29, v33
	ds_write_b32 v3, v2 offset:384
	s_waitcnt vmcnt(6)
	v_cvt_pk_bf16_f32 v2, v34, v38
	v_add_u32_e32 v3, v69, v101
	ds_write_b32 v3, v2
	v_cvt_pk_bf16_f32 v2, v35, v39
	ds_write_b32 v3, v2 offset:128
	v_cvt_pk_bf16_f32 v2, v36, v40
	ds_write_b32 v3, v2 offset:256
	v_cvt_pk_bf16_f32 v2, v37, v41
	ds_write_b32 v3, v2 offset:384
	s_waitcnt vmcnt(4)
	v_cvt_pk_bf16_f32 v2, v42, v46
	v_add_u32_e32 v3, v69, v103
	ds_write_b32 v3, v2
	v_cvt_pk_bf16_f32 v2, v43, v47
	ds_write_b32 v3, v2 offset:128
	v_cvt_pk_bf16_f32 v2, v44, v48
	ds_write_b32 v3, v2 offset:256
	v_cvt_pk_bf16_f32 v2, v45, v49
	ds_write_b32 v3, v2 offset:384
	s_waitcnt vmcnt(2)
	v_cvt_pk_bf16_f32 v2, v50, v54
	v_add_u32_e32 v3, v69, v105
	ds_write_b32 v3, v2
	v_cvt_pk_bf16_f32 v2, v51, v55
	ds_write_b32 v3, v2 offset:128
	v_cvt_pk_bf16_f32 v2, v52, v56
	ds_write_b32 v3, v2 offset:256
	v_cvt_pk_bf16_f32 v2, v53, v57
	ds_write_b32 v3, v2 offset:384
	s_waitcnt vmcnt(0)
	v_cvt_pk_bf16_f32 v2, v58, v62
	v_add_u32_e32 v3, v69, v107
	ds_write_b32 v3, v2
	v_cvt_pk_bf16_f32 v2, v59, v63
	ds_write_b32 v3, v2 offset:128
	v_cvt_pk_bf16_f32 v2, v60, v64
	ds_write_b32 v3, v2 offset:256
	v_cvt_pk_bf16_f32 v2, v61, v65
	ds_write_b32 v3, v2 offset:384
	s_waitcnt lgkmcnt(0)
	v_add_u32_e32 v2, v112, v113
	ds_read_b128 v[2:5], v2
	v_lshl_add_u64 v[6:7], s[2:3], 0, v[70:71]
	v_lshl_add_u64 v[8:9], v[6:7], 0, v[80:81]
	v_add_co_u32_e32 v10, vcc, s85, v8
	s_waitcnt lgkmcnt(0)
	flat_store_dwordx4 v[8:9], v[2:5] sc1
	v_addc_co_u32_e32 v11, vcc, 0, v9, vcc
	s_nop 0
	v_add_u32_e32 v2, v114, v115
	ds_read_b128 v[2:5], v2
	v_mov_b32_e32 v87, v71
	v_mov_b32_e32 v89, v71
	s_mov_b64 s[2:3], 0
	s_waitcnt lgkmcnt(0)
	flat_store_dwordx4 v[10:11], v[2:5] sc1
	v_add_co_u32_e32 v10, vcc, s77, v8
	s_nop 0
	v_add_u32_e32 v2, v116, v117
	ds_read_b128 v[2:5], v2
	v_addc_co_u32_e32 v11, vcc, 0, v9, vcc
	v_add_co_u32_e32 v8, vcc, s78, v8
	s_waitcnt lgkmcnt(0)
	flat_store_dwordx4 v[10:11], v[2:5] sc1
	v_addc_co_u32_e32 v9, vcc, 0, v9, vcc
	s_nop 0
	v_add_u32_e32 v2, v118, v119
	ds_read_b128 v[2:5], v2
	s_waitcnt lgkmcnt(0)
	flat_store_dwordx4 v[8:9], v[2:5] sc1
	s_nop 1
	v_add_u32_e32 v2, v120, v113
	ds_read_b128 v[2:5], v2
	v_lshl_add_u64 v[8:9], v[6:7], 0, v[82:83]
	s_waitcnt lgkmcnt(0)
	flat_store_dwordx4 v[8:9], v[2:5] sc1
	s_nop 1
	v_add_u32_e32 v2, v121, v122
	ds_read_b128 v[2:5], v2
	v_lshl_add_u64 v[8:9], v[6:7], 0, v[84:85]
	s_waitcnt lgkmcnt(0)
	flat_store_dwordx4 v[8:9], v[2:5] sc1
	s_nop 1
	v_add_u32_e32 v2, v123, v124
	ds_read_b128 v[2:5], v2
	v_lshl_add_u64 v[8:9], v[6:7], 0, v[86:87]
	v_lshl_add_u64 v[6:7], v[6:7], 0, v[88:89]
	s_waitcnt lgkmcnt(0)
	flat_store_dwordx4 v[8:9], v[2:5] sc1
	s_nop 1
	v_add_u32_e32 v2, v125, v126
	ds_read_b128 v[2:5], v2
	s_waitcnt lgkmcnt(0)
	flat_store_dwordx4 v[6:7], v[2:5] sc1
	s_waitcnt lgkmcnt(0)

; #define LAS __attribute__((address_space(3)))
; __device__ __forceinline__ unsigned pk2(float lo, float hi) { return pg8::cvt_pk_bf16(lo, hi); }
; #define LDS_WAIT() asm volatile("s_waitcnt lgkmcnt(0)" ::: "memory")
; __device__ __forceinline__ void transpose_item(const float* W, int K, int N, int k0, int n0, bf16* dst, const float* kscale, LAS unsigned char* scr, int lane) {
;     ...
;     for (int j = 0; j < 8; ++j) { const int k = 8 * j + 2 * r; float s0 = 1.0f, s1 = 1.0f; if (kscale) { const f32x2 sc = *(const f32x2*)(kscale + k0 + k); s0 = sc.x; s1 = sc.y; }
; #pragma unroll
;         for (int i = 0; i < 4; ++i) { const int n = 4 * c + i; *(LAS unsigned*)(scr + n * 128 + ((j ^ (c & 7)) << 4) + 4 * r) = pk2(v[2 * j][i] * s0, v[2 * j + 1][i] * s1); } }
;     LDS_WAIT(); asm volatile("" ::: "memory");
;     const int rr = lane >> 3, cc = lane & 7;
; #pragma unroll
;     for (int j = 0; j < 8; ++j) { const int n = 8 * j + rr; const v4u o = *(const LAS v4u*)(scr + n * 128 + ((cc ^ ((n >> 2) & 7)) << 4)); *(v4u*)(dst + (size_t)n * K + k0 + 8 * cc) = o; }
;     LDS_WAIT(); asm volatile("" ::: "memory");
; __device__ __forceinline__ void p0_prologue(const Ptrs& P, LAS unsigned char* lds, int gw, int NGW, int wave, int lane) {
;     ...
;         if (r < I_G) { const int kb = r / 88, n0 = (r % 88) * 64; transpose_item(P.w_up, DM, FFN, kb * 64, n0, P.Wt_gu + (size_t)((n0 >> 7) * 256 + 128 + (n0 & 127)) * DM, P.norm2_g, scr, lane); continue; }
.LBB0_33:
	s_waitcnt vmcnt(0)
	v_mul_f32_e32 v2, v2, v18
	v_mul_f32_e32 v6, v6, v19
	v_cvt_pk_bf16_f32 v2, v2, v6
	v_add_u32_e32 v6, v69, v107
	ds_write_b32 v6, v2
	v_mul_f32_e32 v2, v3, v18
	v_mul_f32_e32 v3, v7, v19
	v_cvt_pk_bf16_f32 v2, v2, v3
	ds_write_b32 v6, v2 offset:128
	v_mul_f32_e32 v2, v4, v18
	s_lshl_b32 s3, s55, 18
	v_mul_f32_e32 v3, v8, v19
	v_cvt_pk_bf16_f32 v2, v2, v3
	s_lshl_b32 s2, s55, 19
	s_and_b32 s3, s3, 0x40000
	ds_write_b32 v6, v2 offset:256
	v_mul_f32_e32 v2, v5, v18
	s_or_b32 s2, s2, s3
	v_mul_f32_e32 v3, v9, v19
	v_cvt_pk_bf16_f32 v2, v2, v3
	ds_write_b32 v6, v2 offset:384
	s_bitset1_b32 s2, 19
	s_waitcnt lgkmcnt(0)
	s_add_u32 s2, s70, s2
	v_add_u32_e32 v2, v112, v113
	s_addc_u32 s3, s71, 0
	s_lshl_b32 s40, s54, 1
	ds_read_b128 v[2:5], v2
	s_add_u32 s2, s2, s40
	s_addc_u32 s3, s3, 0
	v_lshlrev_b32_e32 v70, 1, v68
	v_lshl_add_u64 v[6:7], s[2:3], 0, v[70:71]
	v_lshlrev_b32_e32 v70, 1, v92
	v_lshl_add_u64 v[8:9], v[6:7], 0, v[70:71]
	s_waitcnt lgkmcnt(0)
	flat_store_dwordx4 v[8:9], v[2:5] sc1
	v_lshlrev_b32_e32 v70, 1, v94
	v_lshl_add_u64 v[8:9], v[6:7], 0, v[70:71]
	v_add_u32_e32 v2, v114, v115
	ds_read_b128 v[2:5], v2
	v_lshlrev_b32_e32 v70, 1, v96
	s_waitcnt lgkmcnt(0)
	flat_store_dwordx4 v[8:9], v[2:5] sc1
	s_nop 1
	v_add_u32_e32 v2, v116, v117
	ds_read_b128 v[2:5], v2
	v_lshl_add_u64 v[8:9], v[6:7], 0, v[70:71]
	v_lshlrev_b32_e32 v70, 1, v98
	s_waitcnt lgkmcnt(0)
	flat_store_dwordx4 v[8:9], v[2:5] sc1
	s_nop 1
	v_add_u32_e32 v2, v118, v119
	ds_read_b128 v[2:5], v2
	v_lshl_add_u64 v[8:9], v[6:7], 0, v[70:71]
	v_lshlrev_b32_e32 v70, 1, v100
	s_waitcnt lgkmcnt(0)
	flat_store_dwordx4 v[8:9], v[2:5] sc1
	s_nop 1
	v_add_u32_e32 v2, v120, v113
	ds_read_b128 v[2:5], v2
	v_lshl_add_u64 v[8:9], v[6:7], 0, v[70:71]
	v_lshlrev_b32_e32 v70, 1, v102
	s_waitcnt lgkmcnt(0)
	flat_store_dwordx4 v[8:9], v[2:5] sc1
	s_nop 1
	v_add_u32_e32 v2, v121, v122
	ds_read_b128 v[2:5], v2
	v_lshl_add_u64 v[8:9], v[6:7], 0, v[70:71]
	v_lshlrev_b32_e32 v70, 1, v104
	s_waitcnt lgkmcnt(0)
	flat_store_dwordx4 v[8:9], v[2:5] sc1
	s_nop 1
	v_add_u32_e32 v2, v123, v124
	ds_read_b128 v[2:5], v2
	v_lshl_add_u64 v[8:9], v[6:7], 0, v[70:71]
	v_lshlrev_b32_e32 v70, 1, v106
	v_lshl_add_u64 v[6:7], v[6:7], 0, v[70:71]
	s_waitcnt lgkmcnt(0)
	flat_store_dwordx4 v[8:9], v[2:5] sc1
	s_nop 1
	v_add_u32_e32 v2, v125, v126
	ds_read_b128 v[2:5], v2
	s_waitcnt lgkmcnt(0)
	flat_store_dwordx4 v[6:7], v[2:5] sc1
	s_waitcnt lgkmcnt(0)

; #define LAS __attribute__((address_space(3)))
; __device__ __forceinline__ unsigned pk2(float lo, float hi) { return pg8::cvt_pk_bf16(lo, hi); }
; #define LDS_WAIT() asm volatile("s_waitcnt lgkmcnt(0)" ::: "memory")
; __device__ __forceinline__ void transpose_item(const float* W, int K, int N, int k0, int n0, bf16* dst, const float* kscale, LAS unsigned char* scr, int lane) {
;     ...
;     for (int j = 0; j < 8; ++j) { const int k = 8 * j + 2 * r; float s0 = 1.0f, s1 = 1.0f; if (kscale) { const f32x2 sc = *(const f32x2*)(kscale + k0 + k); s0 = sc.x; s1 = sc.y; }
; #pragma unroll
;         for (int i = 0; i < 4; ++i) { const int n = 4 * c + i; *(LAS unsigned*)(scr + n * 128 + ((j ^ (c & 7)) << 4) + 4 * r) = pk2(v[2 * j][i] * s0, v[2 * j + 1][i] * s1); } }
;     LDS_WAIT(); asm volatile("" ::: "memory");
;     const int rr = lane >> 3, cc = lane & 7;
; #pragma unroll
;     for (int j = 0; j < 8; ++j) { const int n = 8 * j + rr; const v4u o = *(const LAS v4u*)(scr + n * 128 + ((cc ^ ((n >> 2) & 7)) << 4)); *(v4u*)(dst + (size_t)n * K + k0 + 8 * cc) = o; }
;     LDS_WAIT(); asm volatile("" ::: "memory");
; __device__ __forceinline__ void p0_prologue(const Ptrs& P, LAS unsigned char* lds, int gw, int NGW, int wave, int lane) {
;     ...
;         if (r < I_G) { const int kb = r / 88, n0 = (r % 88) * 64; transpose_item(P.w_gate, DM, FFN, kb * 64, n0, P.Wt_gu + (size_t)((n0 >> 7) * 256 + (n0 & 127)) * DM, P.norm2_g, scr, lane); continue; }
.LBB0_52:
	s_waitcnt vmcnt(0)
	v_mul_f32_e32 v2, v2, v18
	v_mul_f32_e32 v6, v6, v19
	v_cvt_pk_bf16_f32 v2, v2, v6
	v_add_u32_e32 v6, v69, v107
	ds_write_b32 v6, v2
	v_mul_f32_e32 v2, v3, v18
	v_mul_f32_e32 v3, v7, v19
	v_cvt_pk_bf16_f32 v2, v2, v3
	ds_write_b32 v6, v2 offset:128
	v_mul_f32_e32 v2, v4, v18
	s_lshl_b32 s2, s55, 6
	s_lshl_b32 s3, s55, 7
	v_mul_f32_e32 v3, v8, v19
	v_cvt_pk_bf16_f32 v2, v2, v3
	s_and_b32 s3, s3, 0x3f00
	s_and_b32 s2, s2, 64
	ds_write_b32 v6, v2 offset:256
	v_mul_f32_e32 v2, v5, v18
	s_or_b32 s2, s3, s2
	v_mul_f32_e32 v3, v9, v19
	v_cvt_pk_bf16_f32 v2, v2, v3
	ds_write_b32 v6, v2 offset:384
	s_lshl_b32 s2, s2, 12
	s_waitcnt lgkmcnt(0)
	s_add_u32 s2, s70, s2
	v_add_u32_e32 v2, v112, v113
	s_addc_u32 s3, s71, 0
	s_lshl_b32 s40, s54, 1
	ds_read_b128 v[2:5], v2
	s_add_u32 s2, s2, s40
	s_addc_u32 s3, s3, 0
	v_lshlrev_b32_e32 v70, 1, v68
	v_lshl_add_u64 v[6:7], s[2:3], 0, v[70:71]
	v_lshlrev_b32_e32 v70, 1, v92
	v_lshl_add_u64 v[8:9], v[6:7], 0, v[70:71]
	s_waitcnt lgkmcnt(0)
	flat_store_dwordx4 v[8:9], v[2:5] sc1
	v_lshlrev_b32_e32 v70, 1, v94
	v_lshl_add_u64 v[8:9], v[6:7], 0, v[70:71]
	v_add_u32_e32 v2, v114, v115
	ds_read_b128 v[2:5], v2
	v_lshlrev_b32_e32 v70, 1, v96
	s_waitcnt lgkmcnt(0)
	flat_store_dwordx4 v[8:9], v[2:5] sc1
	s_nop 1
	v_add_u32_e32 v2, v116, v117
	ds_read_b128 v[2:5], v2
	v_lshl_add_u64 v[8:9], v[6:7], 0, v[70:71]
	v_lshlrev_b32_e32 v70, 1, v98
	s_waitcnt lgkmcnt(0)
	flat_store_dwordx4 v[8:9], v[2:5] sc1
	s_nop 1
	v_add_u32_e32 v2, v118, v119
	ds_read_b128 v[2:5], v2
	v_lshl_add_u64 v[8:9], v[6:7], 0, v[70:71]
	v_lshlrev_b32_e32 v70, 1, v100
	s_waitcnt lgkmcnt(0)
	flat_store_dwordx4 v[8:9], v[2:5] sc1
	s_nop 1
	v_add_u32_e32 v2, v120, v113
	ds_read_b128 v[2:5], v2
	v_lshl_add_u64 v[8:9], v[6:7], 0, v[70:71]
	v_lshlrev_b32_e32 v70, 1, v102
	s_waitcnt lgkmcnt(0)
	flat_store_dwordx4 v[8:9], v[2:5] sc1
	s_nop 1
	v_add_u32_e32 v2, v121, v122
	ds_read_b128 v[2:5], v2
	v_lshl_add_u64 v[8:9], v[6:7], 0, v[70:71]
	v_lshlrev_b32_e32 v70, 1, v104
	s_waitcnt lgkmcnt(0)
	flat_store_dwordx4 v[8:9], v[2:5] sc1
	s_nop 1
	v_add_u32_e32 v2, v123, v124
	ds_read_b128 v[2:5], v2
	v_lshl_add_u64 v[8:9], v[6:7], 0, v[70:71]
	v_lshlrev_b32_e32 v70, 1, v106
	v_lshl_add_u64 v[6:7], v[6:7], 0, v[70:71]
	s_waitcnt lgkmcnt(0)
	flat_store_dwordx4 v[8:9], v[2:5] sc1
	s_nop 1
	v_add_u32_e32 v2, v125, v126
	ds_read_b128 v[2:5], v2
	s_waitcnt lgkmcnt(0)
	flat_store_dwordx4 v[6:7], v[2:5] sc1
	s_waitcnt lgkmcnt(0)

; #define LAS __attribute__((address_space(3)))
; __device__ __forceinline__ void transpose_item(const float* W, int K, int N, int k0, int n0, bf16* dst, const float* kscale, LAS unsigned char* scr, int lane) {
;     const int r = lane >> 4, c = lane & 15;
;     f32x4 v[16];
; #pragma unroll
;     for (int j = 0; j < 8; ++j)
; #pragma unroll
;         for (int p = 0; p < 2; ++p) v[2 * j + p] = *(const f32x4*)(W + (size_t)(k0 + 8 * j + 2 * r + p) * N + n0 + 4 * c);
; #pragma unroll
; __device__ __forceinline__ void p0_prologue(const Ptrs& P, LAS unsigned char* lds, int gw, int NGW, int wave, int lane) {
;     ...
;         if (r < I_OUT) { const int kb = r / 32, n0 = (r % 32) * 64; transpose_item(P.w_out, DM, DM, kb * 64, n0, P.Wt_out + (size_t)n0 * DM, nullptr, scr, lane); continue; }
.LBB0_54:
	s_andn2_b64 vcc, exec, s[2:3]
	s_cbranch_vccnz .LBB0_56
	s_and_b32 s3, s79, 0x7c0
	s_and_b32 s2, s83, 0x1fc0
	s_addk_i32 s2, 0xec00
	s_lshl_b32 s40, s3, 12
	s_add_u32 s40, s5, s40
	v_or_b32_e32 v70, s2, v66
	s_addc_u32 s41, s61, 0
	s_lshl_b32 s66, s3, 2
	v_or_b32_e32 v4, 1, v70
	v_mov_b32_e32 v5, v71
	v_lshl_add_u64 v[58:59], v[78:79], 0, s[66:67]
	v_lshlrev_b64 v[2:3], 13, v[70:71]
	v_lshlrev_b64 v[4:5], 13, v[4:5]
	v_lshl_add_u64 v[2:3], v[58:59], 0, v[2:3]
	v_lshl_add_u64 v[6:7], v[58:59], 0, v[4:5]
	global_load_dwordx4 v[2:5], v[2:3], off
	s_nop 0
	global_load_dwordx4 v[6:9], v[6:7], off
	v_or_b32_e32 v10, 8, v70
	v_mov_b32_e32 v11, v71
	v_or_b32_e32 v12, 9, v70
	v_mov_b32_e32 v13, v71
	v_lshlrev_b64 v[10:11], 13, v[10:11]
	v_lshlrev_b64 v[12:13], 13, v[12:13]
	v_lshl_add_u64 v[10:11], v[58:59], 0, v[10:11]
	v_lshl_add_u64 v[14:15], v[58:59], 0, v[12:13]
	global_load_dwordx4 v[10:13], v[10:11], off
	s_nop 0
	global_load_dwordx4 v[14:17], v[14:15], off
	v_or_b32_e32 v18, 16, v70
	v_mov_b32_e32 v19, v71
	v_or_b32_e32 v20, 17, v70
	v_mov_b32_e32 v21, v71
	v_lshlrev_b64 v[18:19], 13, v[18:19]
	v_lshlrev_b64 v[20:21], 13, v[20:21]
	v_lshl_add_u64 v[18:19], v[58:59], 0, v[18:19]
	v_lshl_add_u64 v[22:23], v[58:59], 0, v[20:21]
	global_load_dwordx4 v[18:21], v[18:19], off
	s_nop 0
	global_load_dwordx4 v[22:25], v[22:23], off
	v_or_b32_e32 v26, 24, v70
	v_mov_b32_e32 v27, v71
	v_or_b32_e32 v28, 25, v70
	v_mov_b32_e32 v29, v71
	v_lshlrev_b64 v[26:27], 13, v[26:27]
	v_lshlrev_b64 v[28:29], 13, v[28:29]
	v_lshl_add_u64 v[26:27], v[58:59], 0, v[26:27]
	v_lshl_add_u64 v[30:31], v[58:59], 0, v[28:29]
	global_load_dwordx4 v[26:29], v[26:27], off
	s_nop 0
	global_load_dwordx4 v[30:33], v[30:31], off
	v_or_b32_e32 v34, 32, v70
	v_mov_b32_e32 v35, v71
	v_or_b32_e32 v36, 33, v70
	v_mov_b32_e32 v37, v71
	v_lshlrev_b64 v[34:35], 13, v[34:35]
	v_lshlrev_b64 v[36:37], 13, v[36:37]
	v_lshl_add_u64 v[34:35], v[58:59], 0, v[34:35]
	v_lshl_add_u64 v[38:39], v[58:59], 0, v[36:37]
	global_load_dwordx4 v[34:37], v[34:35], off
	s_nop 0
	global_load_dwordx4 v[38:41], v[38:39], off
	v_or_b32_e32 v42, 40, v70
	v_mov_b32_e32 v43, v71
	v_or_b32_e32 v44, 41, v70
	v_mov_b32_e32 v45, v71
	v_lshlrev_b64 v[42:43], 13, v[42:43]
	v_lshlrev_b64 v[44:45], 13, v[44:45]
	v_lshl_add_u64 v[42:43], v[58:59], 0, v[42:43]
	v_lshl_add_u64 v[46:47], v[58:59], 0, v[44:45]
	global_load_dwordx4 v[42:45], v[42:43], off
	s_nop 0
	global_load_dwordx4 v[46:49], v[46:47], off
	v_or_b32_e32 v50, 48, v70
	v_mov_b32_e32 v51, v71
	v_or_b32_e32 v52, 49, v70
	v_mov_b32_e32 v53, v71
	v_lshlrev_b64 v[50:51], 13, v[50:51]
	v_lshlrev_b64 v[52:53], 13, v[52:53]
	v_lshl_add_u64 v[50:51], v[58:59], 0, v[50:51]
	v_lshl_add_u64 v[54:55], v[58:59], 0, v[52:53]
	global_load_dwordx4 v[50:53], v[50:51], off
	s_nop 0
	global_load_dwordx4 v[54:57], v[54:55], off
	v_or_b32_e32 v60, 56, v70
	v_mov_b32_e32 v61, v71
	v_or_b32_e32 v70, 57, v70
	v_lshlrev_b64 v[60:61], 13, v[60:61]
	v_lshlrev_b64 v[62:63], 13, v[70:71]
	v_lshl_add_u64 v[60:61], v[58:59], 0, v[60:61]
	v_lshl_add_u64 v[62:63], v[58:59], 0, v[62:63]
	global_load_dwordx4 v[58:61], v[60:61], off
	s_nop 0
	global_load_dwordx4 v[62:65], v[62:63], off
	s_mov_b32 s3, s67
	s_lshl_b64 s[2:3], s[2:3], 1
	s_add_u32 s2, s40, s2
	s_addc_u32 s3, s41, s3
	v_lshlrev_b32_e32 v70, 1, v68
	s_waitcnt vmcnt(0)
; #define LAS __attribute__((address_space(3)))
; __device__ __forceinline__ unsigned pk2(float lo, float hi) { return pg8::cvt_pk_bf16(lo, hi); }
; #define LDS_WAIT() asm volatile("s_waitcnt lgkmcnt(0)" ::: "memory")
; __device__ __forceinline__ void transpose_item(const float* W, int K, int N, int k0, int n0, bf16* dst, const float* kscale, LAS unsigned char* scr, int lane) {
;     ...
;     for (int j = 0; j < 8; ++j) { const int k = 8 * j + 2 * r; float s0 = 1.0f, s1 = 1.0f; if (kscale) { const f32x2 sc = *(const f32x2*)(kscale + k0 + k); s0 = sc.x; s1 = sc.y; }
; #pragma unroll
;         for (int i = 0; i < 4; ++i) { const int n = 4 * c + i; *(LAS unsigned*)(scr + n * 128 + ((j ^ (c & 7)) << 4) + 4 * r) = pk2(v[2 * j][i] * s0, v[2 * j + 1][i] * s1); } }
;     LDS_WAIT(); asm volatile("" ::: "memory");
;     const int rr = lane >> 3, cc = lane & 7;
; #pragma unroll
;     for (int j = 0; j < 8; ++j) { const int n = 8 * j + rr; const v4u o = *(const LAS v4u*)(scr + n * 128 + ((cc ^ ((n >> 2) & 7)) << 4)); *(v4u*)(dst + (size_t)n * K + k0 + 8 * cc) = o; }
;     LDS_WAIT(); asm volatile("" ::: "memory");
	v_cvt_pk_bf16_f32 v2, v2, v6
	v_add_u32_e32 v6, v69, v93
	ds_write_b32 v6, v2
	v_cvt_pk_bf16_f32 v2, v3, v7
	ds_write_b32 v6, v2 offset:128
	v_cvt_pk_bf16_f32 v2, v4, v8
	ds_write_b32 v6, v2 offset:256
	v_cvt_pk_bf16_f32 v2, v5, v9
	ds_write_b32 v6, v2 offset:384
	v_cvt_pk_bf16_f32 v2, v10, v14
	v_add_u32_e32 v3, v69, v95
	ds_write_b32 v3, v2
	v_cvt_pk_bf16_f32 v2, v11, v15
	ds_write_b32 v3, v2 offset:128
	v_cvt_pk_bf16_f32 v2, v12, v16
	ds_write_b32 v3, v2 offset:256
	v_cvt_pk_bf16_f32 v2, v13, v17
	ds_write_b32 v3, v2 offset:384
	v_cvt_pk_bf16_f32 v2, v18, v22
	v_add_u32_e32 v3, v69, v97
	ds_write_b32 v3, v2
	v_cvt_pk_bf16_f32 v2, v19, v23
	ds_write_b32 v3, v2 offset:128
	v_cvt_pk_bf16_f32 v2, v20, v24
	ds_write_b32 v3, v2 offset:256
	v_cvt_pk_bf16_f32 v2, v21, v25
	ds_write_b32 v3, v2 offset:384
	v_cvt_pk_bf16_f32 v2, v26, v30
	v_add_u32_e32 v3, v69, v99
	ds_write_b32 v3, v2
	v_cvt_pk_bf16_f32 v2, v27, v31
	ds_write_b32 v3, v2 offset:128
	v_cvt_pk_bf16_f32 v2, v28, v32
	ds_write_b32 v3, v2 offset:256
	v_cvt_pk_bf16_f32 v2, v29, v33
	ds_write_b32 v3, v2 offset:384
	v_cvt_pk_bf16_f32 v2, v34, v38
	v_add_u32_e32 v3, v69, v101
	ds_write_b32 v3, v2
	v_cvt_pk_bf16_f32 v2, v35, v39
	ds_write_b32 v3, v2 offset:128
	v_cvt_pk_bf16_f32 v2, v36, v40
	ds_write_b32 v3, v2 offset:256
	v_cvt_pk_bf16_f32 v2, v37, v41
	ds_write_b32 v3, v2 offset:384
	v_cvt_pk_bf16_f32 v2, v42, v46
	v_add_u32_e32 v3, v69, v103
	ds_write_b32 v3, v2
	v_cvt_pk_bf16_f32 v2, v43, v47
	ds_write_b32 v3, v2 offset:128
	v_cvt_pk_bf16_f32 v2, v44, v48
	ds_write_b32 v3, v2 offset:256
	v_cvt_pk_bf16_f32 v2, v45, v49
	ds_write_b32 v3, v2 offset:384
	v_cvt_pk_bf16_f32 v2, v50, v54
	v_add_u32_e32 v3, v69, v105
	ds_write_b32 v3, v2
	v_cvt_pk_bf16_f32 v2, v51, v55
	ds_write_b32 v3, v2 offset:128
	v_cvt_pk_bf16_f32 v2, v52, v56
	ds_write_b32 v3, v2 offset:256
	v_cvt_pk_bf16_f32 v2, v53, v57
	ds_write_b32 v3, v2 offset:384
	v_cvt_pk_bf16_f32 v2, v58, v62
	v_add_u32_e32 v3, v69, v107
	ds_write_b32 v3, v2
	v_cvt_pk_bf16_f32 v2, v59, v63
	ds_write_b32 v3, v2 offset:128
	v_cvt_pk_bf16_f32 v2, v60, v64
	ds_write_b32 v3, v2 offset:256
	v_cvt_pk_bf16_f32 v2, v61, v65
	ds_write_b32 v3, v2 offset:384
	s_waitcnt lgkmcnt(0)
	v_add_u32_e32 v2, v112, v113
	ds_read_b128 v[2:5], v2
	v_lshl_add_u64 v[6:7], s[2:3], 0, v[70:71]
	v_lshlrev_b32_e32 v70, 1, v92
	v_lshl_add_u64 v[8:9], v[6:7], 0, v[70:71]
	v_lshlrev_b32_e32 v70, 1, v94
	s_waitcnt lgkmcnt(0)
	flat_store_dwordx4 v[8:9], v[2:5] sc1
	v_lshl_add_u64 v[8:9], v[6:7], 0, v[70:71]
	v_lshlrev_b32_e32 v70, 1, v96
	v_add_u32_e32 v2, v114, v115
	ds_read_b128 v[2:5], v2
	s_waitcnt lgkmcnt(0)
	flat_store_dwordx4 v[8:9], v[2:5] sc1
	s_nop 1
	v_add_u32_e32 v2, v116, v117
	ds_read_b128 v[2:5], v2
	v_lshl_add_u64 v[8:9], v[6:7], 0, v[70:71]
	v_lshlrev_b32_e32 v70, 1, v98
	s_waitcnt lgkmcnt(0)
	flat_store_dwordx4 v[8:9], v[2:5] sc1
	s_nop 1
	v_add_u32_e32 v2, v118, v119
	ds_read_b128 v[2:5], v2
	v_lshl_add_u64 v[8:9], v[6:7], 0, v[70:71]
	v_lshlrev_b32_e32 v70, 1, v100
	s_waitcnt lgkmcnt(0)
	flat_store_dwordx4 v[8:9], v[2:5] sc1
	s_nop 1
	v_add_u32_e32 v2, v120, v113
	ds_read_b128 v[2:5], v2
	v_lshl_add_u64 v[8:9], v[6:7], 0, v[70:71]
	v_lshlrev_b32_e32 v70, 1, v102
	s_waitcnt lgkmcnt(0)
	flat_store_dwordx4 v[8:9], v[2:5] sc1
	s_nop 1
	v_add_u32_e32 v2, v121, v122
	ds_read_b128 v[2:5], v2
	v_lshl_add_u64 v[8:9], v[6:7], 0, v[70:71]
	v_lshlrev_b32_e32 v70, 1, v104
	s_waitcnt lgkmcnt(0)
	flat_store_dwordx4 v[8:9], v[2:5] sc1
	s_nop 1
	v_add_u32_e32 v2, v123, v124
	ds_read_b128 v[2:5], v2
	v_lshl_add_u64 v[8:9], v[6:7], 0, v[70:71]
	v_lshlrev_b32_e32 v70, 1, v106
	v_lshl_add_u64 v[6:7], v[6:7], 0, v[70:71]
	s_waitcnt lgkmcnt(0)
	flat_store_dwordx4 v[8:9], v[2:5] sc1
	s_nop 1
	v_add_u32_e32 v2, v125, v126
	ds_read_b128 v[2:5], v2
	s_waitcnt lgkmcnt(0)
	flat_store_dwordx4 v[6:7], v[2:5] sc1
	s_waitcnt lgkmcnt(0)

; __device__ __forceinline__ unsigned pk2(float lo, float hi) { return pg8::cvt_pk_bf16(lo, hi); }
; __device__ __forceinline__ void x_row_to_bf16(const float* xrow, bf16* orow, float* rs, int lane) {
;     const int lo = lane & 31, hi = lane >> 5;
;     const f32x4* xr = (const f32x4*)xrow + 2 * lo + hi;
;     f32x4 v[8]; float s = 0.f;
; #pragma unroll
;     for (int j = 0; j < 8; ++j) { v[j] = xr[64 * j]; s += (v[j].x * v[j].x + v[j].y * v[j].y) + (v[j].z * v[j].z + v[j].w * v[j].w); }
;     const float rinv = 1.0f / sqrtf(wave_sum(s) * (1.f / DM) + EPS_RMS);
;     if (lane == 0) *rs = rinv;
; #pragma unroll
;     for (int i = 0; i < 4; ++i) { v2u wa, wb;
;         { const f32x4 x = v[2 * i]; wa.x = pk2(x.x, x.y); wa.y = pk2(x.z, x.w); }
;         { const f32x4 x = v[2 * i + 1]; wb.x = pk2(x.x, x.y); wb.y = pk2(x.z, x.w); }
;         const auto rx = __builtin_amdgcn_permlane32_swap(wa.x, wb.x, false, false);
;         const auto ry = __builtin_amdgcn_permlane32_swap(wa.y, wb.y, false, false);
;         v4u w16; w16.x = rx[0]; w16.y = ry[0]; w16.z = rx[1]; w16.w = ry[1];
;         *(v4u*)(orow + 256 * (2 * i + hi) + 8 * lo) = w16; }
; }
; __device__ __forceinline__ void p0_prologue(const Ptrs& P, LAS unsigned char* lds, int gw, int NGW, int wave, int lane) {
;     ...
;     for (int m = gw; m < M_TOK; m += NGW) x_row_to_bf16(P.x + (size_t)m * DM, P.XN + (size_t)m * DM, P.RS1 + m, lane);
.LBB0_88:
	s_or_b64 exec, exec, s[38:39]
	v_cvt_pk_bf16_f32 v26, v26, v27
	v_cvt_pk_bf16_f32 v27, v28, v29
	v_cvt_pk_bf16_f32 v28, v30, v31
	v_lshl_add_u64 v[30:31], s[62:63], 0, v[36:37]
	v_cvt_pk_bf16_f32 v29, v32, v33
	v_add_co_u32_e32 v30, vcc, s52, v30
	v_permlane32_swap_b32_e32 v26, v28
	v_permlane32_swap_b32_e32 v27, v29
	v_addc_co_u32_e32 v31, vcc, 0, v31, vcc
	flat_store_dwordx4 v[30:31], v[26:29] sc1
	v_cvt_pk_bf16_f32 v18, v18, v19
	v_cvt_pk_bf16_f32 v19, v20, v21
	v_cvt_pk_bf16_f32 v20, v22, v23
	v_cvt_pk_bf16_f32 v21, v24, v25
	s_add_i32 s53, s53, s4
	v_permlane32_swap_b32_e32 v18, v20
	v_permlane32_swap_b32_e32 v19, v21
	flat_store_dwordx4 v[30:31], v[18:21] offset:1024 sc1
	v_cvt_pk_bf16_f32 v10, v10, v11
	v_cvt_pk_bf16_f32 v11, v12, v13
	v_cvt_pk_bf16_f32 v12, v14, v15
	v_cvt_pk_bf16_f32 v13, v16, v17
	s_add_u32 s40, s40, s24
	v_permlane32_swap_b32_e32 v10, v12
	v_permlane32_swap_b32_e32 v11, v13
	flat_store_dwordx4 v[30:31], v[10:13] offset:2048 sc1
	v_cvt_pk_bf16_f32 v2, v2, v3
	v_cvt_pk_bf16_f32 v3, v4, v5
	v_cvt_pk_bf16_f32 v4, v6, v7
	v_cvt_pk_bf16_f32 v5, v8, v9
	s_addc_u32 s41, s41, s25
	v_permlane32_swap_b32_e32 v2, v4
	v_permlane32_swap_b32_e32 v3, v5
	v_lshl_add_u64 v[34:35], v[34:35], 0, s[26:27]
	s_cmpk_gt_i32 s53, 0x7fff
	v_lshl_add_u64 v[36:37], v[36:37], 0, s[36:37]
	flat_store_dwordx4 v[30:31], v[2:5] offset:3072 sc1
	s_cbranch_scc1 .LBB0_91
.LBB0_89:
	global_load_dwordx4 v[26:29], v[34:35], off offset:-4096
	global_load_dwordx4 v[30:33], v[34:35], off offset:-3072
	global_load_dwordx4 v[18:21], v[34:35], off offset:-2048
	global_load_dwordx4 v[22:25], v[34:35], off offset:-1024
	global_load_dwordx4 v[10:13], v[34:35], off
	global_load_dwordx4 v[14:17], v[34:35], off offset:1024
	global_load_dwordx4 v[2:5], v[34:35], off offset:2048
	global_load_dwordx4 v[6:9], v[34:35], off offset:3072
	s_waitcnt vmcnt(0)
	v_mul_f32_e32 v46, v27, v27
	s_waitcnt lgkmcnt(0)
	v_mul_f32_e32 v47, v29, v29
	v_mul_f32_e32 v48, v31, v31
	v_mul_f32_e32 v49, v33, v33
	v_mul_f32_e32 v50, v19, v19
	v_mul_f32_e32 v51, v21, v21
	v_fmac_f32_e32 v46, v26, v26
	v_fmac_f32_e32 v47, v28, v28
	v_fmac_f32_e32 v48, v30, v30
	v_fmac_f32_e32 v49, v32, v32
	v_mul_f32_e32 v52, v23, v23
	v_mul_f32_e32 v53, v25, v25
	v_fmac_f32_e32 v50, v18, v18
	v_fmac_f32_e32 v51, v20, v20
	v_add_f32_e32 v46, v46, v47
	v_add_f32_e32 v47, v48, v49
	v_mul_f32_e32 v54, v11, v11
	v_mul_f32_e32 v55, v13, v13
	v_fmac_f32_e32 v52, v22, v22
	v_fmac_f32_e32 v53, v24, v24
	v_add_f32_e32 v48, v50, v51
	v_add_f32_e32 v46, v46, v47
	v_mul_f32_e32 v56, v15, v15
	v_mul_f32_e32 v57, v17, v17
	v_fmac_f32_e32 v54, v10, v10
	v_fmac_f32_e32 v55, v12, v12
	v_add_f32_e32 v49, v52, v53
	v_add_f32_e32 v46, v46, v48
	v_mul_f32_e32 v58, v3, v3
	v_mul_f32_e32 v59, v5, v5
	v_fmac_f32_e32 v56, v14, v14
	v_fmac_f32_e32 v57, v16, v16
	v_add_f32_e32 v50, v54, v55
	v_add_f32_e32 v46, v46, v49
	v_mul_f32_e32 v60, v7, v7
	v_mul_f32_e32 v61, v9, v9
	v_fmac_f32_e32 v58, v2, v2
	v_fmac_f32_e32 v59, v4, v4
	v_add_f32_e32 v51, v56, v57
	v_add_f32_e32 v46, v46, v50
	v_fmac_f32_e32 v60, v6, v6
	v_fmac_f32_e32 v61, v8, v8
	v_add_f32_e32 v52, v58, v59
	v_add_f32_e32 v46, v46, v51
	v_add_f32_e32 v46, v46, v52
	v_add_f32_e32 v47, v60, v61
	v_add_f32_e32 v46, v46, v47
	s_nop 1
	v_add_f32_dpp v46, v46, v46 quad_perm:[1,0,3,2] row_mask:0xf bank_mask:0xf
	s_nop 1
	v_add_f32_dpp v46, v46, v46 quad_perm:[2,3,0,1] row_mask:0xf bank_mask:0xf
	s_nop 1
	v_add_f32_dpp v46, v46, v46 row_half_mirror row_mask:0xf bank_mask:0xf
	s_nop 1
	v_add_f32_dpp v46, v46, v46 row_mirror row_mask:0xf bank_mask:0xf
	s_nop 1
	v_add_f32_dpp v46, v46, v46 row_bcast:15 row_mask:0xa bank_mask:0xf
	s_nop 1
	v_add_f32_dpp v46, v46, v46 row_bcast:31 row_mask:0xc bank_mask:0xf
	s_and_saveexec_b64 s[38:39], s[2:3]
	s_cbranch_execz .LBB0_88
	s_nop 1
	v_fmamk_f32 v46, v46, 0x3a000000, v44
	v_mul_f32_e32 v47, 0x4f800000, v46
	v_cmp_gt_f32_e32 vcc, s5, v46
	s_nop 1
	v_cndmask_b32_e32 v46, v46, v47, vcc
	v_sqrt_f32_e32 v47, v46
	s_nop 0
	v_add_u32_e32 v48, -1, v47
	v_fma_f32 v50, -v48, v47, v46
	v_add_u32_e32 v49, 1, v47
	v_cmp_ge_f32_e64 s[0:1], 0, v50
	s_nop 1
	v_cndmask_b32_e64 v48, v47, v48, s[0:1]
	v_fma_f32 v47, -v49, v47, v46
	v_cmp_lt_f32_e64 s[0:1], 0, v47
	s_nop 1
	v_cndmask_b32_e64 v47, v48, v49, s[0:1]
	v_mul_f32_e32 v48, 0x37800000, v47
	v_cndmask_b32_e32 v47, v47, v48, vcc
	v_cmp_class_f32_e32 vcc, v46, v45
	s_nop 1
	v_cndmask_b32_e32 v46, v47, v46, vcc
	v_div_scale_f32 v47, s[0:1], v46, v46, 1.0
	v_rcp_f32_e32 v48, v47
	s_add_u32 s0, s62, s40
	s_addc_u32 s1, s63, s41
	v_fma_f32 v49, -v47, v48, 1.0
	v_fmac_f32_e32 v48, v49, v48
	v_div_scale_f32 v49, vcc, 1.0, v46, 1.0
	v_mul_f32_e32 v50, v49, v48
	v_fma_f32 v51, -v47, v50, v49
	v_fmac_f32_e32 v50, v51, v48
	v_fma_f32 v47, -v47, v50, v49
	v_div_fmas_f32 v47, v47, v48, v50
	v_div_fixup_f32 v48, v47, v46, 1.0
	v_mov_b64_e32 v[46:47], s[0:1]
	flat_store_dword v[46:47], v48 sc1
	s_branch .LBB0_88

; __device__ __forceinline__ void p0_prologue(const Ptrs& P, LAS unsigned char* lds, int gw, int NGW, int wave, int lane) {
;     ...
;     for (int i = gw * 64 + lane; i < SEQ * 64; i += NGW * 64) {
;         const int pos = i >> 6, j = i & 63;
;         const float inv = (float)exp2(-(double)j * (13.287712379549449 / 64.0));
;         const float ang = (float)pos * inv;
;         double rev = (double)ang * 0.15915494309189535; rev -= rint(rev);
;         const float fr = (float)rev;
;         P.COS[i] = __builtin_amdgcn_cosf(fr); P.SIN[i] = __builtin_amdgcn_sinf(fr);
;     }
.LBB0_93:
	v_ashrrev_i32_e32 v3, 6, v2
	v_cvt_f32_i32_e32 v3, v3
	v_add_co_u32_e32 v8, vcc, 0xffe00000, v4
	v_add_u32_e32 v2, s24, v2
	v_mul_f32_e32 v3, v6, v3
	v_cvt_f64_f32_e32 v[10:11], v3
	v_mul_f64 v[12:13], v[10:11], s[36:37]
	v_rndne_f64_e32 v[12:13], v[12:13]
	v_fma_f64 v[10:11], v[10:11], s[36:37], -v[12:13]
	v_cvt_f32_f64_e32 v3, v[10:11]
	v_cos_f32_e32 v7, v3
	v_sin_f32_e32 v3, v3
	v_addc_co_u32_e32 v9, vcc, -1, v5, vcc
	v_cmp_lt_i32_e32 vcc, s5, v2
	s_or_b64 s[26:27], vcc, s[26:27]
	flat_store_dword v[8:9], v7 sc1
	flat_store_dword v[4:5], v3 sc1
	v_lshl_add_u64 v[4:5], v[4:5], 0, s[0:1]
	s_andn2_b64 exec, exec, s[26:27]
	s_cbranch_execnz .LBB0_93

; __device__ __forceinline__ u32x4 pack8(const f32x4 v0, const f32x4 v1) { u32x4 w; w.x = cvt_pk_bf16(v0[0], v0[1]); w.y = cvt_pk_bf16(v0[2], v0[3]); w.z = cvt_pk_bf16(v1[0], v1[1]); w.w = cvt_pk_bf16(v1[2], v1[3]); return w; }
; __device__ __forceinline__ float sigmoid_fast(float x) { return __builtin_amdgcn_rcpf(1.0f + __builtin_amdgcn_exp2f(-1.4426950408889634f * x)); }
;     __device__ __forceinline__ void operator()(const f32x4 (&acc)[2][2][4][2], const Unit& u, int wr, int wc, int fr, int fq) const {
;     ...
;                 for (int m = 0; m < 4; ++m) { bf16_t* rowp = base + (size_t)(row0 + ai * HALF + m * 16) * 1024; const float rs = rs8[ai * 4 + m];
;                     f32x4 v[2];
; #pragma unroll
;                     for (int n = 0; n < 2; ++n) { const f32x4 a = acc[ai][0][m][n] * rs, g = acc[ai][1][m][n] * rs;
;                         v[n] = (f32x4){a[0] * sigmoid_fast(g[0]), a[1] * sigmoid_fast(g[1]), a[2] * sigmoid_fast(g[2]), a[3] * sigmoid_fast(g[3])}; }
;                     *(u32x4*)rowp = pack8(v[0], v[1]); }
.LBB0_190:
	s_waitcnt lgkmcnt(7)
	v_pk_mul_f32 v[196:197], v[118:119], v[176:177] op_sel_hi:[1,0]
	v_pk_mul_f32 v[192:193], v[128:129], v[176:177] op_sel_hi:[1,0]
	v_mul_f32_e32 v157, 0xbfb8aa3b, v196
	v_mul_f32_e32 v196, 0xbfb8aa3b, v197
	v_exp_f32_e32 v198, v196
	v_pk_mul_f32 v[196:197], v[120:121], v[176:177] op_sel_hi:[1,0]
	v_exp_f32_e32 v157, v157
	v_mul_f32_e32 v196, 0xbfb8aa3b, v196
	v_mul_f32_e32 v197, 0xbfb8aa3b, v197
	v_exp_f32_e32 v196, v196
	v_exp_f32_e32 v197, v197
	v_add_f32_e32 v198, 1.0, v198
	v_add_f32_e32 v157, 1.0, v157
	v_add_f32_e32 v196, 1.0, v196
	v_add_f32_e32 v197, 1.0, v197
	v_rcp_f32_e32 v196, v196
	v_rcp_f32_e32 v197, v197
	v_rcp_f32_e32 v198, v198
	v_rcp_f32_e32 v157, v157
	v_mul_f32_e32 v199, v192, v196
	v_mul_f32_e32 v201, v193, v197
	v_pk_mul_f32 v[196:197], v[110:111], v[176:177] op_sel_hi:[1,0]
	v_pk_mul_f32 v[194:195], v[126:127], v[176:177] op_sel_hi:[1,0]
	v_mul_f32_e32 v196, 0xbfb8aa3b, v196
	v_exp_f32_e32 v202, v196
	v_mul_f32_e32 v196, 0xbfb8aa3b, v197
	v_exp_f32_e32 v203, v196
	v_pk_mul_f32 v[196:197], v[112:113], v[176:177] op_sel_hi:[1,0]
	v_mul_f32_e32 v198, v195, v198
	v_mul_f32_e32 v196, 0xbfb8aa3b, v196
	v_mul_f32_e32 v197, 0xbfb8aa3b, v197
	v_exp_f32_e32 v196, v196
	v_exp_f32_e32 v197, v197
	v_pk_mul_f32 v[192:193], v[124:125], v[176:177] op_sel_hi:[1,0]
	v_mul_f32_e32 v157, v194, v157
	v_add_f32_e32 v196, 1.0, v196
	v_add_f32_e32 v197, 1.0, v197
	v_rcp_f32_e32 v196, v196
	v_rcp_f32_e32 v197, v197
	v_add_f32_e32 v202, 1.0, v202
	v_add_f32_e32 v203, 1.0, v203
	v_mul_f32_e32 v196, v192, v196
	v_mul_f32_e32 v197, v193, v197
	v_cvt_pk_bf16_f32 v192, v157, v198
	v_cvt_pk_bf16_f32 v193, v199, v201
	s_waitcnt lgkmcnt(6)
	v_pk_mul_f32 v[198:199], v[102:103], v[172:173] op_sel_hi:[1,0]
	v_rcp_f32_e32 v202, v202
	v_mul_f32_e32 v157, 0xbfb8aa3b, v198
	v_mul_f32_e32 v198, 0xbfb8aa3b, v199
	v_exp_f32_e32 v201, v198
	v_pk_mul_f32 v[198:199], v[104:105], v[172:173] op_sel_hi:[1,0]
	v_rcp_f32_e32 v203, v203
	v_mul_f32_e32 v198, 0xbfb8aa3b, v198
	v_mul_f32_e32 v199, 0xbfb8aa3b, v199
	v_exp_f32_e32 v198, v198
	v_exp_f32_e32 v199, v199
	s_lshl_b32 s26, s92, 8
	v_lshl_add_u64 v[180:181], v[138:139], 0, s[26:27]
	v_add_f32_e32 v198, 1.0, v198
	v_add_f32_e32 v199, 1.0, v199
	s_mov_b64 s[64:65], 0x1a7ff800
	v_pk_mul_f32 v[194:195], v[122:123], v[176:177] op_sel_hi:[1,0]
	v_rcp_f32_e32 v198, v198
	v_rcp_f32_e32 v199, v199
	v_lshl_add_u64 v[182:183], v[180:181], 0, s[64:65]
	v_lshlrev_b64 v[180:181], 11, v[178:179]
	v_mul_f32_e32 v194, v194, v202
	v_mul_f32_e32 v195, v195, v203
	v_lshl_add_u64 v[180:181], v[182:183], 0, v[180:181]
	v_cvt_pk_bf16_f32 v194, v194, v195
	v_cvt_pk_bf16_f32 v195, v196, v197
	flat_store_dwordx4 v[180:181], v[192:195] sc1
	v_exp_f32_e32 v157, v157
	v_add_f32_e32 v201, 1.0, v201
	v_pk_mul_f32 v[194:195], v[116:117], v[172:173] op_sel_hi:[1,0]
	v_rcp_f32_e32 v201, v201
	v_mul_f32_e32 v202, v194, v198
	v_mul_f32_e32 v203, v195, v199
	v_pk_mul_f32 v[198:199], v[94:95], v[172:173] op_sel_hi:[1,0]
	v_add_f32_e32 v157, 1.0, v157
	v_mul_f32_e32 v198, 0xbfb8aa3b, v198
	v_exp_f32_e32 v204, v198
	v_mul_f32_e32 v198, 0xbfb8aa3b, v199
	v_exp_f32_e32 v205, v198
	v_pk_mul_f32 v[198:199], v[96:97], v[172:173] op_sel_hi:[1,0]
	v_rcp_f32_e32 v157, v157
	v_mul_f32_e32 v198, 0xbfb8aa3b, v198
	v_mul_f32_e32 v199, 0xbfb8aa3b, v199
	v_exp_f32_e32 v198, v198
	v_exp_f32_e32 v199, v199
	v_add_f32_e32 v204, 1.0, v204
	v_add_f32_e32 v205, 1.0, v205
	v_add_f32_e32 v198, 1.0, v198
	v_add_f32_e32 v199, 1.0, v199
	v_rcp_f32_e32 v198, v198
	v_rcp_f32_e32 v199, v199
	v_rcp_f32_e32 v204, v204
	v_rcp_f32_e32 v205, v205
	v_pk_mul_f32 v[196:197], v[114:115], v[172:173] op_sel_hi:[1,0]
	v_pk_mul_f32 v[194:195], v[108:109], v[172:173] op_sel_hi:[1,0]
	v_lshlrev_b64 v[192:193], 11, v[174:175]
	v_mul_f32_e32 v157, v196, v157
	v_mul_f32_e32 v201, v197, v201
	v_pk_mul_f32 v[196:197], v[106:107], v[172:173] op_sel_hi:[1,0]
	v_mul_f32_e32 v198, v194, v198
	v_mul_f32_e32 v195, v195, v199
	v_mul_f32_e32 v204, v196, v204
	v_mul_f32_e32 v205, v197, v205
	v_lshl_add_u64 v[196:197], v[182:183], 0, v[192:193]
	v_cvt_pk_bf16_f32 v192, v157, v201
	v_cvt_pk_bf16_f32 v193, v202, v203
	v_cvt_pk_bf16_f32 v194, v204, v205
	v_cvt_pk_bf16_f32 v195, v198, v195
	s_waitcnt lgkmcnt(0)
; __device__ __forceinline__ float sigmoid_fast(float x) { return __builtin_amdgcn_rcpf(1.0f + __builtin_amdgcn_exp2f(-1.4426950408889634f * x)); }
; __device__ __forceinline__ u32x4 pack8(const f32x4 v0, const f32x4 v1) { u32x4 w; w.x = cvt_pk_bf16(v0[0], v0[1]); w.y = cvt_pk_bf16(v0[2], v0[3]); w.z = cvt_pk_bf16(v1[0], v1[1]); w.w = cvt_pk_bf16(v1[2], v1[3]); return w; }
;     __device__ __forceinline__ void operator()(const f32x4 (&acc)[2][2][4][2], const Unit& u, int wr, int wc, int fr, int fq) const {
;     ...
;                 for (int m = 0; m < 4; ++m) { bf16_t* rowp = base + (size_t)(row0 + ai * HALF + m * 16) * 1024; const float rs = rs8[ai * 4 + m];
;                     f32x4 v[2];
; #pragma unroll
;                     for (int n = 0; n < 2; ++n) { const f32x4 a = acc[ai][0][m][n] * rs, g = acc[ai][1][m][n] * rs;
;                         v[n] = (f32x4){a[0] * sigmoid_fast(g[0]), a[1] * sigmoid_fast(g[1]), a[2] * sigmoid_fast(g[2]), a[3] * sigmoid_fast(g[3])}; }
;                     *(u32x4*)rowp = pack8(v[0], v[1]); }
	v_pk_mul_f32 v[198:199], v[86:87], v[168:169] op_sel_hi:[1,0]
	flat_store_dwordx4 v[196:197], v[192:195] sc1
	v_mul_f32_e32 v157, 0xbfb8aa3b, v198
	v_mul_f32_e32 v198, 0xbfb8aa3b, v199
	v_exp_f32_e32 v201, v198
	v_pk_mul_f32 v[198:199], v[88:89], v[168:169] op_sel_hi:[1,0]
	v_pk_mul_f32 v[194:195], v[100:101], v[168:169] op_sel_hi:[1,0]
	v_mul_f32_e32 v198, 0xbfb8aa3b, v198
	v_mul_f32_e32 v199, 0xbfb8aa3b, v199
	v_exp_f32_e32 v198, v198
	v_exp_f32_e32 v199, v199
	v_exp_f32_e32 v157, v157
	v_add_f32_e32 v201, 1.0, v201
	v_add_f32_e32 v198, 1.0, v198
	v_add_f32_e32 v199, 1.0, v199
	v_rcp_f32_e32 v198, v198
	v_rcp_f32_e32 v199, v199
	v_add_f32_e32 v157, 1.0, v157
	v_rcp_f32_e32 v157, v157
	v_mul_f32_e32 v202, v194, v198
	v_mul_f32_e32 v203, v195, v199
	v_pk_mul_f32 v[198:199], v[78:79], v[168:169] op_sel_hi:[1,0]
	v_rcp_f32_e32 v201, v201
	v_mul_f32_e32 v198, 0xbfb8aa3b, v198
	v_exp_f32_e32 v204, v198
	v_mul_f32_e32 v198, 0xbfb8aa3b, v199
	v_exp_f32_e32 v205, v198
	v_pk_mul_f32 v[198:199], v[80:81], v[168:169] op_sel_hi:[1,0]
	v_add_f32_e32 v204, 1.0, v204
	v_mul_f32_e32 v198, 0xbfb8aa3b, v198
	v_mul_f32_e32 v199, 0xbfb8aa3b, v199
	v_exp_f32_e32 v198, v198
	v_exp_f32_e32 v199, v199
	v_add_f32_e32 v205, 1.0, v205
	v_rcp_f32_e32 v204, v204
	v_add_f32_e32 v198, 1.0, v198
	v_add_f32_e32 v199, 1.0, v199
	v_rcp_f32_e32 v198, v198
	v_rcp_f32_e32 v199, v199
	v_rcp_f32_e32 v205, v205
	v_pk_mul_f32 v[196:197], v[98:99], v[168:169] op_sel_hi:[1,0]
	v_pk_mul_f32 v[194:195], v[92:93], v[168:169] op_sel_hi:[1,0]
	v_lshlrev_b64 v[192:193], 11, v[170:171]
	v_mul_f32_e32 v157, v196, v157
	v_mul_f32_e32 v201, v197, v201
	v_pk_mul_f32 v[196:197], v[90:91], v[168:169] op_sel_hi:[1,0]
	v_mul_f32_e32 v198, v194, v198
	v_mul_f32_e32 v195, v195, v199
	v_mul_f32_e32 v204, v196, v204
	v_mul_f32_e32 v205, v197, v205
	v_lshl_add_u64 v[196:197], v[182:183], 0, v[192:193]
	v_cvt_pk_bf16_f32 v192, v157, v201
	v_cvt_pk_bf16_f32 v193, v202, v203
	v_cvt_pk_bf16_f32 v194, v204, v205
	v_cvt_pk_bf16_f32 v195, v198, v195
	v_pk_mul_f32 v[198:199], v[70:71], v[164:165] op_sel_hi:[1,0]
	flat_store_dwordx4 v[196:197], v[192:195] sc1
	v_mul_f32_e32 v157, 0xbfb8aa3b, v198
	v_mul_f32_e32 v198, 0xbfb8aa3b, v199
	v_exp_f32_e32 v201, v198
	v_pk_mul_f32 v[198:199], v[72:73], v[164:165] op_sel_hi:[1,0]
	v_pk_mul_f32 v[194:195], v[84:85], v[164:165] op_sel_hi:[1,0]
	v_mul_f32_e32 v198, 0xbfb8aa3b, v198
	v_mul_f32_e32 v199, 0xbfb8aa3b, v199
	v_exp_f32_e32 v198, v198
	v_exp_f32_e32 v199, v199
	v_exp_f32_e32 v157, v157
	v_add_f32_e32 v201, 1.0, v201
	v_add_f32_e32 v198, 1.0, v198
	v_add_f32_e32 v199, 1.0, v199
	v_rcp_f32_e32 v198, v198
	v_rcp_f32_e32 v199, v199
	v_add_f32_e32 v157, 1.0, v157
	v_rcp_f32_e32 v157, v157
	v_mul_f32_e32 v202, v194, v198
	v_mul_f32_e32 v203, v195, v199
	v_pk_mul_f32 v[198:199], v[66:67], v[164:165] op_sel_hi:[1,0]
	v_rcp_f32_e32 v201, v201
	v_mul_f32_e32 v198, 0xbfb8aa3b, v198
	v_exp_f32_e32 v204, v198
	v_mul_f32_e32 v198, 0xbfb8aa3b, v199
	v_exp_f32_e32 v205, v198
	v_pk_mul_f32 v[198:199], v[68:69], v[164:165] op_sel_hi:[1,0]
	v_add_f32_e32 v204, 1.0, v204
	v_mul_f32_e32 v199, 0xbfb8aa3b, v199
	v_mul_f32_e32 v198, 0xbfb8aa3b, v198
	v_exp_f32_e32 v199, v199
	v_exp_f32_e32 v198, v198
	v_add_f32_e32 v205, 1.0, v205
	v_rcp_f32_e32 v204, v204
	v_add_f32_e32 v199, 1.0, v199
	v_add_f32_e32 v198, 1.0, v198
	v_rcp_f32_e32 v199, v199
	v_rcp_f32_e32 v205, v205
	v_rcp_f32_e32 v198, v198
	v_pk_mul_f32 v[196:197], v[82:83], v[164:165] op_sel_hi:[1,0]
	v_pk_mul_f32 v[194:195], v[76:77], v[164:165] op_sel_hi:[1,0]
	v_lshlrev_b64 v[192:193], 11, v[166:167]
	v_mul_f32_e32 v157, v196, v157
	v_mul_f32_e32 v201, v197, v201
	v_pk_mul_f32 v[196:197], v[74:75], v[164:165] op_sel_hi:[1,0]
	v_mul_f32_e32 v195, v195, v199
	v_mul_f32_e32 v196, v196, v204
	v_mul_f32_e32 v197, v197, v205
	v_mul_f32_e32 v198, v194, v198
	v_lshl_add_u64 v[182:183], v[182:183], 0, v[192:193]
	v_cvt_pk_bf16_f32 v192, v157, v201
	v_cvt_pk_bf16_f32 v193, v202, v203
	v_cvt_pk_bf16_f32 v194, v196, v197
	v_cvt_pk_bf16_f32 v195, v198, v195
	flat_store_dwordx4 v[182:183], v[192:195] sc1
	v_pk_mul_f32 v[182:183], v[64:65], v[162:163] op_sel_hi:[1,0]
	s_nop 0
	v_pk_mul_f32 v[194:195], v[54:55], v[162:163] op_sel_hi:[1,0]
	v_pk_mul_f32 v[192:193], v[62:63], v[162:163] op_sel_hi:[1,0]
	v_mul_f32_e32 v157, 0xbfb8aa3b, v194
	v_mul_f32_e32 v194, 0xbfb8aa3b, v195
	v_exp_f32_e32 v196, v194
	v_pk_mul_f32 v[194:195], v[56:57], v[162:163] op_sel_hi:[1,0]
	v_exp_f32_e32 v157, v157
	v_mul_f32_e32 v194, 0xbfb8aa3b, v194
	v_mul_f32_e32 v195, 0xbfb8aa3b, v195
	v_exp_f32_e32 v194, v194
	v_exp_f32_e32 v195, v195
	v_add_f32_e32 v157, 1.0, v157
	v_add_f32_e32 v196, 1.0, v196
	v_add_f32_e32 v194, 1.0, v194
	v_add_f32_e32 v195, 1.0, v195
	v_rcp_f32_e32 v194, v194
	v_rcp_f32_e32 v195, v195
	v_rcp_f32_e32 v157, v157
	v_rcp_f32_e32 v196, v196
	v_mul_f32_e32 v197, v182, v194
	v_mul_f32_e32 v198, v183, v195
	v_pk_mul_f32 v[194:195], v[46:47], v[162:163] op_sel_hi:[1,0]
	v_pk_mul_f32 v[182:183], v[60:61], v[162:163] op_sel_hi:[1,0]
	v_mul_f32_e32 v194, 0xbfb8aa3b, v194
	v_exp_f32_e32 v199, v194
	v_mul_f32_e32 v194, 0xbfb8aa3b, v195
	v_exp_f32_e32 v201, v194
	v_pk_mul_f32 v[194:195], v[48:49], v[162:163] op_sel_hi:[1,0]
	v_add_f32_e32 v199, 1.0, v199
	v_mul_f32_e32 v194, 0xbfb8aa3b, v194
	v_exp_f32_e32 v194, v194
	v_mul_f32_e32 v195, 0xbfb8aa3b, v195
	v_exp_f32_e32 v195, v195
	v_add_f32_e32 v201, 1.0, v201
	v_add_f32_e32 v194, 1.0, v194
	v_rcp_f32_e32 v194, v194
	v_add_f32_e32 v195, 1.0, v195
	v_rcp_f32_e32 v199, v199
	v_rcp_f32_e32 v201, v201
	v_rcp_f32_e32 v195, v195
	v_mul_f32_e32 v157, v192, v157
	v_mul_f32_e32 v196, v193, v196
; __device__ __forceinline__ float sigmoid_fast(float x) { return __builtin_amdgcn_rcpf(1.0f + __builtin_amdgcn_exp2f(-1.4426950408889634f * x)); }
; __device__ __forceinline__ u32x4 pack8(const f32x4 v0, const f32x4 v1) { u32x4 w; w.x = cvt_pk_bf16(v0[0], v0[1]); w.y = cvt_pk_bf16(v0[2], v0[3]); w.z = cvt_pk_bf16(v1[0], v1[1]); w.w = cvt_pk_bf16(v1[2], v1[3]); return w; }
;     __device__ __forceinline__ void operator()(const f32x4 (&acc)[2][2][4][2], const Unit& u, int wr, int wc, int fr, int fq) const {
;     ...
;                 for (int m = 0; m < 4; ++m) { bf16_t* rowp = base + (size_t)(row0 + ai * HALF + m * 16) * 1024; const float rs = rs8[ai * 4 + m];
;                     f32x4 v[2];
; #pragma unroll
;                     for (int n = 0; n < 2; ++n) { const f32x4 a = acc[ai][0][m][n] * rs, g = acc[ai][1][m][n] * rs;
;                         v[n] = (f32x4){a[0] * sigmoid_fast(g[0]), a[1] * sigmoid_fast(g[1]), a[2] * sigmoid_fast(g[2]), a[3] * sigmoid_fast(g[3])}; }
;                     *(u32x4*)rowp = pack8(v[0], v[1]); }
	v_pk_mul_f32 v[192:193], v[58:59], v[162:163] op_sel_hi:[1,0]
	v_mul_f32_e32 v182, v182, v194
	v_mul_f32_e32 v199, v192, v199
	v_mul_f32_e32 v201, v193, v201
	v_mul_f32_e32 v183, v183, v195
	v_cvt_pk_bf16_f32 v192, v157, v196
	v_cvt_pk_bf16_f32 v193, v197, v198
	v_cvt_pk_bf16_f32 v194, v199, v201
	v_cvt_pk_bf16_f32 v195, v182, v183
	v_add_co_u32_e32 v182, vcc, s87, v180
	s_nop 1
	v_addc_co_u32_e32 v183, vcc, 0, v181, vcc
	flat_store_dwordx4 v[182:183], v[192:195] sc1
	v_pk_mul_f32 v[182:183], v[52:53], v[160:161] op_sel_hi:[1,0]
	s_nop 0
	v_pk_mul_f32 v[194:195], v[38:39], v[160:161] op_sel_hi:[1,0]
	v_pk_mul_f32 v[192:193], v[50:51], v[160:161] op_sel_hi:[1,0]
	v_mul_f32_e32 v157, 0xbfb8aa3b, v194
	v_mul_f32_e32 v194, 0xbfb8aa3b, v195
	v_exp_f32_e32 v196, v194
	v_pk_mul_f32 v[194:195], v[40:41], v[160:161] op_sel_hi:[1,0]
	v_exp_f32_e32 v157, v157
	v_mul_f32_e32 v194, 0xbfb8aa3b, v194
	v_mul_f32_e32 v195, 0xbfb8aa3b, v195
	v_exp_f32_e32 v194, v194
	v_exp_f32_e32 v195, v195
	v_add_f32_e32 v157, 1.0, v157
	v_add_f32_e32 v196, 1.0, v196
	v_add_f32_e32 v194, 1.0, v194
	v_add_f32_e32 v195, 1.0, v195
	v_rcp_f32_e32 v194, v194
	v_rcp_f32_e32 v195, v195
	v_rcp_f32_e32 v157, v157
	v_rcp_f32_e32 v196, v196
	v_mul_f32_e32 v197, v182, v194
	v_mul_f32_e32 v198, v183, v195
	v_pk_mul_f32 v[194:195], v[30:31], v[160:161] op_sel_hi:[1,0]
	v_pk_mul_f32 v[182:183], v[44:45], v[160:161] op_sel_hi:[1,0]
	v_mul_f32_e32 v194, 0xbfb8aa3b, v194
	v_exp_f32_e32 v199, v194
	v_mul_f32_e32 v194, 0xbfb8aa3b, v195
	v_exp_f32_e32 v201, v194
	v_pk_mul_f32 v[194:195], v[32:33], v[160:161] op_sel_hi:[1,0]
	v_add_f32_e32 v199, 1.0, v199
	v_mul_f32_e32 v194, 0xbfb8aa3b, v194
	v_exp_f32_e32 v194, v194
	v_mul_f32_e32 v195, 0xbfb8aa3b, v195
	v_exp_f32_e32 v195, v195
	v_add_f32_e32 v201, 1.0, v201
	v_add_f32_e32 v194, 1.0, v194
	v_rcp_f32_e32 v194, v194
	v_add_f32_e32 v195, 1.0, v195
	v_rcp_f32_e32 v199, v199
	v_rcp_f32_e32 v201, v201
	v_rcp_f32_e32 v195, v195
	v_mul_f32_e32 v157, v192, v157
	v_mul_f32_e32 v196, v193, v196
	v_pk_mul_f32 v[192:193], v[42:43], v[160:161] op_sel_hi:[1,0]
	v_mul_f32_e32 v182, v182, v194
	v_mul_f32_e32 v199, v192, v199
	v_mul_f32_e32 v201, v193, v201
	v_mul_f32_e32 v183, v183, v195
	v_cvt_pk_bf16_f32 v192, v157, v196
	v_cvt_pk_bf16_f32 v193, v197, v198
	v_cvt_pk_bf16_f32 v194, v199, v201
	v_cvt_pk_bf16_f32 v195, v182, v183
	v_add_co_u32_e32 v182, vcc, s88, v180
	s_nop 1
	v_addc_co_u32_e32 v183, vcc, 0, v181, vcc
	flat_store_dwordx4 v[182:183], v[192:195] sc1
	v_pk_mul_f32 v[182:183], v[36:37], v[158:159] op_sel_hi:[1,0]
	s_nop 0
	v_pk_mul_f32 v[194:195], v[22:23], v[158:159] op_sel_hi:[1,0]
	v_pk_mul_f32 v[192:193], v[34:35], v[158:159] op_sel_hi:[1,0]
	v_mul_f32_e32 v157, 0xbfb8aa3b, v194
	v_mul_f32_e32 v194, 0xbfb8aa3b, v195
	v_exp_f32_e32 v196, v194
	v_pk_mul_f32 v[194:195], v[24:25], v[158:159] op_sel_hi:[1,0]
	v_exp_f32_e32 v157, v157
	v_mul_f32_e32 v194, 0xbfb8aa3b, v194
	v_mul_f32_e32 v195, 0xbfb8aa3b, v195
	v_exp_f32_e32 v194, v194
	v_exp_f32_e32 v195, v195
	v_add_f32_e32 v157, 1.0, v157
	v_add_f32_e32 v196, 1.0, v196
	v_add_f32_e32 v194, 1.0, v194
	v_add_f32_e32 v195, 1.0, v195
	v_rcp_f32_e32 v194, v194
	v_rcp_f32_e32 v195, v195
	v_rcp_f32_e32 v157, v157
	v_rcp_f32_e32 v196, v196
	v_mul_f32_e32 v197, v182, v194
	v_mul_f32_e32 v198, v183, v195
	v_pk_mul_f32 v[194:195], v[14:15], v[158:159] op_sel_hi:[1,0]
	v_pk_mul_f32 v[182:183], v[28:29], v[158:159] op_sel_hi:[1,0]
	v_mul_f32_e32 v194, 0xbfb8aa3b, v194
	v_exp_f32_e32 v199, v194
	v_mul_f32_e32 v194, 0xbfb8aa3b, v195
	v_exp_f32_e32 v201, v194
	v_pk_mul_f32 v[194:195], v[16:17], v[158:159] op_sel_hi:[1,0]
	v_add_f32_e32 v199, 1.0, v199
	v_mul_f32_e32 v194, 0xbfb8aa3b, v194
	v_exp_f32_e32 v194, v194
	v_mul_f32_e32 v195, 0xbfb8aa3b, v195
	v_exp_f32_e32 v195, v195
	v_add_f32_e32 v201, 1.0, v201
	v_add_f32_e32 v194, 1.0, v194
	v_rcp_f32_e32 v194, v194
	v_add_f32_e32 v195, 1.0, v195
	v_rcp_f32_e32 v199, v199
	v_rcp_f32_e32 v201, v201
	v_rcp_f32_e32 v195, v195
	v_mul_f32_e32 v157, v192, v157
	v_mul_f32_e32 v196, v193, v196
	v_pk_mul_f32 v[192:193], v[26:27], v[158:159] op_sel_hi:[1,0]
	v_mul_f32_e32 v182, v182, v194
	v_mul_f32_e32 v199, v192, v199
	v_mul_f32_e32 v201, v193, v201
	v_mul_f32_e32 v183, v183, v195
	v_cvt_pk_bf16_f32 v192, v157, v196
	v_cvt_pk_bf16_f32 v193, v197, v198
	v_cvt_pk_bf16_f32 v194, v199, v201
	v_cvt_pk_bf16_f32 v195, v182, v183
	v_add_co_u32_e32 v182, vcc, s89, v180
	s_nop 1
	v_addc_co_u32_e32 v183, vcc, 0, v181, vcc
	flat_store_dwordx4 v[182:183], v[192:195] sc1
	v_pk_mul_f32 v[182:183], v[20:21], v[156:157] op_sel_hi:[1,0]
	v_add_co_u32_e32 v180, vcc, 0x58000, v180
	v_pk_mul_f32 v[194:195], v[6:7], v[156:157] op_sel_hi:[1,0]
	v_pk_mul_f32 v[192:193], v[18:19], v[156:157] op_sel_hi:[1,0]
	v_mul_f32_e32 v157, 0xbfb8aa3b, v194
	v_exp_f32_e32 v157, v157
	v_mul_f32_e32 v194, 0xbfb8aa3b, v195
	v_exp_f32_e32 v196, v194
	v_addc_co_u32_e32 v181, vcc, 0, v181, vcc
	v_pk_mul_f32 v[194:195], v[8:9], v[156:157] op_sel_hi:[1,0]
	v_add_f32_e32 v157, 1.0, v157
	v_mul_f32_e32 v194, 0xbfb8aa3b, v194
	v_mul_f32_e32 v195, 0xbfb8aa3b, v195
	v_exp_f32_e32 v194, v194
	v_exp_f32_e32 v195, v195
	v_rcp_f32_e32 v157, v157
	v_add_f32_e32 v196, 1.0, v196
	v_add_f32_e32 v194, 1.0, v194
	v_add_f32_e32 v195, 1.0, v195
	v_rcp_f32_e32 v194, v194
	v_rcp_f32_e32 v195, v195
	v_mul_f32_e32 v157, v192, v157
	v_rcp_f32_e32 v196, v196
	v_mul_f32_e32 v197, v182, v194
	v_mul_f32_e32 v198, v183, v195
	v_pk_mul_f32 v[194:195], v[2:3], v[156:157] op_sel_hi:[1,0]
	v_mul_f32_e32 v196, v193, v196
	v_mul_f32_e32 v194, 0xbfb8aa3b, v194
	v_exp_f32_e32 v199, v194
	v_mul_f32_e32 v194, 0xbfb8aa3b, v195
	v_exp_f32_e32 v201, v194
	v_pk_mul_f32 v[194:195], v[4:5], v[156:157] op_sel_hi:[1,0]
	v_add_f32_e32 v199, 1.0, v199
	v_mul_f32_e32 v194, 0xbfb8aa3b, v194
	v_mul_f32_e32 v195, 0xbfb8aa3b, v195
	v_exp_f32_e32 v194, v194
	v_exp_f32_e32 v195, v195
	v_add_f32_e32 v201, 1.0, v201
	v_rcp_f32_e32 v199, v199
	v_add_f32_e32 v194, 1.0, v194
	v_add_f32_e32 v195, 1.0, v195
	v_rcp_f32_e32 v201, v201
	v_rcp_f32_e32 v194, v194
	v_rcp_f32_e32 v195, v195
	v_pk_mul_f32 v[182:183], v[12:13], v[156:157] op_sel_hi:[1,0]
	v_pk_mul_f32 v[192:193], v[10:11], v[156:157] op_sel_hi:[1,0]
	v_mul_f32_e32 v182, v182, v194
	v_mul_f32_e32 v199, v192, v199
	v_mul_f32_e32 v201, v193, v201
	v_mul_f32_e32 v183, v183, v195
	v_cvt_pk_bf16_f32 v192, v157, v196
	v_cvt_pk_bf16_f32 v193, v197, v198
	v_cvt_pk_bf16_f32 v194, v199, v201
	v_cvt_pk_bf16_f32 v195, v182, v183
	flat_store_dwordx4 v[180:181], v[192:195] sc1
	s_cbranch_execnz .LBB0_189
; __device__ __forceinline__ u32x4 pack8(const f32x4 v0, const f32x4 v1) { u32x4 w; w.x = cvt_pk_bf16(v0[0], v0[1]); w.y = cvt_pk_bf16(v0[2], v0[3]); w.z = cvt_pk_bf16(v1[0], v1[1]); w.w = cvt_pk_bf16(v1[2], v1[3]); return w; }
;     __device__ __forceinline__ void operator()(const f32x4 (&acc)[2][2][4][2], const Unit& u, int wr, int wc, int fr, int fq) const {
;     ...
;             bf16_t* base = (u.pn < 4 ? Q : K) + (u.pn & 3) * 256 + wc * 32 + 8 * fq;
; #pragma unroll
;             for (int ai = 0; ai < 2; ++ai)
; #pragma unroll
;                 for (int m = 0; m < 4; ++m) { bf16_t* rowp = base + (size_t)(row0 + ai * HALF + m * 16) * 1024; const float rs = rs8[ai * 4 + m];
; #pragma unroll
;                     for (int bj = 0; bj < 2; ++bj) *(u32x4*)(rowp + bj * HALF) = pack8(acc[ai][bj][m][0] * rs, acc[ai][bj][m][1] * rs); }
.LBB0_191:
	s_cmp_lt_i32 s92, 4
	s_mov_b32 s26, 0xe800000
	s_cselect_b32 s26, s26, 0x12800000
	s_add_u32 s26, s24, s26
	s_addc_u32 s53, s25, 0
	s_lshl_b32 s55, s92, 9
	s_and_b32 s55, s55, 0x600
	s_add_u32 s26, s26, s55
	s_addc_u32 s53, s53, 0
	s_add_u32 s64, s26, s90
	s_addc_u32 s65, s53, 0
	v_lshl_add_u64 v[180:181], s[64:65], 0, v[134:135]
	v_lshlrev_b64 v[178:179], 11, v[178:179]
	v_lshl_add_u64 v[178:179], v[180:181], 0, v[178:179]
	s_waitcnt lgkmcnt(0)
	v_pk_mul_f32 v[128:129], v[128:129], v[176:177] op_sel_hi:[1,0]
	v_pk_mul_f32 v[126:127], v[126:127], v[176:177] op_sel_hi:[1,0]
	v_pk_mul_f32 v[182:183], v[124:125], v[176:177] op_sel_hi:[1,0]
	v_pk_mul_f32 v[124:125], v[122:123], v[176:177] op_sel_hi:[1,0]
	v_cvt_pk_bf16_f32 v122, v126, v127
	v_cvt_pk_bf16_f32 v123, v128, v129
	v_pk_mul_f32 v[120:121], v[120:121], v[176:177] op_sel_hi:[1,0]
	v_cvt_pk_bf16_f32 v124, v124, v125
	v_cvt_pk_bf16_f32 v125, v182, v183
	flat_store_dwordx4 v[178:179], v[122:125] sc1
	v_pk_mul_f32 v[118:119], v[118:119], v[176:177] op_sel_hi:[1,0]
	v_pk_mul_f32 v[114:115], v[114:115], v[172:173] op_sel_hi:[1,0]
	v_pk_mul_f32 v[122:123], v[112:113], v[176:177] op_sel_hi:[1,0]
	v_pk_mul_f32 v[112:113], v[110:111], v[176:177] op_sel_hi:[1,0]
	v_cvt_pk_bf16_f32 v110, v118, v119
	v_cvt_pk_bf16_f32 v111, v120, v121
	v_pk_mul_f32 v[104:105], v[104:105], v[172:173] op_sel_hi:[1,0]
	v_cvt_pk_bf16_f32 v112, v112, v113
	v_cvt_pk_bf16_f32 v113, v122, v123
	flat_store_dwordx4 v[178:179], v[110:113] offset:256 sc1
	v_pk_mul_f32 v[102:103], v[102:103], v[172:173] op_sel_hi:[1,0]
	v_pk_mul_f32 v[98:99], v[98:99], v[168:169] op_sel_hi:[1,0]
	v_lshlrev_b64 v[110:111], 11, v[174:175]
	v_lshl_add_u64 v[110:111], v[180:181], 0, v[110:111]
	v_pk_mul_f32 v[112:113], v[116:117], v[172:173] op_sel_hi:[1,0]
	v_pk_mul_f32 v[116:117], v[108:109], v[172:173] op_sel_hi:[1,0]
	v_pk_mul_f32 v[108:109], v[106:107], v[172:173] op_sel_hi:[1,0]
	v_cvt_pk_bf16_f32 v106, v114, v115
	v_cvt_pk_bf16_f32 v107, v112, v113
	v_pk_mul_f32 v[88:89], v[88:89], v[168:169] op_sel_hi:[1,0]
	v_cvt_pk_bf16_f32 v108, v108, v109
	v_cvt_pk_bf16_f32 v109, v116, v117
	flat_store_dwordx4 v[110:111], v[106:109] sc1
	v_pk_mul_f32 v[86:87], v[86:87], v[168:169] op_sel_hi:[1,0]
	v_pk_mul_f32 v[82:83], v[82:83], v[164:165] op_sel_hi:[1,0]
	v_pk_mul_f32 v[106:107], v[96:97], v[172:173] op_sel_hi:[1,0]
	v_pk_mul_f32 v[96:97], v[94:95], v[172:173] op_sel_hi:[1,0]
	v_cvt_pk_bf16_f32 v94, v102, v103
	v_cvt_pk_bf16_f32 v95, v104, v105
	v_pk_mul_f32 v[72:73], v[72:73], v[164:165] op_sel_hi:[1,0]
	v_cvt_pk_bf16_f32 v96, v96, v97
	v_cvt_pk_bf16_f32 v97, v106, v107
	flat_store_dwordx4 v[110:111], v[94:97] offset:256 sc1
	v_pk_mul_f32 v[70:71], v[70:71], v[164:165] op_sel_hi:[1,0]
	v_pk_mul_f32 v[62:63], v[62:63], v[162:163] op_sel_hi:[1,0]
	v_lshlrev_b64 v[94:95], 11, v[170:171]
	v_lshl_add_u64 v[94:95], v[180:181], 0, v[94:95]
	v_pk_mul_f32 v[96:97], v[100:101], v[168:169] op_sel_hi:[1,0]
	v_pk_mul_f32 v[100:101], v[92:93], v[168:169] op_sel_hi:[1,0]
	v_pk_mul_f32 v[92:93], v[90:91], v[168:169] op_sel_hi:[1,0]
	v_cvt_pk_bf16_f32 v90, v98, v99
	v_cvt_pk_bf16_f32 v91, v96, v97
	v_pk_mul_f32 v[64:65], v[64:65], v[162:163] op_sel_hi:[1,0]
	v_cvt_pk_bf16_f32 v92, v92, v93
	v_cvt_pk_bf16_f32 v93, v100, v101
	flat_store_dwordx4 v[94:95], v[90:93] sc1
	s_mov_b64 s[64:65], 0x40000
	v_pk_mul_f32 v[56:57], v[56:57], v[162:163] op_sel_hi:[1,0]
	v_pk_mul_f32 v[90:91], v[80:81], v[168:169] op_sel_hi:[1,0]
	v_pk_mul_f32 v[80:81], v[78:79], v[168:169] op_sel_hi:[1,0]
	v_cvt_pk_bf16_f32 v78, v86, v87
	v_cvt_pk_bf16_f32 v79, v88, v89
	v_pk_mul_f32 v[54:55], v[54:55], v[162:163] op_sel_hi:[1,0]
	v_cvt_pk_bf16_f32 v80, v80, v81
	v_cvt_pk_bf16_f32 v81, v90, v91
	flat_store_dwordx4 v[94:95], v[78:81] offset:256 sc1
	v_pk_mul_f32 v[50:51], v[50:51], v[160:161] op_sel_hi:[1,0]
	v_pk_mul_f32 v[40:41], v[40:41], v[160:161] op_sel_hi:[1,0]
	v_lshlrev_b64 v[78:79], 11, v[166:167]
	v_lshl_add_u64 v[78:79], v[180:181], 0, v[78:79]
	v_pk_mul_f32 v[80:81], v[84:85], v[164:165] op_sel_hi:[1,0]
	v_pk_mul_f32 v[84:85], v[76:77], v[164:165] op_sel_hi:[1,0]
	v_pk_mul_f32 v[76:77], v[74:75], v[164:165] op_sel_hi:[1,0]
	v_cvt_pk_bf16_f32 v74, v82, v83
	v_cvt_pk_bf16_f32 v75, v80, v81
; __device__ __forceinline__ u32x4 pack8(const f32x4 v0, const f32x4 v1) { u32x4 w; w.x = cvt_pk_bf16(v0[0], v0[1]); w.y = cvt_pk_bf16(v0[2], v0[3]); w.z = cvt_pk_bf16(v1[0], v1[1]); w.w = cvt_pk_bf16(v1[2], v1[3]); return w; }
;     __device__ __forceinline__ void operator()(const f32x4 (&acc)[2][2][4][2], const Unit& u, int wr, int wc, int fr, int fq) const {
;     ...
;                 for (int m = 0; m < 4; ++m) { bf16_t* rowp = base + (size_t)(row0 + ai * HALF + m * 16) * 1024; const float rs = rs8[ai * 4 + m];
; #pragma unroll
;                     for (int bj = 0; bj < 2; ++bj) *(u32x4*)(rowp + bj * HALF) = pack8(acc[ai][bj][m][0] * rs, acc[ai][bj][m][1] * rs); }
; template <class Epi, class Sched, bool ALIGN_EPI = false, bool SP2 = false>
; __device__ __forceinline__ void gemm_phase(PG8_LAS unsigned char* lds, const Gemm g, const Sched& S, const Epi& E) {
;     ...
;         if constexpr (!Epi::AFTER_DRAIN) { E(acc, cur, wr, wc, fr, fq); S.done(cur); }
;         if (!has_next) break;
; #pragma unroll
;         for (int a = 0; a < 2; ++a)
; #pragma unroll
;             for (int b = 0; b < 2; ++b)
; #pragma unroll
;                 for (int m = 0; m < 4; ++m)
; #pragma unroll
;                     for (int n = 0; n < 2; ++n) acc[a][b][m][n] = (f32x4){0.f, 0.f, 0.f, 0.f};
;         cur = nxt; cA = nA; cB = nB; ++ui;
	v_pk_mul_f32 v[38:39], v[38:39], v[160:161] op_sel_hi:[1,0]
	v_cvt_pk_bf16_f32 v76, v76, v77
	v_cvt_pk_bf16_f32 v77, v84, v85
	flat_store_dwordx4 v[78:79], v[74:77] sc1
	v_pk_mul_f32 v[34:35], v[34:35], v[158:159] op_sel_hi:[1,0]
	v_pk_mul_f32 v[24:25], v[24:25], v[158:159] op_sel_hi:[1,0]
	v_pk_mul_f32 v[74:75], v[68:69], v[164:165] op_sel_hi:[1,0]
	v_pk_mul_f32 v[68:69], v[66:67], v[164:165] op_sel_hi:[1,0]
	v_cvt_pk_bf16_f32 v66, v70, v71
	v_cvt_pk_bf16_f32 v67, v72, v73
	v_pk_mul_f32 v[22:23], v[22:23], v[158:159] op_sel_hi:[1,0]
	v_cvt_pk_bf16_f32 v68, v68, v69
	v_cvt_pk_bf16_f32 v69, v74, v75
	flat_store_dwordx4 v[78:79], v[66:69] offset:256 sc1
	s_mov_b32 s26, 0x58000
	v_pk_mul_f32 v[18:19], v[18:19], v[156:157] op_sel_hi:[1,0]
	v_pk_mul_f32 v[68:69], v[60:61], v[162:163] op_sel_hi:[1,0]
	v_pk_mul_f32 v[60:61], v[58:59], v[162:163] op_sel_hi:[1,0]
	v_cvt_pk_bf16_f32 v58, v62, v63
	v_add_co_u32_e32 v62, vcc, s87, v178
	v_cvt_pk_bf16_f32 v59, v64, v65
	v_cvt_pk_bf16_f32 v60, v60, v61
	v_cvt_pk_bf16_f32 v61, v68, v69
	v_lshl_add_u64 v[66:67], v[178:179], 0, s[64:65]
	s_nop 0
	v_addc_co_u32_e32 v63, vcc, 0, v179, vcc
	flat_store_dwordx4 v[62:63], v[58:61] sc1
	s_mov_b64 s[64:65], 0x48000
	v_pk_mul_f32 v[8:9], v[8:9], v[156:157] op_sel_hi:[1,0]
	v_pk_mul_f32 v[58:59], v[48:49], v[162:163] op_sel_hi:[1,0]
	v_pk_mul_f32 v[48:49], v[46:47], v[162:163] op_sel_hi:[1,0]
	v_cvt_pk_bf16_f32 v46, v54, v55
	v_cvt_pk_bf16_f32 v47, v56, v57
	v_pk_mul_f32 v[6:7], v[6:7], v[156:157] op_sel_hi:[1,0]
	v_cvt_pk_bf16_f32 v48, v48, v49
	v_cvt_pk_bf16_f32 v49, v58, v59
	flat_store_dwordx4 v[66:67], v[46:49] offset:256 sc1
	s_nop 1
	v_pk_mul_f32 v[48:49], v[52:53], v[160:161] op_sel_hi:[1,0]
	v_pk_mul_f32 v[52:53], v[44:45], v[160:161] op_sel_hi:[1,0]
	v_pk_mul_f32 v[44:45], v[42:43], v[160:161] op_sel_hi:[1,0]
	v_cvt_pk_bf16_f32 v42, v50, v51
	v_cvt_pk_bf16_f32 v43, v48, v49
	v_add_co_u32_e32 v48, vcc, s88, v178
	v_cvt_pk_bf16_f32 v44, v44, v45
	v_cvt_pk_bf16_f32 v45, v52, v53
	v_lshl_add_u64 v[46:47], v[178:179], 0, s[64:65]
	s_nop 0
	v_addc_co_u32_e32 v49, vcc, 0, v179, vcc
	flat_store_dwordx4 v[48:49], v[42:45] sc1
	s_mov_b64 s[64:65], 0x50000
	s_nop 0
	v_pk_mul_f32 v[42:43], v[32:33], v[160:161] op_sel_hi:[1,0]
	v_pk_mul_f32 v[32:33], v[30:31], v[160:161] op_sel_hi:[1,0]
	v_cvt_pk_bf16_f32 v30, v38, v39
	v_cvt_pk_bf16_f32 v31, v40, v41
	s_nop 0
	v_cvt_pk_bf16_f32 v32, v32, v33
	v_cvt_pk_bf16_f32 v33, v42, v43
	flat_store_dwordx4 v[46:47], v[30:33] offset:256 sc1
	s_nop 1
	v_pk_mul_f32 v[32:33], v[36:37], v[158:159] op_sel_hi:[1,0]
	v_pk_mul_f32 v[36:37], v[28:29], v[158:159] op_sel_hi:[1,0]
	v_pk_mul_f32 v[28:29], v[26:27], v[158:159] op_sel_hi:[1,0]
	v_cvt_pk_bf16_f32 v26, v34, v35
	v_cvt_pk_bf16_f32 v27, v32, v33
	v_add_co_u32_e32 v32, vcc, s89, v178
	v_cvt_pk_bf16_f32 v28, v28, v29
	v_cvt_pk_bf16_f32 v29, v36, v37
	v_lshl_add_u64 v[30:31], v[178:179], 0, s[64:65]
	s_nop 0
	v_addc_co_u32_e32 v33, vcc, 0, v179, vcc
	flat_store_dwordx4 v[32:33], v[26:29] sc1
	s_mov_b64 s[64:65], 0x58000
	s_nop 0
	v_pk_mul_f32 v[26:27], v[16:17], v[158:159] op_sel_hi:[1,0]
	v_pk_mul_f32 v[16:17], v[14:15], v[158:159] op_sel_hi:[1,0]
	v_cvt_pk_bf16_f32 v14, v22, v23
	v_cvt_pk_bf16_f32 v15, v24, v25
	s_nop 0
	v_cvt_pk_bf16_f32 v16, v16, v17
	v_cvt_pk_bf16_f32 v17, v26, v27
	flat_store_dwordx4 v[30:31], v[14:17] offset:256 sc1
	s_nop 1
	v_pk_mul_f32 v[16:17], v[20:21], v[156:157] op_sel_hi:[1,0]
	v_pk_mul_f32 v[20:21], v[12:13], v[156:157] op_sel_hi:[1,0]
	v_pk_mul_f32 v[12:13], v[10:11], v[156:157] op_sel_hi:[1,0]
	v_cvt_pk_bf16_f32 v10, v18, v19
	v_cvt_pk_bf16_f32 v11, v16, v17
	v_add_co_u32_e32 v16, vcc, s26, v178
	v_lshl_add_u64 v[14:15], v[178:179], 0, s[64:65]
	s_nop 0
	v_addc_co_u32_e32 v17, vcc, 0, v179, vcc
	v_cvt_pk_bf16_f32 v12, v12, v13
	v_cvt_pk_bf16_f32 v13, v20, v21
	flat_store_dwordx4 v[16:17], v[10:13] sc1
	s_nop 1
	v_pk_mul_f32 v[10:11], v[4:5], v[156:157] op_sel_hi:[1,0]
	v_pk_mul_f32 v[4:5], v[2:3], v[156:157] op_sel_hi:[1,0]
	v_cvt_pk_bf16_f32 v2, v6, v7
	v_cvt_pk_bf16_f32 v3, v8, v9
	s_nop 0
	v_cvt_pk_bf16_f32 v4, v4, v5
	v_cvt_pk_bf16_f32 v5, v10, v11
	flat_store_dwordx4 v[14:15], v[2:5] offset:256 sc1
	s_andn2_b64 vcc, exec, s[2:3]
	s_mov_b64 s[2:3], -1
	s_cbranch_vccnz .LBB0_174

;     __device__ __forceinline__ void operator()(const f32x4 (&acc)[2][2][4][2], const Unit& u, int wr, int wc, int fr, int fq) const {
;         const int row0 = u.pm * BM + wr * 64 + fr, col0 = u.pn * BM + wc * 32 + 8 * fq; bf16_t* base = O + col0;
;         f32x4 rc[2][2];
; #pragma unroll
;         for (int bj = 0; bj < 2; ++bj)
; #pragma unroll
;             for (int n = 0; n < 2; ++n) rc[bj][n] = *(const f32x4*)(rsv + col0 + bj * HALF + 4 * n);
; #pragma unroll
;         for (int ai = 0; ai < 2; ++ai)
; #pragma unroll
;             for (int m = 0; m < 4; ++m) { bf16_t* rowp = base + (size_t)(row0 + ai * HALF + m * 16) * ldc;
.LBB0_215:
	v_lshl_or_b32 v162, s93, 8, v166
	v_ashrrev_i32_e32 v163, 31, v162
	v_lshl_add_u64 v[130:131], v[162:163], 2, s[6:7]
	flat_load_dwordx4 v[142:145], v[130:131]
	flat_load_dwordx4 v[138:141], v[130:131] offset:16
	flat_load_dwordx4 v[134:137], v[130:131] offset:512
	s_nop 0
	flat_load_dwordx4 v[130:133], v[130:131] offset:528
	v_lshl_add_u32 v170, s66, 8, v164
	v_or_b32_e32 v172, 16, v170
	v_or_b32_e32 v174, 32, v170
	v_or_b32_e32 v176, 48, v170
	v_ashrrev_i32_e32 v171, 31, v170
	v_ashrrev_i32_e32 v173, 31, v172
	v_ashrrev_i32_e32 v175, 31, v174
	v_ashrrev_i32_e32 v177, 31, v176
	v_lshl_add_u64 v[178:179], v[162:163], 1, s[24:25]
	v_lshlrev_b64 v[162:163], 16, v[170:171]
	v_lshlrev_b64 v[170:171], 16, v[172:173]
	v_lshlrev_b64 v[172:173], 16, v[174:175]
	v_lshlrev_b64 v[174:175], 16, v[176:177]
	v_lshl_add_u64 v[162:163], v[178:179], 0, v[162:163]
	v_lshl_add_u64 v[170:171], v[178:179], 0, v[170:171]
	v_lshl_add_u64 v[172:173], v[178:179], 0, v[172:173]
	v_lshl_add_u64 v[174:175], v[178:179], 0, v[174:175]
	s_mov_b32 s55, 0x800000
	s_mov_b64 s[68:69], 0x800000
	s_waitcnt vmcnt(0) lgkmcnt(0)
; __device__ __forceinline__ u32x4 pack8(const f32x4 v0, const f32x4 v1) { u32x4 w; w.x = cvt_pk_bf16(v0[0], v0[1]); w.y = cvt_pk_bf16(v0[2], v0[3]); w.z = cvt_pk_bf16(v1[0], v1[1]); w.w = cvt_pk_bf16(v1[2], v1[3]); return w; }
; #define PG8_BAR __builtin_amdgcn_s_barrier()
;     __device__ __forceinline__ void operator()(const f32x4 (&acc)[2][2][4][2], const Unit& u, int wr, int wc, int fr, int fq) const {
;     ...
;         for (int ai = 0; ai < 2; ++ai)
; #pragma unroll
;             for (int m = 0; m < 4; ++m) { bf16_t* rowp = base + (size_t)(row0 + ai * HALF + m * 16) * ldc;
; #pragma unroll
;                 for (int bj = 0; bj < 2; ++bj) *(u32x4*)(rowp + bj * HALF) = pack8(acc[ai][bj][m][0] * rc[bj][0], acc[ai][bj][m][1] * rc[bj][1]); }
; template <class Epi, class Sched, bool ALIGN_EPI = false, bool SP2 = false>
; __device__ __forceinline__ void gemm_phase(PG8_LAS unsigned char* lds, const Gemm g, const Sched& S, const Epi& E) {
;     ...
;         if constexpr (ALIGN_EPI) { if (wr == 1) PG8_BAR; }
	v_pk_mul_f32 v[128:129], v[128:129], v[144:145]
	v_pk_mul_f32 v[126:127], v[126:127], v[142:143]
	v_pk_mul_f32 v[124:125], v[124:125], v[140:141]
	v_pk_mul_f32 v[122:123], v[122:123], v[138:139]
	v_pk_mul_f32 v[176:177], v[68:69], v[132:133]
	v_pk_mul_f32 v[178:179], v[66:67], v[130:131]
	v_cvt_pk_bf16_f32 v66, v126, v127
	v_cvt_pk_bf16_f32 v67, v128, v129
	v_cvt_pk_bf16_f32 v68, v122, v123
	v_cvt_pk_bf16_f32 v69, v124, v125
	v_pk_mul_f32 v[108:109], v[108:109], v[136:137]
	v_pk_mul_f32 v[106:107], v[106:107], v[134:135]
	v_pk_mul_f32 v[100:101], v[100:101], v[132:133]
	v_pk_mul_f32 v[98:99], v[98:99], v[130:131]
	flat_store_dwordx4 v[162:163], v[66:69] sc1
	v_pk_mul_f32 v[120:121], v[120:121], v[144:145]
	v_pk_mul_f32 v[118:119], v[118:119], v[142:143]
	v_cvt_pk_bf16_f32 v66, v106, v107
	v_cvt_pk_bf16_f32 v67, v108, v109
	v_cvt_pk_bf16_f32 v68, v98, v99
	v_cvt_pk_bf16_f32 v69, v100, v101
	v_pk_mul_f32 v[116:117], v[116:117], v[140:141]
	v_pk_mul_f32 v[114:115], v[114:115], v[138:139]
	flat_store_dwordx4 v[162:163], v[66:69] offset:256 sc1
	v_pk_mul_f32 v[92:93], v[92:93], v[136:137]
	v_pk_mul_f32 v[90:91], v[90:91], v[134:135]
	v_cvt_pk_bf16_f32 v66, v118, v119
	v_cvt_pk_bf16_f32 v67, v120, v121
	v_cvt_pk_bf16_f32 v68, v114, v115
	v_cvt_pk_bf16_f32 v69, v116, v117
	v_pk_mul_f32 v[84:85], v[84:85], v[132:133]
	v_pk_mul_f32 v[82:83], v[82:83], v[130:131]
	flat_store_dwordx4 v[170:171], v[66:69] sc1
	v_pk_mul_f32 v[112:113], v[112:113], v[144:145]
	v_pk_mul_f32 v[110:111], v[110:111], v[142:143]
	v_cvt_pk_bf16_f32 v66, v90, v91
	v_cvt_pk_bf16_f32 v67, v92, v93
	v_cvt_pk_bf16_f32 v68, v82, v83
	v_cvt_pk_bf16_f32 v69, v84, v85
	v_pk_mul_f32 v[104:105], v[104:105], v[140:141]
	v_pk_mul_f32 v[102:103], v[102:103], v[138:139]
	flat_store_dwordx4 v[170:171], v[66:69] offset:256 sc1
	v_pk_mul_f32 v[80:81], v[80:81], v[136:137]
	v_pk_mul_f32 v[78:79], v[78:79], v[134:135]
	v_cvt_pk_bf16_f32 v66, v110, v111
	v_cvt_pk_bf16_f32 v67, v112, v113
	v_cvt_pk_bf16_f32 v68, v102, v103
	v_cvt_pk_bf16_f32 v69, v104, v105
	v_pk_mul_f32 v[76:77], v[76:77], v[132:133]
	v_pk_mul_f32 v[74:75], v[74:75], v[130:131]
	flat_store_dwordx4 v[172:173], v[66:69] sc1
	v_pk_mul_f32 v[96:97], v[96:97], v[144:145]
	v_pk_mul_f32 v[94:95], v[94:95], v[142:143]
	v_cvt_pk_bf16_f32 v66, v78, v79
	v_cvt_pk_bf16_f32 v67, v80, v81
	v_cvt_pk_bf16_f32 v68, v74, v75
	v_cvt_pk_bf16_f32 v69, v76, v77
	v_pk_mul_f32 v[88:89], v[88:89], v[140:141]
	v_pk_mul_f32 v[86:87], v[86:87], v[138:139]
	flat_store_dwordx4 v[172:173], v[66:69] offset:256 sc1
	v_pk_mul_f32 v[72:73], v[72:73], v[136:137]
	v_pk_mul_f32 v[70:71], v[70:71], v[134:135]
	v_cvt_pk_bf16_f32 v66, v94, v95
	v_cvt_pk_bf16_f32 v67, v96, v97
	v_cvt_pk_bf16_f32 v68, v86, v87
	v_cvt_pk_bf16_f32 v69, v88, v89
	flat_store_dwordx4 v[174:175], v[66:69] sc1
	v_pk_mul_f32 v[62:63], v[62:63], v[142:143]
	v_pk_mul_f32 v[64:65], v[64:65], v[144:145]
	v_cvt_pk_bf16_f32 v66, v70, v71
	v_cvt_pk_bf16_f32 v67, v72, v73
	v_cvt_pk_bf16_f32 v68, v178, v179
	v_cvt_pk_bf16_f32 v69, v176, v177
	flat_store_dwordx4 v[174:175], v[66:69] offset:256 sc1
	v_pk_mul_f32 v[56:57], v[56:57], v[136:137]
	v_pk_mul_f32 v[54:55], v[54:55], v[134:135]
	v_pk_mul_f32 v[68:69], v[60:61], v[140:141]
	v_pk_mul_f32 v[60:61], v[58:59], v[138:139]
	v_cvt_pk_bf16_f32 v58, v62, v63
	v_add_co_u32_e32 v62, vcc, s55, v162
	v_cvt_pk_bf16_f32 v59, v64, v65
	v_cvt_pk_bf16_f32 v60, v60, v61
	v_cvt_pk_bf16_f32 v61, v68, v69
	v_lshl_add_u64 v[66:67], v[162:163], 0, s[68:69]
	s_nop 0
	v_addc_co_u32_e32 v63, vcc, 0, v163, vcc
	flat_store_dwordx4 v[62:63], v[58:61] sc1
	v_pk_mul_f32 v[50:51], v[50:51], v[142:143]
	s_mov_b64 s[68:69], 0x900000
	v_pk_mul_f32 v[58:59], v[48:49], v[132:133]
	v_pk_mul_f32 v[48:49], v[46:47], v[130:131]
	v_cvt_pk_bf16_f32 v46, v54, v55
	v_cvt_pk_bf16_f32 v47, v56, v57
	v_pk_mul_f32 v[40:41], v[40:41], v[136:137]
	v_cvt_pk_bf16_f32 v48, v48, v49
	v_cvt_pk_bf16_f32 v49, v58, v59
	flat_store_dwordx4 v[66:67], v[46:49] offset:256 sc1
	v_pk_mul_f32 v[38:39], v[38:39], v[134:135]
	v_pk_mul_f32 v[34:35], v[34:35], v[142:143]
	v_pk_mul_f32 v[48:49], v[52:53], v[144:145]
	v_pk_mul_f32 v[52:53], v[44:45], v[140:141]
	v_pk_mul_f32 v[44:45], v[42:43], v[138:139]
	v_cvt_pk_bf16_f32 v42, v50, v51
	v_cvt_pk_bf16_f32 v43, v48, v49
	v_add_co_u32_e32 v48, vcc, s90, v162
	v_cvt_pk_bf16_f32 v44, v44, v45
	v_cvt_pk_bf16_f32 v45, v52, v53
	v_lshl_add_u64 v[46:47], v[162:163], 0, s[68:69]
	s_nop 0
	v_addc_co_u32_e32 v49, vcc, 0, v163, vcc
	flat_store_dwordx4 v[48:49], v[42:45] sc1
	v_pk_mul_f32 v[24:25], v[24:25], v[136:137]
	v_pk_mul_f32 v[22:23], v[22:23], v[134:135]
	v_pk_mul_f32 v[42:43], v[32:33], v[132:133]
	v_pk_mul_f32 v[32:33], v[30:31], v[130:131]
	v_cvt_pk_bf16_f32 v30, v38, v39
	v_cvt_pk_bf16_f32 v31, v40, v41
	v_pk_mul_f32 v[18:19], v[18:19], v[142:143]
	v_cvt_pk_bf16_f32 v32, v32, v33
	v_cvt_pk_bf16_f32 v33, v42, v43
	flat_store_dwordx4 v[46:47], v[30:33] offset:256 sc1
	v_pk_mul_f32 v[8:9], v[8:9], v[136:137]
	v_pk_mul_f32 v[6:7], v[6:7], v[134:135]
	v_pk_mul_f32 v[32:33], v[36:37], v[144:145]
	v_pk_mul_f32 v[36:37], v[28:29], v[140:141]
	v_pk_mul_f32 v[28:29], v[26:27], v[138:139]
	v_cvt_pk_bf16_f32 v26, v34, v35
	v_cvt_pk_bf16_f32 v27, v32, v33
	v_add_co_u32_e32 v32, vcc, s91, v162
	v_cvt_pk_bf16_f32 v28, v28, v29
	v_cvt_pk_bf16_f32 v29, v36, v37
	v_lshl_add_u64 v[30:31], v[162:163], 0, s[40:41]
	s_nop 0
	v_addc_co_u32_e32 v33, vcc, 0, v163, vcc
	flat_store_dwordx4 v[32:33], v[26:29] sc1
	s_nop 1
	v_pk_mul_f32 v[26:27], v[16:17], v[132:133]
	v_pk_mul_f32 v[16:17], v[14:15], v[130:131]
	v_cvt_pk_bf16_f32 v14, v22, v23
	v_cvt_pk_bf16_f32 v15, v24, v25
	s_nop 0
	v_cvt_pk_bf16_f32 v16, v16, v17
	v_cvt_pk_bf16_f32 v17, v26, v27
	flat_store_dwordx4 v[30:31], v[14:17] offset:256 sc1
	s_nop 1
	v_pk_mul_f32 v[16:17], v[20:21], v[144:145]
	v_pk_mul_f32 v[20:21], v[12:13], v[140:141]
	v_pk_mul_f32 v[12:13], v[10:11], v[138:139]
	v_cvt_pk_bf16_f32 v10, v18, v19
	v_cvt_pk_bf16_f32 v11, v16, v17
	v_add_co_u32_e32 v16, vcc, s92, v162
	v_lshl_add_u64 v[14:15], v[162:163], 0, s[52:53]
	s_nop 0
	v_addc_co_u32_e32 v17, vcc, 0, v163, vcc
	v_cvt_pk_bf16_f32 v12, v12, v13
	v_cvt_pk_bf16_f32 v13, v20, v21
	flat_store_dwordx4 v[16:17], v[10:13] sc1
	s_andn2_b64 vcc, exec, s[2:3]
	s_mov_b64 s[2:3], -1
	v_pk_mul_f32 v[10:11], v[4:5], v[132:133]
	v_pk_mul_f32 v[4:5], v[2:3], v[130:131]
	v_cvt_pk_bf16_f32 v2, v6, v7
	v_cvt_pk_bf16_f32 v3, v8, v9
	s_nop 0
	v_cvt_pk_bf16_f32 v4, v4, v5
	v_cvt_pk_bf16_f32 v5, v10, v11
	flat_store_dwordx4 v[14:15], v[2:5] offset:256 sc1
	s_cbranch_vccnz .LBB0_204
	s_andn2_b64 vcc, exec, s[26:27]
	s_cbranch_vccnz .LBB0_203
	s_barrier
	s_branch .LBB0_203

; __device__ __forceinline__ void p2_qk_norm_rope(const Ptrs& P, int gw, int NGW, int lane) {
;     ...
;     for (int row = gw; row < M_TOK; row += NGW) {
;         bf16* pq = P.Q + (size_t)row * 1024 + grp * 128 + sub * 8; bf16* pk = P.K + (size_t)row * 1024 + grp * 128 + sub * 8;
;         const v4u q1 = *(const v4u*)pq, q2 = *(const v4u*)(pq + 64), k1 = *(const v4u*)pk, k2 = *(const v4u*)(pk + 64);
;         const int pos = row & (SEQ - 1);
;         const f32x4 c0 = *(const f32x4*)(P.COS + pos * 64 + sub * 8), c1 = *(const f32x4*)(P.COS + pos * 64 + sub * 8 + 4);
;         const f32x4 s0 = *(const f32x4*)(P.SIN + pos * 64 + sub * 8), s1 = *(const f32x4*)(P.SIN + pos * 64 + sub * 8 + 4);
; #pragma unroll
;         for (int which = 0; which < 2; ++which) {
;             const v4u r1 = which ? k1 : q1, r2 = which ? k2 : q2;
;             float t1[8], t2[8];
; #pragma unroll
;             for (int j = 0; j < 4; ++j) { t1[2 * j] = bflo(r1[j]); t1[2 * j + 1] = bfhi(r1[j]); t2[2 * j] = bflo(r2[j]); t2[2 * j + 1] = bfhi(r2[j]); }
;             float ss = 0.f;
; #pragma unroll
;             for (int j = 0; j < 8; ++j) ss += t1[j] * t1[j] + t2[j] * t2[j];
;             ss += __shfl_xor(ss, 1); ss += __shfl_xor(ss, 2); ss += __shfl_xor(ss, 4);
;             const float rinv = (1.0f / sqrtf(ss * (1.f / HD) + EPS_RMS)) * (which ? 1.0f : QSCALE);
;             float o1[8], o2[8];
; #pragma unroll
;             for (int j = 0; j < 8; ++j) {
;                 const float cc = j < 4 ? c0[j & 3] : c1[j & 3], sn = j < 4 ? s0[j & 3] : s1[j & 3];
;                 const float ga = which ? (j < 4 ? gk[0][j & 3] : gk[1][j & 3]) : (j < 4 ? gq[0][j & 3] : gq[1][j & 3]);
;                 const float gb = which ? (j < 4 ? gk[2][j & 3] : gk[3][j & 3]) : (j < 4 ? gq[2][j & 3] : gq[3][j & 3]);
;                 const float n1 = t1[j] * rinv * ga, n2 = t2[j] * rinv * gb;
;                 o1[j] = n1 * cc - n2 * sn; o2[j] = n2 * cc + n1 * sn;
;             }
.LBB0_290:
	flat_load_dwordx4 v[70:73], v[46:47] offset:128
	flat_load_dwordx4 v[74:77], v[46:47]
	s_and_b32 s0, s36, 0x7ffc0
	s_lshl_b32 s6, s0, 2
	v_lshl_add_u64 v[36:37], v[44:45], 0, s[6:7]
	v_lshl_add_u64 v[34:35], v[42:43], 0, s[6:7]
	flat_load_dwordx4 v[22:25], v[36:37] offset:16
	flat_load_dwordx4 v[18:21], v[34:35] offset:16
	flat_load_dwordx4 v[30:33], v[36:37]
	flat_load_dwordx4 v[26:29], v[34:35]
	v_add_co_u32_e32 v64, vcc, 0x4000000, v46
	s_add_i32 s5, s5, s4
	s_nop 0
	v_addc_co_u32_e32 v65, vcc, 0, v47, vcc
	flat_load_dwordx4 v[34:37], v[64:65]
	flat_load_dwordx4 v[38:41], v[64:65] offset:128
	s_add_i32 s36, s36, s26
	s_cmp_lt_i32 s5, 0x8000
	s_waitcnt vmcnt(0) lgkmcnt(0)
	v_lshlrev_b32_e32 v85, 16, v73
	v_and_b32_e32 v69, 0xffff0000, v73
	v_lshlrev_b32_e32 v87, 16, v72
	v_and_b32_e32 v89, 0xffff0000, v72
	v_and_b32_e32 v93, 0xffff0000, v71
	v_and_b32_e32 v92, 0xffff0000, v75
	v_lshlrev_b32_e32 v95, 16, v70
	v_lshlrev_b32_e32 v94, 16, v74
	v_and_b32_e32 v97, 0xffff0000, v70
	v_and_b32_e32 v96, 0xffff0000, v74
	v_lshlrev_b32_e32 v84, 16, v77
	v_and_b32_e32 v68, 0xffff0000, v77
	v_lshlrev_b32_e32 v86, 16, v76
	v_and_b32_e32 v88, 0xffff0000, v76
	v_lshlrev_b32_e32 v91, 16, v71
	v_lshlrev_b32_e32 v90, 16, v75
	v_mov_b32_e32 v70, v69
	v_mov_b32_e32 v71, v85
	v_mov_b32_e32 v74, v89
	v_mov_b32_e32 v75, v87
	v_pk_mul_f32 v[98:99], v[92:93], v[92:93]
	v_pk_mul_f32 v[100:101], v[94:95], v[94:95]
	v_pk_mul_f32 v[102:103], v[96:97], v[96:97]
	v_mov_b32_e32 v66, v68
	v_mov_b32_e32 v67, v84
	v_mov_b32_e32 v72, v88
	v_mov_b32_e32 v73, v86
	v_pk_mul_f32 v[76:77], v[90:91], v[90:91]
	v_pk_mul_f32 v[70:71], v[70:71], v[70:71]
	v_pk_mul_f32 v[74:75], v[74:75], v[74:75]
	v_add_f32_e32 v83, v98, v99
	v_add_f32_e32 v98, v102, v103
	v_add_f32_e32 v99, v100, v101
	v_add_f32_e32 v76, v76, v77
	v_pk_fma_f32 v[66:67], v[66:67], v[66:67], v[70:71]
	v_pk_fma_f32 v[70:71], v[72:73], v[72:73], v[74:75]
	v_add_f32_e32 v72, v99, v98
	v_add_f32_e32 v72, v76, v72
	v_add_f32_e32 v72, v83, v72
	v_add_f32_e32 v71, v71, v72
	v_add_f32_e32 v70, v70, v71
	v_add_f32_e32 v67, v67, v70
	v_add_f32_e32 v72, v66, v67
	v_mov_b32_e32 v99, v32
	v_mov_b32_e32 v74, v30
	v_mov_b32_e32 v75, v26
	v_mov_b32_e32 v70, v22
	v_mov_b32_dpp v73, v72 quad_perm:[1,0,3,2] row_mask:0xf bank_mask:0xf
	v_add_f32_e32 v76, v72, v73
	v_mov_b32_e32 v73, v28
	v_mov_b32_e32 v72, v32
	v_mov_b32_e32 v32, v29
	v_mov_b32_e32 v71, v18
	v_mov_b32_dpp v77, v76 quad_perm:[2,3,0,1] row_mask:0xf bank_mask:0xf
	v_add_f32_e32 v83, v76, v77
	v_mov_b32_e32 v76, v26
	v_mov_b32_e32 v77, v30
	v_mov_b32_e32 v66, v24
	v_mov_b32_e32 v67, v20
	v_mov_b32_dpp v98, v83 row_half_mirror row_mask:0xf bank_mask:0xf
	v_add_f32_e32 v83, v83, v98
	v_fmamk_f32 v83, v83, 0x3c000000, v78
	v_mul_f32_e32 v98, 0x4f800000, v83
	v_cmp_gt_f32_e32 vcc, s27, v83
	v_mov_b32_e32 v30, v27
	v_mov_b32_e32 v26, v31
	v_cndmask_b32_e32 v83, v83, v98, vcc
	v_sqrt_f32_e32 v100, v83
	v_mov_b32_e32 v98, v28
	v_and_b32_e32 v113, 0xffff0000, v38
	v_and_b32_e32 v112, 0xffff0000, v34
	v_add_u32_e32 v28, -1, v100
	v_add_u32_e32 v101, 1, v100
	v_fma_f32 v102, -v28, v100, v83
	v_fma_f32 v103, -v101, v100, v83
	v_cmp_ge_f32_e64 s[0:1], 0, v102
	s_nop 1
	v_cndmask_b32_e64 v28, v100, v28, s[0:1]
	v_cmp_lt_f32_e64 s[0:1], 0, v103
	s_nop 1
	v_cndmask_b32_e64 v28, v28, v101, s[0:1]
	v_mul_f32_e32 v100, 0x37800000, v28
	v_cndmask_b32_e32 v28, v28, v100, vcc
	v_cmp_class_f32_e32 vcc, v83, v79
	s_nop 1
	v_cndmask_b32_e32 v83, v28, v83, vcc
	v_div_scale_f32 v100, s[0:1], v83, v83, 1.0
	v_rcp_f32_e32 v101, v100
	v_div_scale_f32 v102, vcc, 1.0, v83, 1.0
	v_mov_b32_e32 v28, v33
	v_fma_f32 v103, -v100, v101, 1.0
	v_fmac_f32_e32 v101, v103, v101
	v_mul_f32_e32 v103, v102, v101
	v_fma_f32 v104, -v100, v103, v102
	v_fmac_f32_e32 v103, v104, v101
	v_fma_f32 v100, -v100, v103, v102
	v_div_fmas_f32 v100, v100, v101, v103
	v_div_fixup_f32 v83, v100, v83, 1.0
	v_mul_f32_e32 v100, 0x3e0293ee, v83
	v_pk_mul_f32 v[90:91], v[100:101], v[90:91] op_sel_hi:[0,1]
	v_pk_mul_f32 v[94:95], v[100:101], v[94:95] op_sel_hi:[0,1]
	v_pk_mul_f32 v[92:93], v[100:101], v[92:93] op_sel_hi:[0,1]
	v_pk_mul_f32 v[90:91], v[52:53], v[90:91]
	v_pk_mul_f32 v[86:87], v[100:101], v[86:87] op_sel_hi:[0,1]
	v_pk_mul_f32 v[94:95], v[54:55], v[94:95]
	v_pk_mul_f32 v[92:93], v[8:9], v[92:93]
	v_pk_mul_f32 v[106:107], v[98:99], v[90:91]
	v_pk_mul_f32 v[90:91], v[72:73], v[90:91]
	v_pk_mul_f32 v[86:87], v[50:51], v[86:87]
	v_pk_mul_f32 v[102:103], v[76:77], v[94:95]
	v_pk_mul_f32 v[94:95], v[74:75], v[94:95]
	v_pk_mul_f32 v[108:109], v[32:33], v[92:93]
	v_pk_mul_f32 v[92:93], v[28:29], v[92:93]
	v_add_f32_e32 v117, v90, v91
	v_mov_b32_e32 v90, v18
	v_mov_b32_e32 v91, v22
	v_pk_mul_f32 v[96:97], v[100:101], v[96:97] op_sel_hi:[0,1]
	v_add_f32_e32 v101, v94, v95
	v_add_f32_e32 v119, v92, v93
	v_pk_mul_f32 v[92:93], v[90:91], v[86:87]
	v_pk_mul_f32 v[86:87], v[70:71], v[86:87]
	v_mov_b32_e32 v22, v19
	v_add_f32_e32 v121, v86, v87
	v_pk_mul_f32 v[86:87], v[100:101], v[88:89] op_sel_hi:[0,1]
	v_pk_mul_f32 v[86:87], v[2:3], v[86:87]
	v_mov_b32_e32 v18, v23
	v_pk_mul_f32 v[88:89], v[22:23], v[86:87]
	v_pk_mul_f32 v[86:87], v[18:19], v[86:87]
	v_pk_mul_f32 v[84:85], v[100:101], v[84:85] op_sel_hi:[0,1]
	v_add_f32_e32 v123, v86, v87
	v_pk_mul_f32 v[84:85], v[48:49], v[84:85]
	v_mov_b32_e32 v86, v20
	v_mov_b32_e32 v87, v24
	v_sub_f32_e32 v122, v88, v89
	v_pk_mul_f32 v[88:89], v[86:87], v[84:85]
	v_pk_mul_f32 v[84:85], v[66:67], v[84:85]
	v_sub_f32_e32 v124, v88, v89
	v_add_f32_e32 v125, v84, v85
	v_lshlrev_b32_e32 v85, 16, v41
	v_and_b32_e32 v89, 0xffff0000, v41
	v_pk_mul_f32 v[96:97], v[6:7], v[96:97]
; __device__ __forceinline__ unsigned pk2(float lo, float hi) { return pg8::cvt_pk_bf16(lo, hi); }
; __device__ __forceinline__ void p2_qk_norm_rope(const Ptrs& P, int gw, int NGW, int lane) {
;     ...
;         for (int which = 0; which < 2; ++which) {
;             const v4u r1 = which ? k1 : q1, r2 = which ? k2 : q2;
;             float t1[8], t2[8];
; #pragma unroll
;             for (int j = 0; j < 4; ++j) { t1[2 * j] = bflo(r1[j]); t1[2 * j + 1] = bfhi(r1[j]); t2[2 * j] = bflo(r2[j]); t2[2 * j + 1] = bfhi(r2[j]); }
;             float ss = 0.f;
; #pragma unroll
;             for (int j = 0; j < 8; ++j) ss += t1[j] * t1[j] + t2[j] * t2[j];
;             ss += __shfl_xor(ss, 1); ss += __shfl_xor(ss, 2); ss += __shfl_xor(ss, 4);
;             const float rinv = (1.0f / sqrtf(ss * (1.f / HD) + EPS_RMS)) * (which ? 1.0f : QSCALE);
;             float o1[8], o2[8];
; #pragma unroll
;             for (int j = 0; j < 8; ++j) {
;                 const float cc = j < 4 ? c0[j & 3] : c1[j & 3], sn = j < 4 ? s0[j & 3] : s1[j & 3];
;                 const float ga = which ? (j < 4 ? gk[0][j & 3] : gk[1][j & 3]) : (j < 4 ? gq[0][j & 3] : gq[1][j & 3]);
;                 const float gb = which ? (j < 4 ? gk[2][j & 3] : gk[3][j & 3]) : (j < 4 ? gq[2][j & 3] : gq[3][j & 3]);
;                 const float n1 = t1[j] * rinv * ga, n2 = t2[j] * rinv * gb;
;                 o1[j] = n1 * cc - n2 * sn; o2[j] = n2 * cc + n1 * sn;
;             }
;             v4u w1, w2;
; #pragma unroll
;             for (int j = 0; j < 4; ++j) { w1[j] = pk2(o1[2 * j], o1[2 * j + 1]); w2[j] = pk2(o2[2 * j], o2[2 * j + 1]); }
;             bf16* p = which ? pk : pq;
;             *(v4u*)p = w1; *(v4u*)(p + 64) = w2;
;         }
	v_lshlrev_b32_e32 v84, 16, v37
	v_and_b32_e32 v88, 0xffff0000, v37
	v_mov_b32_e32 v94, v89
	v_mov_b32_e32 v95, v85
	v_pk_mul_f32 v[104:105], v[30:31], v[96:97]
	v_pk_mul_f32 v[96:97], v[26:27], v[96:97]
	v_sub_f32_e32 v120, v92, v93
	v_mov_b32_e32 v92, v88
	v_mov_b32_e32 v93, v84
	v_pk_mul_f32 v[94:95], v[94:95], v[94:95]
	v_add_f32_e32 v115, v96, v97
	v_pk_fma_f32 v[92:93], v[92:93], v[92:93], v[94:95]
	v_lshlrev_b32_e32 v95, 16, v40
	v_and_b32_e32 v97, 0xffff0000, v40
	v_sub_f32_e32 v118, v108, v109
	v_lshlrev_b32_e32 v94, 16, v36
	v_and_b32_e32 v96, 0xffff0000, v36
	v_mov_b32_e32 v40, v97
	v_mov_b32_e32 v41, v95
	v_lshlrev_b32_e32 v109, 16, v38
	v_lshlrev_b32_e32 v108, 16, v34
	v_sub_f32_e32 v83, v102, v103
	v_sub_f32_e32 v114, v104, v105
	v_mov_b32_e32 v36, v96
	v_mov_b32_e32 v37, v94
	v_pk_mul_f32 v[40:41], v[40:41], v[40:41]
	v_lshlrev_b32_e32 v103, 16, v39
	v_lshlrev_b32_e32 v102, 16, v35
	v_and_b32_e32 v104, 0xffff0000, v35
	v_pk_mul_f32 v[110:111], v[108:109], v[108:109]
	v_pk_mul_f32 v[34:35], v[112:113], v[112:113]
	v_pk_fma_f32 v[36:37], v[36:37], v[36:37], v[40:41]
	v_pk_mul_f32 v[40:41], v[102:103], v[102:103]
	v_and_b32_e32 v105, 0xffff0000, v39
	v_add_f32_e32 v24, v34, v35
	v_add_f32_e32 v34, v110, v111
	v_sub_f32_e32 v116, v106, v107
	v_pk_mul_f32 v[106:107], v[104:105], v[104:105]
	v_add_f32_e32 v24, v34, v24
	v_add_f32_e32 v34, v40, v41
	v_add_f32_e32 v20, v106, v107
	v_add_f32_e32 v24, v34, v24
	v_add_f32_e32 v20, v20, v24
	v_add_f32_e32 v20, v37, v20
	v_add_f32_e32 v20, v36, v20
	v_add_f32_e32 v20, v93, v20
	v_add_f32_e32 v20, v92, v20
	v_pk_mul_f32 v[34:35], v[100:101], v[68:69] op_sel_hi:[0,1]
	v_pk_mul_f32 v[34:35], v[4:5], v[34:35]
	v_mov_b32_e32 v24, v21
	v_pk_mul_f32 v[36:37], v[24:25], v[34:35]
	v_mov_b32_dpp v38, v20 quad_perm:[1,0,3,2] row_mask:0xf bank_mask:0xf
	v_add_f32_e32 v38, v20, v38
	v_sub_f32_e32 v37, v36, v37
	v_mov_b32_e32 v20, v25
	v_pk_mul_f32 v[34:35], v[20:21], v[34:35]
	v_mov_b32_dpp v39, v38 quad_perm:[2,3,0,1] row_mask:0xf bank_mask:0xf
	v_add_f32_e32 v36, v38, v39
	v_add_f32_e32 v41, v34, v35
	v_cvt_pk_bf16_f32 v34, v83, v114
	v_cvt_pk_bf16_f32 v38, v101, v115
	v_cvt_pk_bf16_f32 v35, v116, v118
	v_mov_b32_dpp v40, v36 row_half_mirror row_mask:0xf bank_mask:0xf
	v_add_f32_e32 v36, v36, v40
	v_fmamk_f32 v36, v36, 0x3c000000, v78
	v_mul_f32_e32 v40, 0x4f800000, v36
	v_cmp_gt_f32_e32 vcc, s27, v36
	v_cvt_pk_bf16_f32 v39, v117, v119
	s_nop 1
	v_cndmask_b32_e32 v68, v36, v40, vcc
	v_sqrt_f32_e32 v69, v68
	v_cvt_pk_bf16_f32 v36, v120, v122
	v_cvt_pk_bf16_f32 v40, v121, v123
	v_cvt_pk_bf16_f32 v37, v124, v37
	v_cvt_pk_bf16_f32 v41, v125, v41
	flat_store_dwordx4 v[46:47], v[34:37] sc1
	flat_store_dwordx4 v[46:47], v[38:41] offset:128 sc1
	v_add_u32_e32 v83, -1, v69
	v_fma_f32 v92, -v83, v69, v68
	v_cmp_ge_f32_e64 s[0:1], 0, v92
	v_add_u32_e32 v92, 1, v69
	v_lshl_add_u64 v[46:47], v[46:47], 0, s[24:25]
	v_cndmask_b32_e64 v83, v69, v83, s[0:1]
	v_fma_f32 v69, -v92, v69, v68
	v_cmp_lt_f32_e64 s[0:1], 0, v69
	s_nop 1
	v_cndmask_b32_e64 v69, v83, v92, s[0:1]
	v_mul_f32_e32 v83, 0x37800000, v69
	v_cndmask_b32_e32 v69, v69, v83, vcc
	v_cmp_class_f32_e32 vcc, v68, v79
	s_nop 1
	v_cndmask_b32_e32 v68, v69, v68, vcc
	v_div_scale_f32 v69, s[0:1], v68, v68, 1.0
	v_rcp_f32_e32 v83, v69
	s_nop 0
	v_fma_f32 v34, -v69, v83, 1.0
	v_fmac_f32_e32 v83, v34, v83
	v_div_scale_f32 v34, vcc, 1.0, v68, 1.0
	v_mul_f32_e32 v35, v34, v83
	v_fma_f32 v36, -v69, v35, v34
	v_fmac_f32_e32 v35, v36, v83
	v_fma_f32 v34, -v69, v35, v34
	v_div_fmas_f32 v34, v34, v83, v35
	v_div_fixup_f32 v34, v34, v68, 1.0
	v_pk_mul_f32 v[36:37], v[34:35], v[108:109] op_sel_hi:[0,1]
	v_pk_mul_f32 v[36:37], v[62:63], v[36:37]
	s_nop 0
	v_pk_mul_f32 v[38:39], v[76:77], v[36:37]
	v_pk_mul_f32 v[36:37], v[74:75], v[36:37]
	v_sub_f32_e32 v35, v38, v39
	v_add_f32_e32 v38, v36, v37
	v_pk_mul_f32 v[36:37], v[34:35], v[112:113] op_sel_hi:[0,1]
	v_pk_mul_f32 v[36:37], v[14:15], v[36:37]
	s_nop 0
	v_pk_mul_f32 v[26:27], v[26:27], v[36:37]
	v_pk_mul_f32 v[30:31], v[30:31], v[36:37]
	v_add_f32_e32 v36, v26, v27
	v_pk_mul_f32 v[26:27], v[34:35], v[102:103] op_sel_hi:[0,1]
	v_pk_mul_f32 v[26:27], v[60:61], v[26:27]
	v_sub_f32_e32 v39, v30, v31
	v_pk_mul_f32 v[30:31], v[98:99], v[26:27]
	v_pk_mul_f32 v[26:27], v[72:73], v[26:27]
	v_sub_f32_e32 v37, v30, v31
	v_add_f32_e32 v40, v26, v27
	v_pk_mul_f32 v[26:27], v[34:35], v[104:105] op_sel_hi:[0,1]
	v_pk_mul_f32 v[26:27], v[16:17], v[26:27]
	s_nop 0
	v_pk_mul_f32 v[30:31], v[32:33], v[26:27]
	v_pk_mul_f32 v[26:27], v[28:29], v[26:27]
	v_sub_f32_e32 v30, v30, v31
	v_add_f32_e32 v31, v26, v27
	v_pk_mul_f32 v[26:27], v[34:35], v[94:95] op_sel_hi:[0,1]
	v_pk_mul_f32 v[26:27], v[58:59], v[26:27]
	s_nop 0
	v_pk_mul_f32 v[28:29], v[90:91], v[26:27]
	v_pk_mul_f32 v[26:27], v[70:71], v[26:27]
	v_sub_f32_e32 v28, v28, v29
	v_add_f32_e32 v29, v26, v27
	v_pk_mul_f32 v[26:27], v[34:35], v[96:97] op_sel_hi:[0,1]
	v_pk_mul_f32 v[26:27], v[10:11], v[26:27]
	s_nop 0
	v_pk_mul_f32 v[18:19], v[18:19], v[26:27]
	v_pk_mul_f32 v[22:23], v[22:23], v[26:27]
	v_add_f32_e32 v26, v18, v19
	v_pk_mul_f32 v[18:19], v[34:35], v[84:85] op_sel_hi:[0,1]
	v_pk_mul_f32 v[18:19], v[56:57], v[18:19]
	v_sub_f32_e32 v32, v22, v23
	v_pk_mul_f32 v[22:23], v[86:87], v[18:19]
	v_pk_mul_f32 v[18:19], v[66:67], v[18:19]
	v_sub_f32_e32 v27, v22, v23
	v_add_f32_e32 v33, v18, v19
	v_pk_mul_f32 v[18:19], v[34:35], v[88:89] op_sel_hi:[0,1]
	v_pk_mul_f32 v[18:19], v[12:13], v[18:19]
	s_nop 0
	v_pk_mul_f32 v[22:23], v[24:25], v[18:19]
	v_pk_mul_f32 v[18:19], v[20:21], v[18:19]
	v_sub_f32_e32 v25, v22, v23
	v_add_f32_e32 v34, v18, v19
	v_cvt_pk_bf16_f32 v18, v35, v39
	v_cvt_pk_bf16_f32 v22, v38, v36
	v_cvt_pk_bf16_f32 v19, v37, v30
	v_cvt_pk_bf16_f32 v23, v40, v31
	v_cvt_pk_bf16_f32 v20, v28, v32
	v_cvt_pk_bf16_f32 v24, v29, v26
	v_cvt_pk_bf16_f32 v21, v27, v25
	v_cvt_pk_bf16_f32 v25, v33, v34
	flat_store_dwordx4 v[64:65], v[18:21] sc1
	flat_store_dwordx4 v[64:65], v[22:25] offset:128 sc1
	s_cbranch_scc1 .LBB0_290

; __device__ __forceinline__ float sigmoid_fast(float x) { return __builtin_amdgcn_rcpf(1.0f + __builtin_amdgcn_exp2f(-1.4426950408889634f * x)); }
; #define LAS __attribute__((address_space(3)))
; __device__ __forceinline__ unsigned pk2(float lo, float hi) { return pg8::cvt_pk_bf16(lo, hi); }
; __device__ __forceinline__ void p3_conv(const Ptrs& P, LAS unsigned char* lds, int first, int stride, int tid, int wave, int lane) {
;     ...
; #pragma unroll
;         for (int t = 0; t < 16; ++t) {
;             const float mu = stat[t * 2], rs = stat[t * 2 + 1];
;             const float y0 = (a[t].x - mu) * rs * lg.x + lb.x, y1 = (a[t].y - mu) * rs * lg.y + lb.y;
;             *(LAS unsigned*)(lds + OT_OFF + t * 2048 + tid * 4) = pk2(y0 * pg8::sigmoid_fast(y0), y1 * pg8::sigmoid_fast(y1));
.LBB0_366:
	s_or_b64 exec, exec, s[20:21]
	s_waitcnt lgkmcnt(0)
	s_barrier
	s_andn2_b64 vcc, exec, s[18:19]
	s_mov_b32 s0, s87
	v_mov_b32_e32 v242, s36
	ds_read_b128 v[72:75], v242
	ds_read_b128 v[76:79], v242 offset:16
	ds_read_b128 v[80:83], v242 offset:32
	ds_read_b128 v[84:87], v242 offset:48
	ds_read_b128 v[88:91], v242 offset:64
	ds_read_b128 v[92:95], v242 offset:80
	ds_read_b128 v[96:99], v242 offset:96
	ds_read_b128 v[100:103], v242 offset:112
	v_add_u32_e32 v243, s68, v173
	s_waitcnt lgkmcnt(0)
	v_sub_f32_e32 v204, v204, v72
	v_sub_f32_e32 v205, v205, v72
	v_sub_f32_e32 v206, v206, v74
	v_sub_f32_e32 v207, v207, v74
	v_sub_f32_e32 v208, v208, v76
	v_sub_f32_e32 v209, v209, v76
	v_sub_f32_e32 v210, v210, v78
	v_sub_f32_e32 v211, v211, v78
	v_sub_f32_e32 v212, v212, v80
	v_sub_f32_e32 v213, v213, v80
	v_sub_f32_e32 v214, v214, v82
	v_sub_f32_e32 v215, v215, v82
	v_sub_f32_e32 v216, v216, v84
	v_sub_f32_e32 v217, v217, v84
	v_sub_f32_e32 v218, v218, v86
	v_sub_f32_e32 v219, v219, v86
	v_sub_f32_e32 v220, v220, v88
	v_sub_f32_e32 v221, v221, v88
	v_sub_f32_e32 v222, v222, v90
	v_sub_f32_e32 v223, v223, v90
	v_sub_f32_e32 v224, v224, v92
	v_sub_f32_e32 v225, v225, v92
	v_sub_f32_e32 v226, v226, v94
	v_sub_f32_e32 v227, v227, v94
	v_sub_f32_e32 v228, v228, v96
	v_sub_f32_e32 v229, v229, v96
	v_sub_f32_e32 v230, v230, v98
	v_sub_f32_e32 v231, v231, v98
	v_sub_f32_e32 v232, v232, v100
	v_sub_f32_e32 v233, v233, v100
	v_sub_f32_e32 v234, v234, v102
	v_sub_f32_e32 v235, v235, v102
	v_mul_f32_e32 v204, v204, v73
	v_mul_f32_e32 v205, v205, v73
	v_mul_f32_e32 v206, v206, v75
	v_mul_f32_e32 v207, v207, v75
	v_mul_f32_e32 v208, v208, v77
	v_mul_f32_e32 v209, v209, v77
	v_mul_f32_e32 v210, v210, v79
	v_mul_f32_e32 v211, v211, v79
	v_mul_f32_e32 v212, v212, v81
	v_mul_f32_e32 v213, v213, v81
	v_mul_f32_e32 v214, v214, v83
	v_mul_f32_e32 v215, v215, v83
	v_mul_f32_e32 v216, v216, v85
	v_mul_f32_e32 v217, v217, v85
	v_mul_f32_e32 v218, v218, v87
	v_mul_f32_e32 v219, v219, v87
	v_mul_f32_e32 v220, v220, v89
	v_mul_f32_e32 v221, v221, v89
	v_mul_f32_e32 v222, v222, v91
	v_mul_f32_e32 v223, v223, v91
	v_mul_f32_e32 v224, v224, v93
	v_mul_f32_e32 v225, v225, v93
	v_mul_f32_e32 v226, v226, v95
	v_mul_f32_e32 v227, v227, v95
	v_mul_f32_e32 v228, v228, v97
	v_mul_f32_e32 v229, v229, v97
	v_mul_f32_e32 v230, v230, v99
	v_mul_f32_e32 v231, v231, v99
	v_mul_f32_e32 v232, v232, v101
	v_mul_f32_e32 v233, v233, v101
	v_mul_f32_e32 v234, v234, v103
	v_mul_f32_e32 v235, v235, v103
	v_fma_f32 v204, v66, v204, v68
	v_fma_f32 v205, v67, v205, v69
	v_fma_f32 v206, v66, v206, v68
	v_fma_f32 v207, v67, v207, v69
	v_fma_f32 v208, v66, v208, v68
	v_fma_f32 v209, v67, v209, v69
	v_fma_f32 v210, v66, v210, v68
	v_fma_f32 v211, v67, v211, v69
	v_fma_f32 v212, v66, v212, v68
	v_fma_f32 v213, v67, v213, v69
	v_fma_f32 v214, v66, v214, v68
	v_fma_f32 v215, v67, v215, v69
	v_fma_f32 v216, v66, v216, v68
	v_fma_f32 v217, v67, v217, v69
	v_fma_f32 v218, v66, v218, v68
	v_fma_f32 v219, v67, v219, v69
	v_fma_f32 v220, v66, v220, v68
	v_fma_f32 v221, v67, v221, v69
	v_fma_f32 v222, v66, v222, v68
	v_fma_f32 v223, v67, v223, v69
	v_fma_f32 v224, v66, v224, v68
	v_fma_f32 v225, v67, v225, v69
	v_fma_f32 v226, v66, v226, v68
	v_fma_f32 v227, v67, v227, v69
	v_fma_f32 v228, v66, v228, v68
	v_fma_f32 v229, v67, v229, v69
	v_fma_f32 v230, v66, v230, v68
	v_fma_f32 v231, v67, v231, v69
	v_fma_f32 v232, v66, v232, v68
	v_fma_f32 v233, v67, v233, v69
	v_fma_f32 v234, v66, v234, v68
	v_fma_f32 v235, v67, v235, v69
	v_mul_f32_e32 v104, 0xbfb8aa3b, v204
	v_mul_f32_e32 v105, 0xbfb8aa3b, v205
	v_mul_f32_e32 v106, 0xbfb8aa3b, v206
	v_mul_f32_e32 v107, 0xbfb8aa3b, v207
	v_mul_f32_e32 v108, 0xbfb8aa3b, v208
	v_mul_f32_e32 v109, 0xbfb8aa3b, v209
	v_mul_f32_e32 v110, 0xbfb8aa3b, v210
	v_mul_f32_e32 v111, 0xbfb8aa3b, v211
	v_mul_f32_e32 v112, 0xbfb8aa3b, v212
	v_mul_f32_e32 v113, 0xbfb8aa3b, v213
	v_mul_f32_e32 v114, 0xbfb8aa3b, v214
	v_mul_f32_e32 v115, 0xbfb8aa3b, v215
	v_mul_f32_e32 v116, 0xbfb8aa3b, v216
	v_mul_f32_e32 v117, 0xbfb8aa3b, v217
	v_mul_f32_e32 v118, 0xbfb8aa3b, v218
	v_mul_f32_e32 v119, 0xbfb8aa3b, v219
	v_mul_f32_e32 v120, 0xbfb8aa3b, v220
	v_mul_f32_e32 v121, 0xbfb8aa3b, v221
	v_mul_f32_e32 v122, 0xbfb8aa3b, v222
	v_mul_f32_e32 v123, 0xbfb8aa3b, v223
	v_mul_f32_e32 v124, 0xbfb8aa3b, v224
	v_mul_f32_e32 v125, 0xbfb8aa3b, v225
	v_mul_f32_e32 v126, 0xbfb8aa3b, v226
	v_mul_f32_e32 v127, 0xbfb8aa3b, v227
	v_mul_f32_e32 v128, 0xbfb8aa3b, v228
	v_mul_f32_e32 v129, 0xbfb8aa3b, v229
	v_mul_f32_e32 v130, 0xbfb8aa3b, v230
	v_mul_f32_e32 v131, 0xbfb8aa3b, v231
	v_mul_f32_e32 v132, 0xbfb8aa3b, v232
	v_mul_f32_e32 v133, 0xbfb8aa3b, v233
	v_mul_f32_e32 v134, 0xbfb8aa3b, v234
	v_mul_f32_e32 v135, 0xbfb8aa3b, v235
	v_exp_f32_e32 v104, v104
	v_exp_f32_e32 v105, v105
	v_exp_f32_e32 v106, v106
	v_exp_f32_e32 v107, v107
	v_exp_f32_e32 v108, v108
	v_exp_f32_e32 v109, v109
	v_exp_f32_e32 v110, v110
	v_exp_f32_e32 v111, v111
	v_exp_f32_e32 v112, v112
	v_exp_f32_e32 v113, v113
	v_exp_f32_e32 v114, v114
	v_exp_f32_e32 v115, v115
	v_exp_f32_e32 v116, v116
	v_exp_f32_e32 v117, v117
	v_exp_f32_e32 v118, v118
	v_exp_f32_e32 v119, v119
	v_exp_f32_e32 v120, v120
	v_exp_f32_e32 v121, v121
	v_exp_f32_e32 v122, v122
	v_exp_f32_e32 v123, v123
	v_exp_f32_e32 v124, v124
	v_exp_f32_e32 v125, v125
	v_exp_f32_e32 v126, v126
	v_exp_f32_e32 v127, v127
; __device__ __forceinline__ float sigmoid_fast(float x) { return __builtin_amdgcn_rcpf(1.0f + __builtin_amdgcn_exp2f(-1.4426950408889634f * x)); }
; #define LAS __attribute__((address_space(3)))
; __device__ __forceinline__ unsigned pk2(float lo, float hi) { return pg8::cvt_pk_bf16(lo, hi); }
; #define CBAR() do { LDS_WAIT(); asm volatile("" ::: "memory"); __builtin_amdgcn_s_barrier(); asm volatile("" ::: "memory"); } while (0)
; __device__ __forceinline__ void p3_conv(const Ptrs& P, LAS unsigned char* lds, int first, int stride, int tid, int wave, int lane) {
;     ...
;         for (int t = 0; t < 16; ++t) {
;             const float mu = stat[t * 2], rs = stat[t * 2 + 1];
;             const float y0 = (a[t].x - mu) * rs * lg.x + lb.x, y1 = (a[t].y - mu) * rs * lg.y + lb.y;
;             *(LAS unsigned*)(lds + OT_OFF + t * 2048 + tid * 4) = pk2(y0 * pg8::sigmoid_fast(y0), y1 * pg8::sigmoid_fast(y1));
;         }
;         CBAR();
; #pragma unroll
;         for (int k = 0; k < 4; ++k) { const int c = tid + 512 * k; const v4u v = *(const LAS v4u*)(lds + OT_OFF + c * 16);
;             *(v4u*)((char*)P.MIX + ((size_t)(row0 + (c >> 7)) * DM + ATT_W) * 2 + (size_t)(c & 127) * 16) = v; }
;         CBAR();
	v_exp_f32_e32 v128, v128
	v_exp_f32_e32 v129, v129
	v_exp_f32_e32 v130, v130
	v_exp_f32_e32 v131, v131
	v_exp_f32_e32 v132, v132
	v_exp_f32_e32 v133, v133
	v_exp_f32_e32 v134, v134
	v_exp_f32_e32 v135, v135
	v_add_f32_e32 v104, 1.0, v104
	v_add_f32_e32 v105, 1.0, v105
	v_add_f32_e32 v106, 1.0, v106
	v_add_f32_e32 v107, 1.0, v107
	v_add_f32_e32 v108, 1.0, v108
	v_add_f32_e32 v109, 1.0, v109
	v_add_f32_e32 v110, 1.0, v110
	v_add_f32_e32 v111, 1.0, v111
	v_add_f32_e32 v112, 1.0, v112
	v_add_f32_e32 v113, 1.0, v113
	v_add_f32_e32 v114, 1.0, v114
	v_add_f32_e32 v115, 1.0, v115
	v_add_f32_e32 v116, 1.0, v116
	v_add_f32_e32 v117, 1.0, v117
	v_add_f32_e32 v118, 1.0, v118
	v_add_f32_e32 v119, 1.0, v119
	v_add_f32_e32 v120, 1.0, v120
	v_add_f32_e32 v121, 1.0, v121
	v_add_f32_e32 v122, 1.0, v122
	v_add_f32_e32 v123, 1.0, v123
	v_add_f32_e32 v124, 1.0, v124
	v_add_f32_e32 v125, 1.0, v125
	v_add_f32_e32 v126, 1.0, v126
	v_add_f32_e32 v127, 1.0, v127
	v_add_f32_e32 v128, 1.0, v128
	v_add_f32_e32 v129, 1.0, v129
	v_add_f32_e32 v130, 1.0, v130
	v_add_f32_e32 v131, 1.0, v131
	v_add_f32_e32 v132, 1.0, v132
	v_add_f32_e32 v133, 1.0, v133
	v_add_f32_e32 v134, 1.0, v134
	v_add_f32_e32 v135, 1.0, v135
	v_rcp_f32_e32 v104, v104
	v_rcp_f32_e32 v105, v105
	v_rcp_f32_e32 v106, v106
	v_rcp_f32_e32 v107, v107
	v_rcp_f32_e32 v108, v108
	v_rcp_f32_e32 v109, v109
	v_rcp_f32_e32 v110, v110
	v_rcp_f32_e32 v111, v111
	v_rcp_f32_e32 v112, v112
	v_rcp_f32_e32 v113, v113
	v_rcp_f32_e32 v114, v114
	v_rcp_f32_e32 v115, v115
	v_rcp_f32_e32 v116, v116
	v_rcp_f32_e32 v117, v117
	v_rcp_f32_e32 v118, v118
	v_rcp_f32_e32 v119, v119
	v_rcp_f32_e32 v120, v120
	v_rcp_f32_e32 v121, v121
	v_rcp_f32_e32 v122, v122
	v_rcp_f32_e32 v123, v123
	v_rcp_f32_e32 v124, v124
	v_rcp_f32_e32 v125, v125
	v_rcp_f32_e32 v126, v126
	v_rcp_f32_e32 v127, v127
	v_rcp_f32_e32 v128, v128
	v_rcp_f32_e32 v129, v129
	v_rcp_f32_e32 v130, v130
	v_rcp_f32_e32 v131, v131
	v_rcp_f32_e32 v132, v132
	v_rcp_f32_e32 v133, v133
	v_rcp_f32_e32 v134, v134
	v_rcp_f32_e32 v135, v135
	v_mul_f32_e32 v204, v204, v104
	v_mul_f32_e32 v205, v205, v105
	v_mul_f32_e32 v206, v206, v106
	v_mul_f32_e32 v207, v207, v107
	v_mul_f32_e32 v208, v208, v108
	v_mul_f32_e32 v209, v209, v109
	v_mul_f32_e32 v210, v210, v110
	v_mul_f32_e32 v211, v211, v111
	v_mul_f32_e32 v212, v212, v112
	v_mul_f32_e32 v213, v213, v113
	v_mul_f32_e32 v214, v214, v114
	v_mul_f32_e32 v215, v215, v115
	v_mul_f32_e32 v216, v216, v116
	v_mul_f32_e32 v217, v217, v117
	v_mul_f32_e32 v218, v218, v118
	v_mul_f32_e32 v219, v219, v119
	v_mul_f32_e32 v220, v220, v120
	v_mul_f32_e32 v221, v221, v121
	v_mul_f32_e32 v222, v222, v122
	v_mul_f32_e32 v223, v223, v123
	v_mul_f32_e32 v224, v224, v124
	v_mul_f32_e32 v225, v225, v125
	v_mul_f32_e32 v226, v226, v126
	v_mul_f32_e32 v227, v227, v127
	v_mul_f32_e32 v228, v228, v128
	v_mul_f32_e32 v229, v229, v129
	v_mul_f32_e32 v230, v230, v130
	v_mul_f32_e32 v231, v231, v131
	v_mul_f32_e32 v232, v232, v132
	v_mul_f32_e32 v233, v233, v133
	v_mul_f32_e32 v234, v234, v134
	v_mul_f32_e32 v235, v235, v135
	v_cvt_pk_bf16_f32 v104, v204, v205
	v_cvt_pk_bf16_f32 v106, v206, v207
	v_cvt_pk_bf16_f32 v108, v208, v209
	v_cvt_pk_bf16_f32 v110, v210, v211
	v_cvt_pk_bf16_f32 v112, v212, v213
	v_cvt_pk_bf16_f32 v114, v214, v215
	v_cvt_pk_bf16_f32 v116, v216, v217
	v_cvt_pk_bf16_f32 v118, v218, v219
	v_cvt_pk_bf16_f32 v120, v220, v221
	v_cvt_pk_bf16_f32 v122, v222, v223
	v_cvt_pk_bf16_f32 v124, v224, v225
	v_cvt_pk_bf16_f32 v126, v226, v227
	v_cvt_pk_bf16_f32 v128, v228, v229
	v_cvt_pk_bf16_f32 v130, v230, v231
	v_cvt_pk_bf16_f32 v132, v232, v233
	v_cvt_pk_bf16_f32 v134, v234, v235
	ds_write_b32 v243, v104
	ds_write_b32 v243, v106 offset:2048
	ds_write_b32 v243, v108 offset:4096
	ds_write_b32 v243, v110 offset:6144
	ds_write_b32 v243, v112 offset:8192
	ds_write_b32 v243, v114 offset:10240
	ds_write_b32 v243, v116 offset:12288
	ds_write_b32 v243, v118 offset:14336
	ds_write_b32 v243, v120 offset:16384
	ds_write_b32 v243, v122 offset:18432
	ds_write_b32 v243, v124 offset:20480
	ds_write_b32 v243, v126 offset:22528
	ds_write_b32 v243, v128 offset:24576
	ds_write_b32 v243, v130 offset:26624
	ds_write_b32 v243, v132 offset:28672
	ds_write_b32 v243, v134 offset:30720
	s_waitcnt lgkmcnt(0)
	s_barrier
	v_add_u32_e32 v72, s68, v177
	ds_read_b128 v[72:75], v72
	v_or_b32_e32 v76, s88, v192
	v_ashrrev_i32_e32 v77, 31, v76
	v_lshlrev_b64 v[76:77], 12, v[76:77]
	v_lshl_add_u64 v[76:77], v[70:71], 0, v[76:77]
	s_waitcnt lgkmcnt(0)
	flat_store_dwordx4 v[76:77], v[72:75] offset:2048 sc1
	ds_read_b128 v[72:75], v197
	v_or_b32_e32 v76, s88, v193
	v_ashrrev_i32_e32 v77, 31, v76
	v_lshlrev_b64 v[76:77], 12, v[76:77]
	v_lshl_add_u64 v[76:77], v[70:71], 0, v[76:77]
	s_waitcnt lgkmcnt(0)
	flat_store_dwordx4 v[76:77], v[72:75] offset:2048 sc1
	ds_read_b128 v[72:75], v198
	v_or_b32_e32 v76, s88, v194
	v_ashrrev_i32_e32 v77, 31, v76
	v_lshlrev_b64 v[76:77], 12, v[76:77]
	v_lshl_add_u64 v[76:77], v[70:71], 0, v[76:77]
	s_waitcnt lgkmcnt(0)
	flat_store_dwordx4 v[76:77], v[72:75] offset:2048 sc1
	ds_read_b128 v[72:75], v199
	v_add_u32_e32 v76, s88, v195
	v_ashrrev_i32_e32 v77, 31, v76
	v_lshlrev_b64 v[76:77], 12, v[76:77]
	v_lshl_add_u64 v[76:77], v[70:71], 0, v[76:77]
	s_waitcnt lgkmcnt(0)
	flat_store_dwordx4 v[76:77], v[72:75] offset:2048 sc1
	s_waitcnt lgkmcnt(0)
	s_barrier
	s_cbranch_vccz .LBB0_406

; #define LAS __attribute__((address_space(3)))
; __device__ __forceinline__ void attn_block(LAS unsigned char* lds, const Ptrs& P, int b, int h, int qb, float negMb, float lam, int tid, int wid, int lane) {
;     ...
;     if (comp == 0) {
;         float ss = 0.f;
; #pragma unroll
;         for (int e = 0; e < 8; ++e)
; #pragma unroll
;             for (int r4 = 0; r4 < 4; ++r4) { const f32x4 x1 = *(const LAS f32x4*)(xb + (e * 4 + r4) * 1024);
; #pragma unroll
;                 for (int i = 0; i < 4; ++i) { const float v = o[e][4 * r4 + i] * inv - x1[i]; o[e][4 * r4 + i] = v; ss += v * v; } }
.LBB0_427:
	s_waitcnt lgkmcnt(0)
	s_barrier
	s_andn2_b64 vcc, exec, s[14:15]
	s_cbranch_vccnz .LBB0_412
	ds_read_b128 v[152:155], v149
	ds_read_b128 v[156:159], v149 offset:1024
	ds_read_b128 v[160:163], v149 offset:2048
	v_and_or_b32 v194, v147, 31, s80
	s_waitcnt lgkmcnt(2)
	v_fma_f32 v150, v131, v148, -v153
	v_fma_f32 v151, v130, v148, -v152
	v_fma_f32 v146, v132, v148, -v154
	v_mul_f32_e32 v154, v150, v150
	v_fmac_f32_e32 v154, v151, v151
	v_fma_f32 v133, v133, v148, -v155
	v_fmac_f32_e32 v154, v146, v146
	v_fmac_f32_e32 v154, v133, v133
	s_waitcnt lgkmcnt(1)
	v_fma_f32 v130, v134, v148, -v156
	v_fmac_f32_e32 v154, v130, v130
	v_fma_f32 v131, v135, v148, -v157
	v_fmac_f32_e32 v154, v131, v131
	v_fma_f32 v132, v136, v148, -v158
	v_fmac_f32_e32 v154, v132, v132
	v_fma_f32 v152, v137, v148, -v159
	ds_read_b128 v[156:159], v149 offset:3072
	v_fmac_f32_e32 v154, v152, v152
	s_waitcnt lgkmcnt(1)
	v_fma_f32 v153, v138, v148, -v160
	v_fmac_f32_e32 v154, v153, v153
	v_fma_f32 v139, v139, v148, -v161
	v_fmac_f32_e32 v154, v139, v139
	v_fma_f32 v137, v140, v148, -v162
	v_fmac_f32_e32 v154, v137, v137
	v_fma_f32 v138, v141, v148, -v163
	ds_read_b128 v[160:163], v149 offset:4096
	v_fmac_f32_e32 v154, v138, v138
	s_waitcnt lgkmcnt(1)
	v_fma_f32 v134, v142, v148, -v156
	v_fmac_f32_e32 v154, v134, v134
	v_fma_f32 v135, v143, v148, -v157
	v_fmac_f32_e32 v154, v135, v135
	v_fma_f32 v136, v144, v148, -v158
	v_fmac_f32_e32 v154, v136, v136
	v_fma_f32 v141, v145, v148, -v159
	ds_read_b128 v[156:159], v149 offset:5120
	v_fmac_f32_e32 v154, v141, v141
	s_waitcnt lgkmcnt(1)
	v_fma_f32 v142, v114, v148, -v160
	v_fmac_f32_e32 v154, v142, v142
	v_fma_f32 v143, v115, v148, -v161
	v_fmac_f32_e32 v154, v143, v143
	v_fma_f32 v140, v116, v148, -v162
	v_fmac_f32_e32 v154, v140, v140
	v_fma_f32 v117, v117, v148, -v163
	ds_read_b128 v[160:163], v149 offset:6144
	v_fmac_f32_e32 v154, v117, v117
	s_waitcnt lgkmcnt(1)
	v_fma_f32 v114, v118, v148, -v156
	v_fmac_f32_e32 v154, v114, v114
	v_fma_f32 v115, v119, v148, -v157
	v_fmac_f32_e32 v154, v115, v115
	v_fma_f32 v116, v120, v148, -v158
	v_fmac_f32_e32 v154, v116, v116
	v_fma_f32 v144, v121, v148, -v159
	ds_read_b128 v[156:159], v149 offset:7168
	v_fmac_f32_e32 v154, v144, v144
	s_waitcnt lgkmcnt(1)
	v_fma_f32 v145, v122, v148, -v160
	v_fmac_f32_e32 v154, v145, v145
	v_fma_f32 v123, v123, v148, -v161
	v_fmac_f32_e32 v154, v123, v123
	v_fma_f32 v121, v124, v148, -v162
	v_fmac_f32_e32 v154, v121, v121
	v_fma_f32 v122, v125, v148, -v163
	ds_read_b128 v[160:163], v149 offset:8192
	v_fmac_f32_e32 v154, v122, v122
	s_waitcnt lgkmcnt(1)
	v_fma_f32 v118, v126, v148, -v156
	v_fmac_f32_e32 v154, v118, v118
	v_fma_f32 v119, v127, v148, -v157
	v_fmac_f32_e32 v154, v119, v119
	v_fma_f32 v120, v128, v148, -v158
	v_fmac_f32_e32 v154, v120, v120
	v_fma_f32 v125, v129, v148, -v159
	ds_read_b128 v[156:159], v149 offset:9216
	v_fmac_f32_e32 v154, v125, v125
	s_waitcnt lgkmcnt(1)
	v_fma_f32 v126, v98, v148, -v160
	v_fmac_f32_e32 v154, v126, v126
	v_fma_f32 v127, v99, v148, -v161
	v_fmac_f32_e32 v154, v127, v127
	v_fma_f32 v124, v100, v148, -v162
	v_fmac_f32_e32 v154, v124, v124
	v_fma_f32 v101, v101, v148, -v163
	ds_read_b128 v[160:163], v149 offset:10240
	v_fmac_f32_e32 v154, v101, v101
	s_waitcnt lgkmcnt(1)
	v_fma_f32 v98, v102, v148, -v156
	v_fmac_f32_e32 v154, v98, v98
	v_fma_f32 v99, v103, v148, -v157
	v_fmac_f32_e32 v154, v99, v99
	v_fma_f32 v100, v104, v148, -v158
	v_fmac_f32_e32 v154, v100, v100
	v_fma_f32 v128, v105, v148, -v159
	ds_read_b128 v[156:159], v149 offset:11264
	v_fmac_f32_e32 v154, v128, v128
	s_waitcnt lgkmcnt(1)
	v_fma_f32 v129, v106, v148, -v160
	v_fmac_f32_e32 v154, v129, v129
	v_fma_f32 v107, v107, v148, -v161
	v_fmac_f32_e32 v154, v107, v107
	v_fma_f32 v105, v108, v148, -v162
	v_fmac_f32_e32 v154, v105, v105
	v_fma_f32 v106, v109, v148, -v163
	ds_read_b128 v[160:163], v149 offset:12288
	v_fmac_f32_e32 v154, v106, v106
	s_waitcnt lgkmcnt(1)
	v_fma_f32 v102, v110, v148, -v156
	v_fmac_f32_e32 v154, v102, v102
	v_fma_f32 v103, v111, v148, -v157
	v_fmac_f32_e32 v154, v103, v103
	v_fma_f32 v104, v112, v148, -v158
	v_fmac_f32_e32 v154, v104, v104
	v_fma_f32 v109, v113, v148, -v159
	ds_read_b128 v[156:159], v149 offset:13312
	v_fmac_f32_e32 v154, v109, v109
	s_waitcnt lgkmcnt(1)
	v_fma_f32 v110, v82, v148, -v160
	v_fmac_f32_e32 v154, v110, v110
	v_fma_f32 v111, v83, v148, -v161
	v_fmac_f32_e32 v154, v111, v111
	v_fma_f32 v108, v84, v148, -v162
	v_fmac_f32_e32 v154, v108, v108
	v_fma_f32 v85, v85, v148, -v163
	ds_read_b128 v[160:163], v149 offset:14336
	v_fmac_f32_e32 v154, v85, v85
	s_waitcnt lgkmcnt(1)
	v_fma_f32 v82, v86, v148, -v156
	v_fmac_f32_e32 v154, v82, v82
	v_fma_f32 v83, v87, v148, -v157
	v_fmac_f32_e32 v154, v83, v83
	v_fma_f32 v84, v88, v148, -v158
	v_fmac_f32_e32 v154, v84, v84
	v_fma_f32 v112, v89, v148, -v159
	ds_read_b128 v[156:159], v149 offset:15360
	v_fmac_f32_e32 v154, v112, v112
	s_waitcnt lgkmcnt(1)
	v_fma_f32 v113, v90, v148, -v160
	v_fmac_f32_e32 v154, v113, v113
	v_fma_f32 v91, v91, v148, -v161
	v_fmac_f32_e32 v154, v91, v91
	v_fma_f32 v89, v92, v148, -v162
	v_fmac_f32_e32 v154, v89, v89
	v_fma_f32 v90, v93, v148, -v163
	ds_read_b128 v[160:163], v149 offset:16384
	v_fmac_f32_e32 v154, v90, v90
	s_waitcnt lgkmcnt(1)
	v_fma_f32 v86, v94, v148, -v156
	v_fmac_f32_e32 v154, v86, v86
	v_fma_f32 v87, v95, v148, -v157
	v_fmac_f32_e32 v154, v87, v87
	v_fma_f32 v88, v96, v148, -v158
	v_fmac_f32_e32 v154, v88, v88
	v_fma_f32 v93, v97, v148, -v159
	ds_read_b128 v[156:159], v149 offset:17408
	v_fmac_f32_e32 v154, v93, v93
	s_waitcnt lgkmcnt(1)
; #define LAS __attribute__((address_space(3)))
; __device__ __forceinline__ void attn_block(LAS unsigned char* lds, const Ptrs& P, int b, int h, int qb, float negMb, float lam, int tid, int wid, int lane) {
;     ...
; #pragma unroll
;         for (int e = 0; e < 8; ++e)
; #pragma unroll
;             for (int r4 = 0; r4 < 4; ++r4) { const f32x4 x1 = *(const LAS f32x4*)(xb + (e * 4 + r4) * 1024);
; #pragma unroll
;                 for (int i = 0; i < 4; ++i) { const float v = o[e][4 * r4 + i] * inv - x1[i]; o[e][4 * r4 + i] = v; ss += v * v; } }
;         ss += __shfl_xor(ss, 32);
	v_fma_f32 v94, v66, v148, -v160
	v_fmac_f32_e32 v154, v94, v94
	v_fma_f32 v95, v67, v148, -v161
	v_fmac_f32_e32 v154, v95, v95
	v_fma_f32 v92, v68, v148, -v162
	v_fmac_f32_e32 v154, v92, v92
	v_fma_f32 v69, v69, v148, -v163
	ds_read_b128 v[160:163], v149 offset:18432
	v_fmac_f32_e32 v154, v69, v69
	s_waitcnt lgkmcnt(1)
	v_fma_f32 v66, v70, v148, -v156
	v_fmac_f32_e32 v154, v66, v66
	v_fma_f32 v67, v71, v148, -v157
	v_fmac_f32_e32 v154, v67, v67
	v_fma_f32 v68, v72, v148, -v158
	v_fmac_f32_e32 v154, v68, v68
	v_fma_f32 v96, v73, v148, -v159
	ds_read_b128 v[156:159], v149 offset:19456
	v_fmac_f32_e32 v154, v96, v96
	s_waitcnt lgkmcnt(1)
	v_fma_f32 v97, v74, v148, -v160
	v_fmac_f32_e32 v154, v97, v97
	v_fma_f32 v75, v75, v148, -v161
	v_fmac_f32_e32 v154, v75, v75
	v_fma_f32 v73, v76, v148, -v162
	v_fmac_f32_e32 v154, v73, v73
	v_fma_f32 v74, v77, v148, -v163
	ds_read_b128 v[160:163], v149 offset:20480
	v_fmac_f32_e32 v154, v74, v74
	s_waitcnt lgkmcnt(1)
	v_fma_f32 v70, v78, v148, -v156
	v_fmac_f32_e32 v154, v70, v70
	v_fma_f32 v71, v79, v148, -v157
	v_fmac_f32_e32 v154, v71, v71
	v_fma_f32 v72, v80, v148, -v158
	v_fmac_f32_e32 v154, v72, v72
	v_fma_f32 v77, v81, v148, -v159
	ds_read_b128 v[156:159], v149 offset:21504
	v_fmac_f32_e32 v154, v77, v77
	s_waitcnt lgkmcnt(1)
	v_fma_f32 v78, v50, v148, -v160
	v_fmac_f32_e32 v154, v78, v78
	v_fma_f32 v79, v51, v148, -v161
	v_fmac_f32_e32 v154, v79, v79
	v_fma_f32 v76, v52, v148, -v162
	v_fmac_f32_e32 v154, v76, v76
	v_fma_f32 v53, v53, v148, -v163
	ds_read_b128 v[160:163], v149 offset:22528
	v_fmac_f32_e32 v154, v53, v53
	s_waitcnt lgkmcnt(1)
	v_fma_f32 v50, v54, v148, -v156
	v_fmac_f32_e32 v154, v50, v50
	v_fma_f32 v51, v55, v148, -v157
	v_fmac_f32_e32 v154, v51, v51
	v_fma_f32 v52, v56, v148, -v158
	v_fmac_f32_e32 v154, v52, v52
	v_fma_f32 v80, v57, v148, -v159
	ds_read_b128 v[156:159], v149 offset:23552
	v_fmac_f32_e32 v154, v80, v80
	s_waitcnt lgkmcnt(1)
	v_fma_f32 v81, v58, v148, -v160
	v_fmac_f32_e32 v154, v81, v81
	v_fma_f32 v59, v59, v148, -v161
	v_fmac_f32_e32 v154, v59, v59
	v_fma_f32 v57, v60, v148, -v162
	v_fmac_f32_e32 v154, v57, v57
	v_fma_f32 v58, v61, v148, -v163
	ds_read_b128 v[160:163], v149 offset:24576
	v_fmac_f32_e32 v154, v58, v58
	s_waitcnt lgkmcnt(1)
	v_fma_f32 v54, v62, v148, -v156
	v_fmac_f32_e32 v154, v54, v54
	v_fma_f32 v55, v63, v148, -v157
	v_fmac_f32_e32 v154, v55, v55
	v_fma_f32 v56, v64, v148, -v158
	v_fmac_f32_e32 v154, v56, v56
	v_fma_f32 v61, v65, v148, -v159
	ds_read_b128 v[156:159], v149 offset:25600
	v_fmac_f32_e32 v154, v61, v61
	s_waitcnt lgkmcnt(1)
	v_fma_f32 v62, v34, v148, -v160
	v_fmac_f32_e32 v154, v62, v62
	v_fma_f32 v63, v35, v148, -v161
	v_fmac_f32_e32 v154, v63, v63
	v_fma_f32 v60, v36, v148, -v162
	v_fmac_f32_e32 v154, v60, v60
	v_fma_f32 v37, v37, v148, -v163
	ds_read_b128 v[160:163], v149 offset:26624
	v_fmac_f32_e32 v154, v37, v37
	s_waitcnt lgkmcnt(1)
	v_fma_f32 v34, v38, v148, -v156
	v_fmac_f32_e32 v154, v34, v34
	v_fma_f32 v35, v39, v148, -v157
	v_fmac_f32_e32 v154, v35, v35
	v_fma_f32 v36, v40, v148, -v158
	v_fmac_f32_e32 v154, v36, v36
	v_fma_f32 v64, v41, v148, -v159
	ds_read_b128 v[156:159], v149 offset:27648
	v_fmac_f32_e32 v154, v64, v64
	s_waitcnt lgkmcnt(1)
	v_fma_f32 v65, v42, v148, -v160
	v_fmac_f32_e32 v154, v65, v65
	v_fma_f32 v43, v43, v148, -v161
	v_fmac_f32_e32 v154, v43, v43
	v_fma_f32 v41, v44, v148, -v162
	v_fmac_f32_e32 v154, v41, v41
	v_fma_f32 v42, v45, v148, -v163
	ds_read_b128 v[160:163], v149 offset:28672
	v_fmac_f32_e32 v154, v42, v42
	s_waitcnt lgkmcnt(1)
	v_fma_f32 v38, v46, v148, -v156
	v_fmac_f32_e32 v154, v38, v38
	v_fma_f32 v39, v47, v148, -v157
	v_fmac_f32_e32 v154, v39, v39
	v_fma_f32 v40, v48, v148, -v158
	v_fmac_f32_e32 v154, v40, v40
	v_fma_f32 v46, v49, v148, -v159
	ds_read_b128 v[156:159], v149 offset:29696
	v_fmac_f32_e32 v154, v46, v46
	s_waitcnt lgkmcnt(1)
	v_fma_f32 v47, v18, v148, -v160
	v_fmac_f32_e32 v154, v47, v47
	v_fma_f32 v48, v19, v148, -v161
	v_fmac_f32_e32 v154, v48, v48
	v_fma_f32 v44, v20, v148, -v162
	v_fmac_f32_e32 v154, v44, v44
	v_fma_f32 v45, v21, v148, -v163
	ds_read_b128 v[160:163], v149 offset:30720
	v_fmac_f32_e32 v154, v45, v45
	s_waitcnt lgkmcnt(1)
	v_fma_f32 v20, v22, v148, -v156
	v_fmac_f32_e32 v154, v20, v20
	v_fma_f32 v21, v23, v148, -v157
	v_fmac_f32_e32 v154, v21, v21
	v_fma_f32 v22, v24, v148, -v158
	v_fmac_f32_e32 v154, v22, v22
	v_fma_f32 v49, v25, v148, -v159
	ds_read_b128 v[156:159], v149 offset:31744
	v_fmac_f32_e32 v154, v49, v49
	s_waitcnt lgkmcnt(1)
	v_fma_f32 v149, v26, v148, -v160
	v_fmac_f32_e32 v154, v149, v149
	v_fma_f32 v155, v27, v148, -v161
	v_fmac_f32_e32 v154, v155, v155
	v_fma_f32 v26, v28, v148, -v162
	v_fmac_f32_e32 v154, v26, v26
	v_fma_f32 v27, v29, v148, -v163
	v_fmac_f32_e32 v154, v27, v27
	s_waitcnt lgkmcnt(0)
	v_fma_f32 v23, v30, v148, -v156
	v_fmac_f32_e32 v154, v23, v23
	v_fma_f32 v24, v31, v148, -v157
	v_fmac_f32_e32 v154, v24, v24
	v_fma_f32 v25, v32, v148, -v158
	v_fmac_f32_e32 v154, v25, v25
	v_fma_f32 v28, v33, v148, -v159
	v_fmac_f32_e32 v154, v28, v28
	ds_bpermute_b32 v18, v201, v154
	v_ashrrev_i32_e32 v31, 5, v147
	s_waitcnt lgkmcnt(0)
; #define LAS __attribute__((address_space(3)))
; __device__ __forceinline__ unsigned pk2(float lo, float hi) { return pg8::cvt_pk_bf16(lo, hi); }
; __device__ __forceinline__ void attn_block(LAS unsigned char* lds, const Ptrs& P, int b, int h, int qb, float negMb, float lam, int tid, int wid, int lane) {
;     ...
;         ss += __shfl_xor(ss, 32);
;         const float rn = (1.0f / sqrtf(ss * (1.f / VD) + EPS_RMS)) * (1.0f - LAMBDA_INIT);
;         bf16* orow = P.MIX + (tok0 + qpos3) * DM + h * 256 + 8 * hh3;
;         const LAS float* gp = (const LAS float*)(lds + MISC_OFF + 3072) + 4 * hh3;
; #pragma unroll
;         for (int e = 0; e < 8; ++e)
; #pragma unroll
;             for (int i2 = 0; i2 < 2; ++i2) { v2u wab[2];
; #pragma unroll
;                 for (int q = 0; q < 2; ++q) { const int r4 = 2 * i2 + q; const f32x4 g = *(const LAS f32x4*)(gp + 32 * e + 8 * r4);
;                     wab[q].x = pk2(o[e][4 * r4] * rn * g[0], o[e][4 * r4 + 1] * rn * g[1]); wab[q].y = pk2(o[e][4 * r4 + 2] * rn * g[2], o[e][4 * r4 + 3] * rn * g[3]); }
;                 const auto rx = __builtin_amdgcn_permlane32_swap(wab[0].x, wab[1].x, false, false);
;                 const auto ry = __builtin_amdgcn_permlane32_swap(wab[0].y, wab[1].y, false, false);
;                 v4u w16; w16.x = rx[0]; w16.y = ry[0]; w16.z = rx[1]; w16.w = ry[1];
;                 *(v4u*)(orow + 32 * e + 16 * i2) = w16; }
	v_add_f32_e32 v18, v154, v18
	v_fmamk_f32 v18, v18, 0x3b800000, v204
	v_mul_f32_e32 v19, 0x4f800000, v18
	v_cmp_gt_f32_e32 vcc, s76, v18
	s_nop 1
	v_cndmask_b32_e32 v18, v18, v19, vcc
	v_sqrt_f32_e32 v19, v18
	s_nop 0
	v_add_u32_e32 v29, -1, v19
	v_fma_f32 v30, -v29, v19, v18
	v_cmp_ge_f32_e64 s[0:1], 0, v30
	v_add_u32_e32 v30, 1, v19
	s_nop 0
	v_cndmask_b32_e64 v29, v19, v29, s[0:1]
	v_fma_f32 v19, -v30, v19, v18
	v_cmp_lt_f32_e64 s[0:1], 0, v19
	s_nop 1
	v_cndmask_b32_e64 v19, v29, v30, s[0:1]
	v_mul_f32_e32 v29, 0x37800000, v19
	v_cndmask_b32_e32 v19, v19, v29, vcc
	v_cmp_class_f32_e32 vcc, v18, v205
	s_nop 1
	v_cndmask_b32_e32 v18, v19, v18, vcc
	v_div_scale_f32 v19, s[0:1], v18, v18, 1.0
	v_rcp_f32_e32 v29, v19
	s_nop 0
	v_fma_f32 v30, -v19, v29, 1.0
	v_fmac_f32_e32 v29, v30, v29
	v_div_scale_f32 v30, vcc, 1.0, v18, 1.0
	v_mul_f32_e32 v32, v30, v29
	v_fma_f32 v33, -v19, v32, v30
	v_fmac_f32_e32 v32, v33, v29
	v_fma_f32 v19, -v19, v32, v30
	v_div_fmas_f32 v19, v19, v29, v32
	v_div_fixup_f32 v18, v19, v18, 1.0
	v_mul_f32_e32 v29, 0x3f4ccccd, v18
	v_lshl_add_u32 v18, v31, 4, 0
	v_add_u32_e32 v30, 0x20c00, v18
	ds_read_b128 v[156:159], v30
	v_mul_f32_e32 v32, v151, v29
	v_mul_f32_e32 v33, v150, v29
	v_lshl_add_u64 v[18:19], s[20:21], 0, v[194:195]
	v_lshlrev_b64 v[18:19], 12, v[18:19]
	s_waitcnt lgkmcnt(0)
	v_mul_f32_e32 v32, v156, v32
	v_mul_f32_e32 v33, v157, v33
	v_cvt_pk_bf16_f32 v156, v32, v33
	v_mul_f32_e32 v32, v146, v29
	v_mul_f32_e32 v33, v133, v29
	v_mul_f32_e32 v32, v158, v32
	v_mul_f32_e32 v33, v159, v33
	v_cvt_pk_bf16_f32 v157, v32, v33
	ds_read_b128 v[158:161], v30 offset:32
	v_lshlrev_b32_e32 v32, 3, v31
	v_lshl_add_u64 v[18:19], s[22:23], 0, v[18:19]
	v_ashrrev_i32_e32 v33, 31, v32
	v_lshl_add_u64 v[18:19], v[32:33], 1, v[18:19]
	v_mul_f32_e32 v31, v130, v29
	v_mul_f32_e32 v32, v131, v29
	s_waitcnt lgkmcnt(0)
	v_mul_f32_e32 v31, v158, v31
	v_mul_f32_e32 v32, v159, v32
	v_cvt_pk_bf16_f32 v158, v31, v32
	v_mul_f32_e32 v31, v132, v29
	v_mul_f32_e32 v32, v152, v29
	v_mul_f32_e32 v31, v160, v31
	v_mul_f32_e32 v32, v161, v32
	v_cvt_pk_bf16_f32 v159, v31, v32
	v_permlane32_swap_b32_e32 v156, v158
	v_permlane32_swap_b32_e32 v157, v159
	flat_store_dwordx4 v[18:19], v[156:159] sc1
	ds_read_b128 v[130:133], v30 offset:64
	v_mul_f32_e32 v31, v153, v29
	v_mul_f32_e32 v32, v139, v29
	v_mul_f32_e32 v33, v37, v29
	v_mul_f32_e32 v20, v20, v29
	s_waitcnt lgkmcnt(0)
	v_mul_f32_e32 v31, v130, v31
	v_mul_f32_e32 v32, v131, v32
	v_cvt_pk_bf16_f32 v130, v31, v32
	v_mul_f32_e32 v31, v137, v29
	v_mul_f32_e32 v32, v138, v29
	v_mul_f32_e32 v31, v132, v31
	v_mul_f32_e32 v32, v133, v32
	v_cvt_pk_bf16_f32 v131, v31, v32
	ds_read_b128 v[150:153], v30 offset:96
	v_mul_f32_e32 v31, v134, v29
	v_mul_f32_e32 v32, v135, v29
	v_mul_f32_e32 v21, v21, v29
	s_waitcnt lgkmcnt(0)
	v_mul_f32_e32 v31, v150, v31
	v_mul_f32_e32 v32, v151, v32
	v_cvt_pk_bf16_f32 v132, v31, v32
	v_mul_f32_e32 v31, v136, v29
	v_mul_f32_e32 v32, v141, v29
	v_mul_f32_e32 v31, v152, v31
	v_mul_f32_e32 v32, v153, v32
	v_cvt_pk_bf16_f32 v133, v31, v32
	v_permlane32_swap_b32_e32 v130, v132
	v_permlane32_swap_b32_e32 v131, v133
	flat_store_dwordx4 v[18:19], v[130:133] offset:32 sc1
	ds_read_b128 v[130:133], v30 offset:128
	v_mul_f32_e32 v31, v142, v29
	v_mul_f32_e32 v32, v143, v29
	s_waitcnt lgkmcnt(0)
	v_mul_f32_e32 v31, v130, v31
	v_mul_f32_e32 v32, v131, v32
	v_cvt_pk_bf16_f32 v130, v31, v32
	v_mul_f32_e32 v31, v140, v29
	v_mul_f32_e32 v32, v117, v29
	v_mul_f32_e32 v31, v132, v31
	v_mul_f32_e32 v32, v133, v32
	v_cvt_pk_bf16_f32 v131, v31, v32
	ds_read_b128 v[132:135], v30 offset:160
	v_mul_f32_e32 v31, v114, v29
	v_mul_f32_e32 v32, v115, v29
	s_waitcnt lgkmcnt(0)
	v_mul_f32_e32 v31, v132, v31
	v_mul_f32_e32 v32, v133, v32
	v_cvt_pk_bf16_f32 v132, v31, v32
	v_mul_f32_e32 v31, v116, v29
	v_mul_f32_e32 v32, v144, v29
	v_mul_f32_e32 v31, v134, v31
	v_mul_f32_e32 v32, v135, v32
	v_cvt_pk_bf16_f32 v133, v31, v32
	v_permlane32_swap_b32_e32 v130, v132
	v_permlane32_swap_b32_e32 v131, v133
	flat_store_dwordx4 v[18:19], v[130:133] offset:64 sc1
	ds_read_b128 v[114:117], v30 offset:192
	v_mul_f32_e32 v31, v145, v29
	v_mul_f32_e32 v32, v123, v29
	s_waitcnt lgkmcnt(0)
	v_mul_f32_e32 v31, v114, v31
	v_mul_f32_e32 v32, v115, v32
	v_cvt_pk_bf16_f32 v114, v31, v32
	v_mul_f32_e32 v31, v121, v29
	v_mul_f32_e32 v32, v122, v29
	v_mul_f32_e32 v31, v116, v31
	v_mul_f32_e32 v32, v117, v32
	v_cvt_pk_bf16_f32 v115, v31, v32
	ds_read_b128 v[130:133], v30 offset:224
	v_mul_f32_e32 v31, v118, v29
	v_mul_f32_e32 v32, v119, v29
	s_waitcnt lgkmcnt(0)
	v_mul_f32_e32 v31, v130, v31
	v_mul_f32_e32 v32, v131, v32
	v_cvt_pk_bf16_f32 v116, v31, v32
	v_mul_f32_e32 v31, v120, v29
	v_mul_f32_e32 v32, v125, v29
	v_mul_f32_e32 v31, v132, v31
	v_mul_f32_e32 v32, v133, v32
	v_cvt_pk_bf16_f32 v117, v31, v32
	v_permlane32_swap_b32_e32 v114, v116
	v_permlane32_swap_b32_e32 v115, v117
	flat_store_dwordx4 v[18:19], v[114:117] offset:96 sc1
	ds_read_b128 v[114:117], v30 offset:256
	v_mul_f32_e32 v31, v126, v29
	v_mul_f32_e32 v32, v127, v29
	s_waitcnt lgkmcnt(0)
	v_mul_f32_e32 v31, v114, v31
	v_mul_f32_e32 v32, v115, v32
	v_cvt_pk_bf16_f32 v114, v31, v32
	v_mul_f32_e32 v31, v124, v29
	v_mul_f32_e32 v32, v101, v29
	v_mul_f32_e32 v31, v116, v31
	v_mul_f32_e32 v32, v117, v32
	v_cvt_pk_bf16_f32 v115, v31, v32
	ds_read_b128 v[116:119], v30 offset:288
	v_mul_f32_e32 v31, v98, v29
	v_mul_f32_e32 v32, v99, v29
	s_waitcnt lgkmcnt(0)
; #define LAS __attribute__((address_space(3)))
; __device__ __forceinline__ unsigned pk2(float lo, float hi) { return pg8::cvt_pk_bf16(lo, hi); }
; __device__ __forceinline__ void attn_block(LAS unsigned char* lds, const Ptrs& P, int b, int h, int qb, float negMb, float lam, int tid, int wid, int lane) {
;     ...
;         for (int e = 0; e < 8; ++e)
; #pragma unroll
;             for (int i2 = 0; i2 < 2; ++i2) { v2u wab[2];
; #pragma unroll
;                 for (int q = 0; q < 2; ++q) { const int r4 = 2 * i2 + q; const f32x4 g = *(const LAS f32x4*)(gp + 32 * e + 8 * r4);
;                     wab[q].x = pk2(o[e][4 * r4] * rn * g[0], o[e][4 * r4 + 1] * rn * g[1]); wab[q].y = pk2(o[e][4 * r4 + 2] * rn * g[2], o[e][4 * r4 + 3] * rn * g[3]); }
;                 const auto rx = __builtin_amdgcn_permlane32_swap(wab[0].x, wab[1].x, false, false);
;                 const auto ry = __builtin_amdgcn_permlane32_swap(wab[0].y, wab[1].y, false, false);
;                 v4u w16; w16.x = rx[0]; w16.y = ry[0]; w16.z = rx[1]; w16.w = ry[1];
;                 *(v4u*)(orow + 32 * e + 16 * i2) = w16; }
	v_mul_f32_e32 v31, v116, v31
	v_mul_f32_e32 v32, v117, v32
	v_cvt_pk_bf16_f32 v116, v31, v32
	v_mul_f32_e32 v31, v100, v29
	v_mul_f32_e32 v32, v128, v29
	v_mul_f32_e32 v31, v118, v31
	v_mul_f32_e32 v32, v119, v32
	v_cvt_pk_bf16_f32 v117, v31, v32
	v_permlane32_swap_b32_e32 v114, v116
	v_permlane32_swap_b32_e32 v115, v117
	flat_store_dwordx4 v[18:19], v[114:117] offset:128 sc1
	ds_read_b128 v[98:101], v30 offset:320
	v_mul_f32_e32 v31, v129, v29
	v_mul_f32_e32 v32, v107, v29
	s_waitcnt lgkmcnt(0)
	v_mul_f32_e32 v31, v98, v31
	v_mul_f32_e32 v32, v99, v32
	v_cvt_pk_bf16_f32 v98, v31, v32
	v_mul_f32_e32 v31, v105, v29
	v_mul_f32_e32 v32, v106, v29
	v_mul_f32_e32 v31, v100, v31
	v_mul_f32_e32 v32, v101, v32
	v_cvt_pk_bf16_f32 v99, v31, v32
	ds_read_b128 v[114:117], v30 offset:352
	v_mul_f32_e32 v31, v102, v29
	v_mul_f32_e32 v32, v103, v29
	s_waitcnt lgkmcnt(0)
	v_mul_f32_e32 v31, v114, v31
	v_mul_f32_e32 v32, v115, v32
	v_cvt_pk_bf16_f32 v100, v31, v32
	v_mul_f32_e32 v31, v104, v29
	v_mul_f32_e32 v32, v109, v29
	v_mul_f32_e32 v31, v116, v31
	v_mul_f32_e32 v32, v117, v32
	v_cvt_pk_bf16_f32 v101, v31, v32
	v_permlane32_swap_b32_e32 v98, v100
	v_permlane32_swap_b32_e32 v99, v101
	flat_store_dwordx4 v[18:19], v[98:101] offset:160 sc1
	ds_read_b128 v[98:101], v30 offset:384
	v_mul_f32_e32 v31, v110, v29
	v_mul_f32_e32 v32, v111, v29
	s_waitcnt lgkmcnt(0)
	v_mul_f32_e32 v31, v98, v31
	v_mul_f32_e32 v32, v99, v32
	v_cvt_pk_bf16_f32 v98, v31, v32
	v_mul_f32_e32 v31, v108, v29
	v_mul_f32_e32 v32, v85, v29
	v_mul_f32_e32 v31, v100, v31
	v_mul_f32_e32 v32, v101, v32
	v_cvt_pk_bf16_f32 v99, v31, v32
	ds_read_b128 v[100:103], v30 offset:416
	v_mul_f32_e32 v31, v82, v29
	v_mul_f32_e32 v32, v83, v29
	s_waitcnt lgkmcnt(0)
	v_mul_f32_e32 v31, v100, v31
	v_mul_f32_e32 v32, v101, v32
	v_cvt_pk_bf16_f32 v100, v31, v32
	v_mul_f32_e32 v31, v84, v29
	v_mul_f32_e32 v32, v112, v29
	v_mul_f32_e32 v31, v102, v31
	v_mul_f32_e32 v32, v103, v32
	v_cvt_pk_bf16_f32 v101, v31, v32
	v_permlane32_swap_b32_e32 v98, v100
	v_permlane32_swap_b32_e32 v99, v101
	flat_store_dwordx4 v[18:19], v[98:101] offset:192 sc1
	ds_read_b128 v[82:85], v30 offset:448
	v_mul_f32_e32 v31, v113, v29
	v_mul_f32_e32 v32, v91, v29
	s_waitcnt lgkmcnt(0)
	v_mul_f32_e32 v31, v82, v31
	v_mul_f32_e32 v32, v83, v32
	v_cvt_pk_bf16_f32 v82, v31, v32
	v_mul_f32_e32 v31, v89, v29
	v_mul_f32_e32 v32, v90, v29
	v_mul_f32_e32 v31, v84, v31
	v_mul_f32_e32 v32, v85, v32
	v_cvt_pk_bf16_f32 v83, v31, v32
	ds_read_b128 v[98:101], v30 offset:480
	v_mul_f32_e32 v31, v86, v29
	v_mul_f32_e32 v32, v87, v29
	s_waitcnt lgkmcnt(0)
	v_mul_f32_e32 v31, v98, v31
	v_mul_f32_e32 v32, v99, v32
	v_cvt_pk_bf16_f32 v84, v31, v32
	v_mul_f32_e32 v31, v88, v29
	v_mul_f32_e32 v32, v93, v29
	v_mul_f32_e32 v31, v100, v31
	v_mul_f32_e32 v32, v101, v32
	v_cvt_pk_bf16_f32 v85, v31, v32
	v_permlane32_swap_b32_e32 v82, v84
	v_permlane32_swap_b32_e32 v83, v85
	flat_store_dwordx4 v[18:19], v[82:85] offset:224 sc1
	ds_read_b128 v[82:85], v30 offset:512
	v_mul_f32_e32 v31, v94, v29
	v_mul_f32_e32 v32, v95, v29
	s_waitcnt lgkmcnt(0)
	v_mul_f32_e32 v31, v82, v31
	v_mul_f32_e32 v32, v83, v32
	v_cvt_pk_bf16_f32 v82, v31, v32
	v_mul_f32_e32 v31, v92, v29
	v_mul_f32_e32 v32, v69, v29
	v_mul_f32_e32 v31, v84, v31
	v_mul_f32_e32 v32, v85, v32
	v_cvt_pk_bf16_f32 v83, v31, v32
	ds_read_b128 v[84:87], v30 offset:544
	v_mul_f32_e32 v31, v66, v29
	v_mul_f32_e32 v32, v67, v29
	s_waitcnt lgkmcnt(0)
	v_mul_f32_e32 v31, v84, v31
	v_mul_f32_e32 v32, v85, v32
	v_cvt_pk_bf16_f32 v84, v31, v32
	v_mul_f32_e32 v31, v68, v29
	v_mul_f32_e32 v32, v96, v29
	v_mul_f32_e32 v31, v86, v31
	v_mul_f32_e32 v32, v87, v32
	v_cvt_pk_bf16_f32 v85, v31, v32
	v_permlane32_swap_b32_e32 v82, v84
	v_permlane32_swap_b32_e32 v83, v85
	flat_store_dwordx4 v[18:19], v[82:85] offset:256 sc1
	ds_read_b128 v[66:69], v30 offset:576
	v_mul_f32_e32 v31, v97, v29
	v_mul_f32_e32 v32, v75, v29
	s_waitcnt lgkmcnt(0)
	v_mul_f32_e32 v31, v66, v31
	v_mul_f32_e32 v32, v67, v32
	v_cvt_pk_bf16_f32 v66, v31, v32
	v_mul_f32_e32 v31, v73, v29
	v_mul_f32_e32 v32, v74, v29
	v_mul_f32_e32 v31, v68, v31
	v_mul_f32_e32 v32, v69, v32
	v_cvt_pk_bf16_f32 v67, v31, v32
	ds_read_b128 v[82:85], v30 offset:608
	v_mul_f32_e32 v31, v70, v29
	v_mul_f32_e32 v32, v71, v29
	s_waitcnt lgkmcnt(0)
	v_mul_f32_e32 v31, v82, v31
	v_mul_f32_e32 v32, v83, v32
	v_cvt_pk_bf16_f32 v68, v31, v32
	v_mul_f32_e32 v31, v72, v29
	v_mul_f32_e32 v32, v77, v29
	v_mul_f32_e32 v31, v84, v31
	v_mul_f32_e32 v32, v85, v32
	v_cvt_pk_bf16_f32 v69, v31, v32
	v_permlane32_swap_b32_e32 v66, v68
	v_permlane32_swap_b32_e32 v67, v69
	flat_store_dwordx4 v[18:19], v[66:69] offset:288 sc1
	ds_read_b128 v[66:69], v30 offset:640
	v_mul_f32_e32 v31, v78, v29
	v_mul_f32_e32 v32, v79, v29
	s_waitcnt lgkmcnt(0)
; #define LAS __attribute__((address_space(3)))
; __device__ __forceinline__ unsigned pk2(float lo, float hi) { return pg8::cvt_pk_bf16(lo, hi); }
; __device__ __forceinline__ void attn_block(LAS unsigned char* lds, const Ptrs& P, int b, int h, int qb, float negMb, float lam, int tid, int wid, int lane) {
;     ...
;         for (int e = 0; e < 8; ++e)
; #pragma unroll
;             for (int i2 = 0; i2 < 2; ++i2) { v2u wab[2];
; #pragma unroll
;                 for (int q = 0; q < 2; ++q) { const int r4 = 2 * i2 + q; const f32x4 g = *(const LAS f32x4*)(gp + 32 * e + 8 * r4);
;                     wab[q].x = pk2(o[e][4 * r4] * rn * g[0], o[e][4 * r4 + 1] * rn * g[1]); wab[q].y = pk2(o[e][4 * r4 + 2] * rn * g[2], o[e][4 * r4 + 3] * rn * g[3]); }
;                 const auto rx = __builtin_amdgcn_permlane32_swap(wab[0].x, wab[1].x, false, false);
;                 const auto ry = __builtin_amdgcn_permlane32_swap(wab[0].y, wab[1].y, false, false);
;                 v4u w16; w16.x = rx[0]; w16.y = ry[0]; w16.z = rx[1]; w16.w = ry[1];
;                 *(v4u*)(orow + 32 * e + 16 * i2) = w16; }
	v_mul_f32_e32 v31, v66, v31
	v_mul_f32_e32 v32, v67, v32
	v_cvt_pk_bf16_f32 v66, v31, v32
	v_mul_f32_e32 v31, v76, v29
	v_mul_f32_e32 v32, v53, v29
	v_mul_f32_e32 v31, v68, v31
	v_mul_f32_e32 v32, v69, v32
	v_cvt_pk_bf16_f32 v67, v31, v32
	ds_read_b128 v[68:71], v30 offset:672
	v_mul_f32_e32 v31, v50, v29
	v_mul_f32_e32 v32, v51, v29
	s_waitcnt lgkmcnt(0)
	v_mul_f32_e32 v31, v68, v31
	v_mul_f32_e32 v32, v69, v32
	v_cvt_pk_bf16_f32 v68, v31, v32
	v_mul_f32_e32 v31, v52, v29
	v_mul_f32_e32 v32, v80, v29
	v_mul_f32_e32 v31, v70, v31
	v_mul_f32_e32 v32, v71, v32
	v_cvt_pk_bf16_f32 v69, v31, v32
	v_permlane32_swap_b32_e32 v66, v68
	v_permlane32_swap_b32_e32 v67, v69
	flat_store_dwordx4 v[18:19], v[66:69] offset:320 sc1
	ds_read_b128 v[50:53], v30 offset:704
	v_mul_f32_e32 v31, v81, v29
	v_mul_f32_e32 v32, v59, v29
	s_waitcnt lgkmcnt(0)
	v_mul_f32_e32 v31, v50, v31
	v_mul_f32_e32 v32, v51, v32
	v_cvt_pk_bf16_f32 v50, v31, v32
	v_mul_f32_e32 v31, v57, v29
	v_mul_f32_e32 v32, v58, v29
	v_mul_f32_e32 v31, v52, v31
	v_mul_f32_e32 v32, v53, v32
	v_cvt_pk_bf16_f32 v51, v31, v32
	ds_read_b128 v[66:69], v30 offset:736
	v_mul_f32_e32 v31, v54, v29
	v_mul_f32_e32 v32, v55, v29
	s_waitcnt lgkmcnt(0)
	v_mul_f32_e32 v31, v66, v31
	v_mul_f32_e32 v32, v67, v32
	v_cvt_pk_bf16_f32 v52, v31, v32
	v_mul_f32_e32 v31, v56, v29
	v_mul_f32_e32 v32, v61, v29
	v_mul_f32_e32 v31, v68, v31
	v_mul_f32_e32 v32, v69, v32
	v_cvt_pk_bf16_f32 v53, v31, v32
	v_permlane32_swap_b32_e32 v50, v52
	v_permlane32_swap_b32_e32 v51, v53
	flat_store_dwordx4 v[18:19], v[50:53] offset:352 sc1
	ds_read_b128 v[50:53], v30 offset:768
	v_mul_f32_e32 v31, v62, v29
	v_mul_f32_e32 v32, v63, v29
	s_waitcnt lgkmcnt(0)
	v_mul_f32_e32 v31, v31, v50
	v_mul_f32_e32 v32, v32, v51
	v_cvt_pk_bf16_f32 v32, v31, v32
	v_mul_f32_e32 v31, v60, v29
	v_mul_f32_e32 v33, v33, v53
	v_mul_f32_e32 v31, v31, v52
	v_cvt_pk_bf16_f32 v33, v31, v33
	ds_read_b128 v[50:53], v30 offset:800
	v_mul_f32_e32 v31, v34, v29
	v_mul_f32_e32 v34, v35, v29
	v_mul_f32_e32 v35, v64, v29
	s_waitcnt lgkmcnt(0)
	v_mul_f32_e32 v31, v31, v50
	v_mul_f32_e32 v34, v34, v51
	v_cvt_pk_bf16_f32 v34, v31, v34
	v_mul_f32_e32 v31, v36, v29
	v_mul_f32_e32 v35, v35, v53
	v_mul_f32_e32 v31, v31, v52
	v_cvt_pk_bf16_f32 v35, v31, v35
	v_permlane32_swap_b32_e32 v32, v34
	v_permlane32_swap_b32_e32 v33, v35
	flat_store_dwordx4 v[18:19], v[32:35] offset:384 sc1
	ds_read_b128 v[32:35], v30 offset:832
	v_mul_f32_e32 v31, v65, v29
	s_waitcnt lgkmcnt(0)
	v_mul_f32_e32 v31, v31, v32
	v_mul_f32_e32 v32, v43, v29
	v_mul_f32_e32 v32, v32, v33
	v_mul_f32_e32 v33, v42, v29
	v_cvt_pk_bf16_f32 v32, v31, v32
	v_mul_f32_e32 v31, v41, v29
	v_mul_f32_e32 v33, v33, v35
	v_mul_f32_e32 v31, v31, v34
	v_cvt_pk_bf16_f32 v33, v31, v33
	ds_read_b128 v[34:37], v30 offset:864
	v_mul_f32_e32 v31, v38, v29
	s_waitcnt lgkmcnt(0)
	v_mul_f32_e32 v31, v31, v34
	v_mul_f32_e32 v34, v39, v29
	v_mul_f32_e32 v34, v34, v35
	v_mul_f32_e32 v35, v46, v29
	v_cvt_pk_bf16_f32 v34, v31, v34
	v_mul_f32_e32 v31, v40, v29
	v_mul_f32_e32 v35, v35, v37
	v_mul_f32_e32 v31, v31, v36
	v_cvt_pk_bf16_f32 v35, v31, v35
	v_permlane32_swap_b32_e32 v32, v34
	v_permlane32_swap_b32_e32 v33, v35
	flat_store_dwordx4 v[18:19], v[32:35] offset:416 sc1
	ds_read_b128 v[32:35], v30 offset:896
	v_mul_f32_e32 v31, v47, v29
	s_waitcnt lgkmcnt(0)
	v_mul_f32_e32 v31, v31, v32
	v_mul_f32_e32 v32, v48, v29
	v_mul_f32_e32 v32, v32, v33
	v_mul_f32_e32 v33, v45, v29
	v_cvt_pk_bf16_f32 v32, v31, v32
	v_mul_f32_e32 v31, v44, v29
	v_mul_f32_e32 v33, v33, v35
	v_mul_f32_e32 v31, v31, v34
	v_cvt_pk_bf16_f32 v33, v31, v33
	ds_read_b128 v[34:37], v30 offset:928
	s_waitcnt lgkmcnt(0)
	v_mul_f32_e32 v20, v20, v34
	v_mul_f32_e32 v21, v21, v35
	v_cvt_pk_bf16_f32 v34, v20, v21
	v_mul_f32_e32 v20, v22, v29
	v_mul_f32_e32 v21, v49, v29
	v_mul_f32_e32 v20, v20, v36
	v_mul_f32_e32 v21, v21, v37
	v_cvt_pk_bf16_f32 v35, v20, v21
	v_permlane32_swap_b32_e32 v32, v34
	v_permlane32_swap_b32_e32 v33, v35
	flat_store_dwordx4 v[18:19], v[32:35] offset:448 sc1
	ds_read_b128 v[32:35], v30 offset:960
	v_mul_f32_e32 v20, v149, v29
	v_mul_f32_e32 v21, v155, v29
	v_mul_f32_e32 v22, v27, v29
	s_waitcnt lgkmcnt(0)
	v_mul_f32_e32 v20, v20, v32
	v_mul_f32_e32 v21, v21, v33
	v_cvt_pk_bf16_f32 v20, v20, v21
	v_mul_f32_e32 v21, v26, v29
	v_mul_f32_e32 v21, v21, v34
	v_mul_f32_e32 v22, v22, v35
	v_cvt_pk_bf16_f32 v21, v21, v22
	ds_read_b128 v[30:33], v30 offset:992
	v_mul_f32_e32 v22, v23, v29
	v_mul_f32_e32 v23, v24, v29
	v_mul_f32_e32 v24, v28, v29
	s_waitcnt lgkmcnt(0)
	v_mul_f32_e32 v22, v22, v30
	v_mul_f32_e32 v23, v23, v31
	v_cvt_pk_bf16_f32 v22, v22, v23
	v_mul_f32_e32 v23, v25, v29
	v_mul_f32_e32 v23, v23, v32
	v_mul_f32_e32 v24, v24, v33
	v_cvt_pk_bf16_f32 v23, v23, v24
	v_permlane32_swap_b32_e32 v20, v22
	v_permlane32_swap_b32_e32 v21, v23
	flat_store_dwordx4 v[18:19], v[20:23] offset:480 sc1
	s_branch .LBB0_412

; __device__ __forceinline__ u32x4 pack8(const f32x4 v0, const f32x4 v1) { u32x4 w; w.x = cvt_pk_bf16(v0[0], v0[1]); w.y = cvt_pk_bf16(v0[2], v0[3]); w.z = cvt_pk_bf16(v1[0], v1[1]); w.w = cvt_pk_bf16(v1[2], v1[3]); return w; }
;     __device__ __forceinline__ void operator()(const f32x4 (&acc)[2][2][4][2], const Unit& u, int wr, int wc, int fr, int fq) const {
;     ...
;         for (int ai = 0; ai < 2; ++ai)
; #pragma unroll
;             for (int m = 0; m < 4; ++m) { const int row = row0 + ai * HALF + m * 16; const size_t off = (size_t)row * ldc + col0; float ss = 0.f;
; #pragma unroll
;                 for (int bj = 0; bj < 2; ++bj) { const u32x4 w = *(const u32x4*)(hb + off + bj * HALF);
;                     const f32x4 x0 = {__builtin_bit_cast(float, w.x << 16), __builtin_bit_cast(float, w.x & 0xffff0000u), __builtin_bit_cast(float, w.y << 16), __builtin_bit_cast(float, w.y & 0xffff0000u)};
;                     const f32x4 x1 = {__builtin_bit_cast(float, w.z << 16), __builtin_bit_cast(float, w.z & 0xffff0000u), __builtin_bit_cast(float, w.w << 16), __builtin_bit_cast(float, w.w & 0xffff0000u)};
;                     const f32x4 h0 = x0 + acc[ai][bj][m][0], h1 = x1 + acc[ai][bj][m][1];
;                     ss += ((h0[0] * h0[0] + h0[1] * h0[1]) + (h0[2] * h0[2] + h0[3] * h0[3])) + ((h1[0] * h1[0] + h1[1] * h1[1]) + (h1[2] * h1[2] + h1[3] * h1[3]));
;                     *(u32x4*)(hb + off + bj * HALF) = pack8(h0, h1); }
;                 ss += __shfl_xor(ss, 16); ss += __shfl_xor(ss, 32);
;                 if (fq == 0) red[(ai * HALF + wr * 64 + m * 16 + fr) * 4 + wc] = ss; }
.LBB0_520:
	s_lshl_b32 s13, s48, 8
	v_add_u32_e32 v148, s13, v151
	v_ashrrev_i32_e32 v149, 31, v148
	v_lshl_or_b32 v146, s12, 8, v153
	v_lshlrev_b64 v[160:161], 12, v[148:149]
	v_ashrrev_i32_e32 v147, 31, v146
	v_lshl_add_u64 v[160:161], s[18:19], 0, v[160:161]
	v_lshl_add_u64 v[164:165], v[146:147], 1, v[160:161]
	flat_load_dwordx4 v[160:163], v[164:165]
	v_xor_b32_e32 v159, 32, v158
	s_waitcnt vmcnt(0) lgkmcnt(0)
	v_lshlrev_b32_e32 v166, 16, v160
	v_and_b32_e32 v167, 0xffff0000, v160
	v_lshlrev_b32_e32 v160, 16, v161
	v_and_b32_e32 v161, 0xffff0000, v161
	v_lshlrev_b32_e32 v168, 16, v162
	v_and_b32_e32 v169, 0xffff0000, v162
	v_lshlrev_b32_e32 v162, 16, v163
	v_and_b32_e32 v163, 0xffff0000, v163
	v_pk_add_f32 v[128:129], v[128:129], v[160:161]
	v_pk_add_f32 v[166:167], v[126:127], v[166:167]
	v_pk_add_f32 v[170:171], v[124:125], v[162:163]
	v_pk_add_f32 v[168:169], v[122:123], v[168:169]
	v_cvt_pk_bf16_f32 v124, v166, v167
	v_cvt_pk_bf16_f32 v125, v128, v129
	v_mul_f32_e32 v167, v167, v167
	v_cvt_pk_bf16_f32 v126, v168, v169
	v_cvt_pk_bf16_f32 v127, v170, v171
	flat_load_dwordx4 v[160:163], v[164:165] offset:256
	v_mul_f32_e32 v129, v129, v129
	v_mul_f32_e32 v169, v169, v169
	v_mul_f32_e32 v171, v171, v171
	v_fmac_f32_e32 v167, v166, v166
	v_fmac_f32_e32 v129, v128, v128
	v_fmac_f32_e32 v169, v168, v168
	v_fmac_f32_e32 v171, v170, v170
	v_add_f32_e32 v128, v167, v129
	v_add_f32_e32 v129, v169, v171
	v_add_f32_e32 v168, v128, v129
	v_and_b32_e32 v123, 64, v158
	v_xor_b32_e32 v122, 16, v158
	v_add_u32_e32 v123, 64, v123
	v_cmp_lt_i32_e32 vcc, v122, v123
	flat_store_dwordx4 v[164:165], v[124:127] sc1
	s_waitcnt vmcnt(0) lgkmcnt(0)
	v_lshlrev_b32_e32 v128, 16, v160
	v_and_b32_e32 v129, 0xffff0000, v160
	v_lshlrev_b32_e32 v160, 16, v161
	v_and_b32_e32 v161, 0xffff0000, v161
	v_lshlrev_b32_e32 v166, 16, v162
	v_and_b32_e32 v167, 0xffff0000, v162
	v_lshlrev_b32_e32 v162, 16, v163
	v_and_b32_e32 v163, 0xffff0000, v163
	v_pk_add_f32 v[120:121], v[120:121], v[160:161]
	v_pk_add_f32 v[118:119], v[118:119], v[128:129]
	v_pk_add_f32 v[128:129], v[116:117], v[162:163]
	v_pk_add_f32 v[160:161], v[114:115], v[166:167]
	v_mul_f32_e32 v114, v119, v119
	v_mul_f32_e32 v115, v121, v121
	v_mul_f32_e32 v116, v161, v161
	v_mul_f32_e32 v117, v129, v129
	v_fmac_f32_e32 v114, v118, v118
	v_fmac_f32_e32 v115, v120, v120
	v_fmac_f32_e32 v116, v160, v160
	v_fmac_f32_e32 v117, v128, v128
	v_add_f32_e32 v114, v114, v115
	v_add_f32_e32 v115, v116, v117
	v_cndmask_b32_e32 v122, v158, v122, vcc
	v_add_f32_e32 v114, v114, v115
	v_lshlrev_b32_e32 v122, 2, v122
	v_add_f32_e32 v114, v168, v114
	ds_bpermute_b32 v115, v122, v114
	v_cmp_lt_i32_e32 vcc, v159, v123
	v_cvt_pk_bf16_f32 v118, v118, v119
	v_cvt_pk_bf16_f32 v119, v120, v121
	v_cvt_pk_bf16_f32 v120, v160, v161
	s_waitcnt lgkmcnt(0)
	v_add_f32_e32 v115, v114, v115
	v_cvt_pk_bf16_f32 v121, v128, v129
	v_cndmask_b32_e32 v116, v158, v159, vcc
	v_lshlrev_b32_e32 v114, 2, v116
	ds_bpermute_b32 v116, v114, v115
	flat_store_dwordx4 v[164:165], v[118:121] offset:256 sc1
	s_and_saveexec_b64 s[48:49], s[2:3]
	s_cbranch_execz .LBB0_522
	s_waitcnt lgkmcnt(0)
	v_add_f32_e32 v115, v115, v116
	ds_write_b32 v154, v115
.LBB0_522:
	s_or_b64 exec, exec, s[48:49]
	s_waitcnt lgkmcnt(0)
	v_or_b32_e32 v116, 16, v148
	v_ashrrev_i32_e32 v117, 31, v116
	v_lshlrev_b64 v[116:117], 12, v[116:117]
	v_lshl_add_u64 v[116:117], s[18:19], 0, v[116:117]
	v_lshl_add_u64 v[120:121], v[146:147], 1, v[116:117]
	flat_load_dwordx4 v[116:119], v[120:121]
	s_waitcnt vmcnt(0) lgkmcnt(0)
	v_lshlrev_b32_e32 v124, 16, v116
	v_and_b32_e32 v125, 0xffff0000, v116
	v_lshlrev_b32_e32 v116, 16, v117
	v_and_b32_e32 v117, 0xffff0000, v117
	v_lshlrev_b32_e32 v126, 16, v118
	v_and_b32_e32 v127, 0xffff0000, v118
	v_lshlrev_b32_e32 v118, 16, v119
	v_and_b32_e32 v119, 0xffff0000, v119
	v_pk_add_f32 v[116:117], v[112:113], v[116:117]
	v_pk_add_f32 v[124:125], v[110:111], v[124:125]
	v_pk_add_f32 v[118:119], v[108:109], v[118:119]
	v_pk_add_f32 v[126:127], v[106:107], v[126:127]
	v_cvt_pk_bf16_f32 v106, v124, v125
	v_cvt_pk_bf16_f32 v107, v116, v117
	v_mul_f32_e32 v115, v125, v125
	v_cvt_pk_bf16_f32 v108, v126, v127
	v_cvt_pk_bf16_f32 v109, v118, v119
	flat_load_dwordx4 v[110:113], v[120:121] offset:256
	v_mul_f32_e32 v117, v117, v117
	v_mul_f32_e32 v123, v127, v127
	v_mul_f32_e32 v119, v119, v119
	v_fmac_f32_e32 v115, v124, v124
	v_fmac_f32_e32 v117, v116, v116
	v_fmac_f32_e32 v123, v126, v126
	v_fmac_f32_e32 v119, v118, v118
	v_add_f32_e32 v115, v115, v117
	v_add_f32_e32 v116, v123, v119
	v_add_f32_e32 v115, v115, v116
	flat_store_dwordx4 v[120:121], v[106:109] sc1
	s_waitcnt vmcnt(0) lgkmcnt(0)
	v_lshlrev_b32_e32 v116, 16, v110
	v_and_b32_e32 v117, 0xffff0000, v110
	v_lshlrev_b32_e32 v110, 16, v111
	v_and_b32_e32 v111, 0xffff0000, v111
	v_lshlrev_b32_e32 v118, 16, v112
	v_and_b32_e32 v119, 0xffff0000, v112
	v_lshlrev_b32_e32 v112, 16, v113
	v_and_b32_e32 v113, 0xffff0000, v113
	v_pk_add_f32 v[104:105], v[104:105], v[110:111]
	v_pk_add_f32 v[102:103], v[102:103], v[116:117]
	v_pk_add_f32 v[110:111], v[100:101], v[112:113]
	v_pk_add_f32 v[112:113], v[98:99], v[118:119]
	v_mul_f32_e32 v98, v103, v103
	v_mul_f32_e32 v99, v105, v105
	v_mul_f32_e32 v100, v113, v113
	v_mul_f32_e32 v101, v111, v111
	v_fmac_f32_e32 v98, v102, v102
	v_fmac_f32_e32 v99, v104, v104
	v_fmac_f32_e32 v100, v112, v112
	v_fmac_f32_e32 v101, v110, v110
	v_add_f32_e32 v98, v98, v99
	v_add_f32_e32 v99, v100, v101
	v_add_f32_e32 v98, v98, v99
	v_add_f32_e32 v98, v115, v98
	ds_bpermute_b32 v99, v122, v98
	v_cvt_pk_bf16_f32 v100, v102, v103
	v_cvt_pk_bf16_f32 v101, v104, v105
	v_cvt_pk_bf16_f32 v102, v112, v113
	v_cvt_pk_bf16_f32 v103, v110, v111
	s_waitcnt lgkmcnt(0)
	v_add_f32_e32 v98, v98, v99
	ds_bpermute_b32 v99, v114, v98
	flat_store_dwordx4 v[120:121], v[100:103] offset:256 sc1
	s_and_saveexec_b64 s[48:49], s[2:3]
	s_cbranch_execz .LBB0_524
	s_waitcnt lgkmcnt(0)
	v_add_f32_e32 v98, v98, v99
	ds_write_b32 v154, v98 offset:256
; __device__ __forceinline__ u32x4 pack8(const f32x4 v0, const f32x4 v1) { u32x4 w; w.x = cvt_pk_bf16(v0[0], v0[1]); w.y = cvt_pk_bf16(v0[2], v0[3]); w.z = cvt_pk_bf16(v1[0], v1[1]); w.w = cvt_pk_bf16(v1[2], v1[3]); return w; }
;     __device__ __forceinline__ void operator()(const f32x4 (&acc)[2][2][4][2], const Unit& u, int wr, int wc, int fr, int fq) const {
;     ...
;         for (int ai = 0; ai < 2; ++ai)
; #pragma unroll
;             for (int m = 0; m < 4; ++m) { const int row = row0 + ai * HALF + m * 16; const size_t off = (size_t)row * ldc + col0; float ss = 0.f;
; #pragma unroll
;                 for (int bj = 0; bj < 2; ++bj) { const u32x4 w = *(const u32x4*)(hb + off + bj * HALF);
;                     const f32x4 x0 = {__builtin_bit_cast(float, w.x << 16), __builtin_bit_cast(float, w.x & 0xffff0000u), __builtin_bit_cast(float, w.y << 16), __builtin_bit_cast(float, w.y & 0xffff0000u)};
;                     const f32x4 x1 = {__builtin_bit_cast(float, w.z << 16), __builtin_bit_cast(float, w.z & 0xffff0000u), __builtin_bit_cast(float, w.w << 16), __builtin_bit_cast(float, w.w & 0xffff0000u)};
;                     const f32x4 h0 = x0 + acc[ai][bj][m][0], h1 = x1 + acc[ai][bj][m][1];
;                     ss += ((h0[0] * h0[0] + h0[1] * h0[1]) + (h0[2] * h0[2] + h0[3] * h0[3])) + ((h1[0] * h1[0] + h1[1] * h1[1]) + (h1[2] * h1[2] + h1[3] * h1[3]));
;                     *(u32x4*)(hb + off + bj * HALF) = pack8(h0, h1); }
;                 ss += __shfl_xor(ss, 16); ss += __shfl_xor(ss, 32);
;                 if (fq == 0) red[(ai * HALF + wr * 64 + m * 16 + fr) * 4 + wc] = ss; }
.LBB0_524:
	s_or_b64 exec, exec, s[48:49]
	v_or_b32_e32 v98, 32, v148
	s_waitcnt lgkmcnt(0)
	v_ashrrev_i32_e32 v99, 31, v98
	v_lshlrev_b64 v[98:99], 12, v[98:99]
	v_lshl_add_u64 v[98:99], s[18:19], 0, v[98:99]
	v_lshl_add_u64 v[102:103], v[146:147], 1, v[98:99]
	flat_load_dwordx4 v[98:101], v[102:103]
	s_waitcnt vmcnt(0) lgkmcnt(0)
	v_lshlrev_b32_e32 v104, 16, v98
	v_and_b32_e32 v105, 0xffff0000, v98
	v_lshlrev_b32_e32 v98, 16, v99
	v_and_b32_e32 v99, 0xffff0000, v99
	v_lshlrev_b32_e32 v106, 16, v100
	v_and_b32_e32 v107, 0xffff0000, v100
	v_lshlrev_b32_e32 v100, 16, v101
	v_and_b32_e32 v101, 0xffff0000, v101
	v_pk_add_f32 v[98:99], v[96:97], v[98:99]
	v_pk_add_f32 v[104:105], v[94:95], v[104:105]
	v_pk_add_f32 v[100:101], v[92:93], v[100:101]
	v_pk_add_f32 v[106:107], v[90:91], v[106:107]
	v_cvt_pk_bf16_f32 v90, v104, v105
	v_cvt_pk_bf16_f32 v91, v98, v99
	v_mul_f32_e32 v105, v105, v105
	v_cvt_pk_bf16_f32 v92, v106, v107
	v_cvt_pk_bf16_f32 v93, v100, v101
	flat_load_dwordx4 v[94:97], v[102:103] offset:256
	v_mul_f32_e32 v99, v99, v99
	v_mul_f32_e32 v107, v107, v107
	v_mul_f32_e32 v101, v101, v101
	v_fmac_f32_e32 v105, v104, v104
	v_fmac_f32_e32 v99, v98, v98
	v_fmac_f32_e32 v107, v106, v106
	v_fmac_f32_e32 v101, v100, v100
	v_add_f32_e32 v98, v105, v99
	v_add_f32_e32 v99, v107, v101
	v_add_f32_e32 v104, v98, v99
	flat_store_dwordx4 v[102:103], v[90:93] sc1
	s_waitcnt vmcnt(0) lgkmcnt(0)
	v_lshlrev_b32_e32 v98, 16, v94
	v_and_b32_e32 v99, 0xffff0000, v94
	v_lshlrev_b32_e32 v94, 16, v95
	v_and_b32_e32 v95, 0xffff0000, v95
	v_lshlrev_b32_e32 v100, 16, v96
	v_and_b32_e32 v101, 0xffff0000, v96
	v_lshlrev_b32_e32 v96, 16, v97
	v_and_b32_e32 v97, 0xffff0000, v97
	v_pk_add_f32 v[88:89], v[88:89], v[94:95]
	v_pk_add_f32 v[86:87], v[86:87], v[98:99]
	v_pk_add_f32 v[94:95], v[84:85], v[96:97]
	v_pk_add_f32 v[96:97], v[82:83], v[100:101]
	v_mul_f32_e32 v82, v87, v87
	v_mul_f32_e32 v83, v89, v89
	v_mul_f32_e32 v84, v97, v97
	v_mul_f32_e32 v85, v95, v95
	v_fmac_f32_e32 v82, v86, v86
	v_fmac_f32_e32 v83, v88, v88
	v_fmac_f32_e32 v84, v96, v96
	v_fmac_f32_e32 v85, v94, v94
	v_add_f32_e32 v82, v82, v83
	v_add_f32_e32 v83, v84, v85
	v_add_f32_e32 v82, v82, v83
	v_add_f32_e32 v82, v104, v82
	ds_bpermute_b32 v83, v122, v82
	v_cvt_pk_bf16_f32 v84, v86, v87
	v_cvt_pk_bf16_f32 v85, v88, v89
	v_cvt_pk_bf16_f32 v86, v96, v97
	v_cvt_pk_bf16_f32 v87, v94, v95
	s_waitcnt lgkmcnt(0)
	v_add_f32_e32 v82, v82, v83
	ds_bpermute_b32 v83, v114, v82
	flat_store_dwordx4 v[102:103], v[84:87] offset:256 sc1
	s_and_saveexec_b64 s[48:49], s[2:3]
	s_cbranch_execz .LBB0_526
	s_waitcnt lgkmcnt(0)
	v_add_f32_e32 v82, v82, v83
	ds_write_b32 v154, v82 offset:512
.LBB0_526:
	s_or_b64 exec, exec, s[48:49]
	v_or_b32_e32 v82, 48, v148
	s_waitcnt lgkmcnt(0)
	v_ashrrev_i32_e32 v83, 31, v82
	v_lshlrev_b64 v[82:83], 12, v[82:83]
	v_lshl_add_u64 v[82:83], s[18:19], 0, v[82:83]
	v_lshl_add_u64 v[86:87], v[146:147], 1, v[82:83]
	flat_load_dwordx4 v[82:85], v[86:87]
	s_waitcnt vmcnt(0) lgkmcnt(0)
	v_lshlrev_b32_e32 v88, 16, v82
	v_and_b32_e32 v89, 0xffff0000, v82
	v_lshlrev_b32_e32 v82, 16, v83
	v_and_b32_e32 v83, 0xffff0000, v83
	v_lshlrev_b32_e32 v90, 16, v84
	v_and_b32_e32 v91, 0xffff0000, v84
	v_lshlrev_b32_e32 v84, 16, v85
	v_and_b32_e32 v85, 0xffff0000, v85
	v_pk_add_f32 v[82:83], v[80:81], v[82:83]
	v_pk_add_f32 v[88:89], v[78:79], v[88:89]
	v_pk_add_f32 v[84:85], v[76:77], v[84:85]
	v_pk_add_f32 v[90:91], v[74:75], v[90:91]
	v_cvt_pk_bf16_f32 v74, v88, v89
	v_cvt_pk_bf16_f32 v75, v82, v83
	v_mul_f32_e32 v89, v89, v89
	v_cvt_pk_bf16_f32 v76, v90, v91
	v_cvt_pk_bf16_f32 v77, v84, v85
	flat_load_dwordx4 v[78:81], v[86:87] offset:256
	v_mul_f32_e32 v83, v83, v83
	v_mul_f32_e32 v91, v91, v91
	v_mul_f32_e32 v85, v85, v85
	v_fmac_f32_e32 v89, v88, v88
	v_fmac_f32_e32 v83, v82, v82
	v_fmac_f32_e32 v91, v90, v90
	v_fmac_f32_e32 v85, v84, v84
	v_add_f32_e32 v82, v89, v83
	v_add_f32_e32 v83, v91, v85
	v_add_f32_e32 v88, v82, v83
	flat_store_dwordx4 v[86:87], v[74:77] sc1
	s_waitcnt vmcnt(0) lgkmcnt(0)
	v_lshlrev_b32_e32 v82, 16, v78
	v_and_b32_e32 v83, 0xffff0000, v78
	v_lshlrev_b32_e32 v78, 16, v79
	v_and_b32_e32 v79, 0xffff0000, v79
	v_lshlrev_b32_e32 v84, 16, v80
	v_and_b32_e32 v85, 0xffff0000, v80
	v_lshlrev_b32_e32 v80, 16, v81
	v_and_b32_e32 v81, 0xffff0000, v81
	v_pk_add_f32 v[72:73], v[72:73], v[78:79]
	v_pk_add_f32 v[70:71], v[70:71], v[82:83]
	v_pk_add_f32 v[78:79], v[68:69], v[80:81]
	v_pk_add_f32 v[80:81], v[66:67], v[84:85]
	v_mul_f32_e32 v66, v71, v71
	v_mul_f32_e32 v67, v73, v73
	v_mul_f32_e32 v68, v81, v81
	v_mul_f32_e32 v69, v79, v79
	v_fmac_f32_e32 v66, v70, v70
	v_fmac_f32_e32 v67, v72, v72
	v_fmac_f32_e32 v68, v80, v80
	v_fmac_f32_e32 v69, v78, v78
	v_add_f32_e32 v66, v66, v67
	v_add_f32_e32 v67, v68, v69
	v_add_f32_e32 v66, v66, v67
	v_add_f32_e32 v66, v88, v66
	ds_bpermute_b32 v67, v122, v66
	v_cvt_pk_bf16_f32 v68, v70, v71
	v_cvt_pk_bf16_f32 v69, v72, v73
	v_cvt_pk_bf16_f32 v70, v80, v81
	v_cvt_pk_bf16_f32 v71, v78, v79
	s_waitcnt lgkmcnt(0)
	v_add_f32_e32 v66, v66, v67
	ds_bpermute_b32 v67, v114, v66
	flat_store_dwordx4 v[86:87], v[68:71] offset:256 sc1
	s_and_saveexec_b64 s[48:49], s[2:3]
	s_cbranch_execz .LBB0_528
	s_waitcnt lgkmcnt(0)
	v_add_f32_e32 v66, v66, v67
	ds_write_b32 v154, v66 offset:768
; __device__ __forceinline__ u32x4 pack8(const f32x4 v0, const f32x4 v1) { u32x4 w; w.x = cvt_pk_bf16(v0[0], v0[1]); w.y = cvt_pk_bf16(v0[2], v0[3]); w.z = cvt_pk_bf16(v1[0], v1[1]); w.w = cvt_pk_bf16(v1[2], v1[3]); return w; }
;     __device__ __forceinline__ void operator()(const f32x4 (&acc)[2][2][4][2], const Unit& u, int wr, int wc, int fr, int fq) const {
;     ...
;         for (int ai = 0; ai < 2; ++ai)
; #pragma unroll
;             for (int m = 0; m < 4; ++m) { const int row = row0 + ai * HALF + m * 16; const size_t off = (size_t)row * ldc + col0; float ss = 0.f;
; #pragma unroll
;                 for (int bj = 0; bj < 2; ++bj) { const u32x4 w = *(const u32x4*)(hb + off + bj * HALF);
;                     const f32x4 x0 = {__builtin_bit_cast(float, w.x << 16), __builtin_bit_cast(float, w.x & 0xffff0000u), __builtin_bit_cast(float, w.y << 16), __builtin_bit_cast(float, w.y & 0xffff0000u)};
;                     const f32x4 x1 = {__builtin_bit_cast(float, w.z << 16), __builtin_bit_cast(float, w.z & 0xffff0000u), __builtin_bit_cast(float, w.w << 16), __builtin_bit_cast(float, w.w & 0xffff0000u)};
;                     const f32x4 h0 = x0 + acc[ai][bj][m][0], h1 = x1 + acc[ai][bj][m][1];
;                     ss += ((h0[0] * h0[0] + h0[1] * h0[1]) + (h0[2] * h0[2] + h0[3] * h0[3])) + ((h1[0] * h1[0] + h1[1] * h1[1]) + (h1[2] * h1[2] + h1[3] * h1[3]));
;                     *(u32x4*)(hb + off + bj * HALF) = pack8(h0, h1); }
;                 ss += __shfl_xor(ss, 16); ss += __shfl_xor(ss, 32);
;                 if (fq == 0) red[(ai * HALF + wr * 64 + m * 16 + fr) * 4 + wc] = ss; }
.LBB0_528:
	s_or_b64 exec, exec, s[48:49]
	s_waitcnt lgkmcnt(0)
	v_lshlrev_b64 v[66:67], 12, v[148:149]
	v_lshl_add_u64 v[66:67], s[18:19], 0, v[66:67]
	v_lshl_add_u64 v[66:67], v[146:147], 1, v[66:67]
	v_add_co_u32_e32 v72, vcc, 0x80000, v66
	v_lshl_add_u64 v[74:75], v[66:67], 0, s[14:15]
	s_nop 0
	v_addc_co_u32_e32 v73, vcc, 0, v67, vcc
	flat_load_dwordx4 v[68:71], v[72:73]
	s_waitcnt vmcnt(0) lgkmcnt(0)
	v_lshlrev_b32_e32 v76, 16, v68
	v_and_b32_e32 v77, 0xffff0000, v68
	v_lshlrev_b32_e32 v68, 16, v69
	v_and_b32_e32 v69, 0xffff0000, v69
	v_lshlrev_b32_e32 v78, 16, v70
	v_and_b32_e32 v79, 0xffff0000, v70
	v_lshlrev_b32_e32 v70, 16, v71
	v_and_b32_e32 v71, 0xffff0000, v71
	v_pk_add_f32 v[68:69], v[64:65], v[68:69]
	v_pk_add_f32 v[76:77], v[62:63], v[76:77]
	v_pk_add_f32 v[70:71], v[60:61], v[70:71]
	v_pk_add_f32 v[78:79], v[58:59], v[78:79]
	v_cvt_pk_bf16_f32 v58, v76, v77
	v_cvt_pk_bf16_f32 v59, v68, v69
	v_mul_f32_e32 v77, v77, v77
	v_cvt_pk_bf16_f32 v60, v78, v79
	v_cvt_pk_bf16_f32 v61, v70, v71
	flat_load_dwordx4 v[62:65], v[74:75] offset:256
	v_mul_f32_e32 v69, v69, v69
	v_mul_f32_e32 v79, v79, v79
	v_mul_f32_e32 v71, v71, v71
	v_fmac_f32_e32 v77, v76, v76
	v_fmac_f32_e32 v69, v68, v68
	v_fmac_f32_e32 v79, v78, v78
	v_fmac_f32_e32 v71, v70, v70
	v_add_f32_e32 v68, v77, v69
	v_add_f32_e32 v69, v79, v71
	v_add_f32_e32 v76, v68, v69
	flat_store_dwordx4 v[72:73], v[58:61] sc1
	s_waitcnt vmcnt(0) lgkmcnt(0)
	v_lshlrev_b32_e32 v68, 16, v62
	v_and_b32_e32 v69, 0xffff0000, v62
	v_lshlrev_b32_e32 v62, 16, v63
	v_and_b32_e32 v63, 0xffff0000, v63
	v_lshlrev_b32_e32 v70, 16, v64
	v_and_b32_e32 v71, 0xffff0000, v64
	v_lshlrev_b32_e32 v64, 16, v65
	v_and_b32_e32 v65, 0xffff0000, v65
	v_pk_add_f32 v[56:57], v[56:57], v[62:63]
	v_pk_add_f32 v[54:55], v[54:55], v[68:69]
	v_pk_add_f32 v[62:63], v[52:53], v[64:65]
	v_pk_add_f32 v[64:65], v[50:51], v[70:71]
	v_mul_f32_e32 v50, v55, v55
	v_mul_f32_e32 v51, v57, v57
	v_mul_f32_e32 v52, v65, v65
	v_mul_f32_e32 v53, v63, v63
	v_fmac_f32_e32 v50, v54, v54
	v_fmac_f32_e32 v51, v56, v56
	v_fmac_f32_e32 v52, v64, v64
	v_fmac_f32_e32 v53, v62, v62
	v_add_f32_e32 v50, v50, v51
	v_add_f32_e32 v51, v52, v53
	v_add_f32_e32 v50, v50, v51
	v_add_f32_e32 v50, v76, v50
	ds_bpermute_b32 v51, v122, v50
	v_cvt_pk_bf16_f32 v52, v54, v55
	v_cvt_pk_bf16_f32 v53, v56, v57
	v_cvt_pk_bf16_f32 v54, v64, v65
	v_cvt_pk_bf16_f32 v55, v62, v63
	s_waitcnt lgkmcnt(0)
	v_add_f32_e32 v50, v50, v51
	ds_bpermute_b32 v51, v114, v50
	flat_store_dwordx4 v[74:75], v[52:55] offset:256 sc1
	s_and_saveexec_b64 s[48:49], s[2:3]
	s_cbranch_execz .LBB0_530
	s_waitcnt lgkmcnt(0)
	v_add_f32_e32 v50, v50, v51
	ds_write_b32 v154, v50 offset:2048
.LBB0_530:
	s_or_b64 exec, exec, s[48:49]
	v_add_co_u32_e32 v54, vcc, 0x90000, v66
	v_lshl_add_u64 v[56:57], v[66:67], 0, s[26:27]
	s_nop 0
	v_addc_co_u32_e32 v55, vcc, 0, v67, vcc
	s_waitcnt lgkmcnt(0)
	flat_load_dwordx4 v[50:53], v[54:55]
	s_waitcnt vmcnt(0) lgkmcnt(0)
	v_lshlrev_b32_e32 v58, 16, v50
	v_and_b32_e32 v59, 0xffff0000, v50
	v_lshlrev_b32_e32 v50, 16, v51
	v_and_b32_e32 v51, 0xffff0000, v51
	v_lshlrev_b32_e32 v60, 16, v52
	v_and_b32_e32 v61, 0xffff0000, v52
	v_lshlrev_b32_e32 v52, 16, v53
	v_and_b32_e32 v53, 0xffff0000, v53
	v_pk_add_f32 v[50:51], v[48:49], v[50:51]
	v_pk_add_f32 v[58:59], v[46:47], v[58:59]
	v_pk_add_f32 v[52:53], v[44:45], v[52:53]
	v_pk_add_f32 v[60:61], v[42:43], v[60:61]
	v_cvt_pk_bf16_f32 v42, v58, v59
	v_cvt_pk_bf16_f32 v43, v50, v51
	v_mul_f32_e32 v59, v59, v59
	v_cvt_pk_bf16_f32 v44, v60, v61
	v_cvt_pk_bf16_f32 v45, v52, v53
	flat_load_dwordx4 v[46:49], v[56:57] offset:256
	v_mul_f32_e32 v51, v51, v51
	v_mul_f32_e32 v61, v61, v61
	v_mul_f32_e32 v53, v53, v53
	v_fmac_f32_e32 v59, v58, v58
	v_fmac_f32_e32 v51, v50, v50
	v_fmac_f32_e32 v61, v60, v60
	v_fmac_f32_e32 v53, v52, v52
	v_add_f32_e32 v50, v59, v51
	v_add_f32_e32 v51, v61, v53
	v_add_f32_e32 v58, v50, v51
	flat_store_dwordx4 v[54:55], v[42:45] sc1
	s_waitcnt vmcnt(0) lgkmcnt(0)
	v_lshlrev_b32_e32 v50, 16, v46
	v_and_b32_e32 v51, 0xffff0000, v46
	v_lshlrev_b32_e32 v46, 16, v47
	v_and_b32_e32 v47, 0xffff0000, v47
	v_lshlrev_b32_e32 v52, 16, v48
	v_and_b32_e32 v53, 0xffff0000, v48
	v_lshlrev_b32_e32 v48, 16, v49
	v_and_b32_e32 v49, 0xffff0000, v49
	v_pk_add_f32 v[40:41], v[40:41], v[46:47]
	v_pk_add_f32 v[38:39], v[38:39], v[50:51]
	v_pk_add_f32 v[46:47], v[36:37], v[48:49]
	v_pk_add_f32 v[48:49], v[34:35], v[52:53]
	v_mul_f32_e32 v34, v39, v39
	v_mul_f32_e32 v35, v41, v41
	v_mul_f32_e32 v36, v49, v49
	v_mul_f32_e32 v37, v47, v47
	v_fmac_f32_e32 v34, v38, v38
	v_fmac_f32_e32 v35, v40, v40
	v_fmac_f32_e32 v36, v48, v48
	v_fmac_f32_e32 v37, v46, v46
	v_add_f32_e32 v34, v34, v35
	v_add_f32_e32 v35, v36, v37
	v_add_f32_e32 v34, v34, v35
	v_add_f32_e32 v34, v58, v34
	ds_bpermute_b32 v35, v122, v34
	v_cvt_pk_bf16_f32 v36, v38, v39
	v_cvt_pk_bf16_f32 v37, v40, v41
	v_cvt_pk_bf16_f32 v38, v48, v49
	v_cvt_pk_bf16_f32 v39, v46, v47
	s_waitcnt lgkmcnt(0)
	v_add_f32_e32 v34, v34, v35
	ds_bpermute_b32 v35, v114, v34
	flat_store_dwordx4 v[56:57], v[36:39] offset:256 sc1
	s_and_saveexec_b64 s[48:49], s[2:3]
	s_cbranch_execz .LBB0_532
	s_waitcnt lgkmcnt(0)
	v_add_f32_e32 v34, v34, v35
	ds_write_b32 v154, v34 offset:2304
; #define PG8_LAS __attribute__((address_space(3)))
; __device__ __forceinline__ u32x4 pack8(const f32x4 v0, const f32x4 v1) { u32x4 w; w.x = cvt_pk_bf16(v0[0], v0[1]); w.y = cvt_pk_bf16(v0[2], v0[3]); w.z = cvt_pk_bf16(v1[0], v1[1]); w.w = cvt_pk_bf16(v1[2], v1[3]); return w; }
;     __device__ __forceinline__ void operator()(const f32x4 (&acc)[2][2][4][2], const Unit& u, int wr, int wc, int fr, int fq) const {
;     ...
;         for (int ai = 0; ai < 2; ++ai)
; #pragma unroll
;             for (int m = 0; m < 4; ++m) { const int row = row0 + ai * HALF + m * 16; const size_t off = (size_t)row * ldc + col0; float ss = 0.f;
; #pragma unroll
;                 for (int bj = 0; bj < 2; ++bj) { const u32x4 w = *(const u32x4*)(hb + off + bj * HALF);
;                     const f32x4 x0 = {__builtin_bit_cast(float, w.x << 16), __builtin_bit_cast(float, w.x & 0xffff0000u), __builtin_bit_cast(float, w.y << 16), __builtin_bit_cast(float, w.y & 0xffff0000u)};
;                     const f32x4 x1 = {__builtin_bit_cast(float, w.z << 16), __builtin_bit_cast(float, w.z & 0xffff0000u), __builtin_bit_cast(float, w.w << 16), __builtin_bit_cast(float, w.w & 0xffff0000u)};
;                     const f32x4 h0 = x0 + acc[ai][bj][m][0], h1 = x1 + acc[ai][bj][m][1];
;                     ss += ((h0[0] * h0[0] + h0[1] * h0[1]) + (h0[2] * h0[2] + h0[3] * h0[3])) + ((h1[0] * h1[0] + h1[1] * h1[1]) + (h1[2] * h1[2] + h1[3] * h1[3]));
;                     *(u32x4*)(hb + off + bj * HALF) = pack8(h0, h1); }
;                 ss += __shfl_xor(ss, 16); ss += __shfl_xor(ss, 32);
;                 if (fq == 0) red[(ai * HALF + wr * 64 + m * 16 + fr) * 4 + wc] = ss; }
;         asm volatile("s_waitcnt lgkmcnt(0)" ::: "memory"); __builtin_amdgcn_s_barrier(); asm volatile("" ::: "memory");
;         { const int t = threadIdx.x; if (t < 256) { const f32x4 p = *(const PG8_LAS f32x4*)(red + t * 4); rss[(size_t)(u.pm * BM + t) * 8 + u.pn] = (p[0] + p[1]) + (p[2] + p[3]); } }
.LBB0_532:
	s_or_b64 exec, exec, s[48:49]
	s_waitcnt lgkmcnt(0)
	v_lshlrev_b64 v[34:35], 12, v[148:149]
	v_lshl_add_u64 v[34:35], s[18:19], 0, v[34:35]
	v_lshl_add_u64 v[34:35], v[146:147], 1, v[34:35]
	v_add_co_u32_e32 v40, vcc, 0xa0000, v34
	v_lshl_add_u64 v[42:43], v[34:35], 0, s[36:37]
	s_nop 0
	v_addc_co_u32_e32 v41, vcc, 0, v35, vcc
	flat_load_dwordx4 v[36:39], v[40:41]
	s_waitcnt vmcnt(0) lgkmcnt(0)
	v_lshlrev_b32_e32 v44, 16, v36
	v_and_b32_e32 v45, 0xffff0000, v36
	v_lshlrev_b32_e32 v36, 16, v37
	v_and_b32_e32 v37, 0xffff0000, v37
	v_lshlrev_b32_e32 v46, 16, v38
	v_and_b32_e32 v47, 0xffff0000, v38
	v_lshlrev_b32_e32 v38, 16, v39
	v_and_b32_e32 v39, 0xffff0000, v39
	v_pk_add_f32 v[36:37], v[32:33], v[36:37]
	v_pk_add_f32 v[44:45], v[30:31], v[44:45]
	v_pk_add_f32 v[38:39], v[28:29], v[38:39]
	v_pk_add_f32 v[46:47], v[26:27], v[46:47]
	v_cvt_pk_bf16_f32 v26, v44, v45
	v_cvt_pk_bf16_f32 v27, v36, v37
	v_mul_f32_e32 v45, v45, v45
	v_cvt_pk_bf16_f32 v28, v46, v47
	v_cvt_pk_bf16_f32 v29, v38, v39
	flat_load_dwordx4 v[30:33], v[42:43] offset:256
	v_mul_f32_e32 v37, v37, v37
	v_mul_f32_e32 v47, v47, v47
	v_mul_f32_e32 v39, v39, v39
	v_fmac_f32_e32 v45, v44, v44
	v_fmac_f32_e32 v37, v36, v36
	v_fmac_f32_e32 v47, v46, v46
	v_fmac_f32_e32 v39, v38, v38
	v_add_f32_e32 v36, v45, v37
	v_add_f32_e32 v37, v47, v39
	v_add_f32_e32 v44, v36, v37
	flat_store_dwordx4 v[40:41], v[26:29] sc1
	s_waitcnt vmcnt(0) lgkmcnt(0)
	v_lshlrev_b32_e32 v36, 16, v30
	v_and_b32_e32 v37, 0xffff0000, v30
	v_lshlrev_b32_e32 v30, 16, v31
	v_and_b32_e32 v31, 0xffff0000, v31
	v_lshlrev_b32_e32 v38, 16, v32
	v_and_b32_e32 v39, 0xffff0000, v32
	v_lshlrev_b32_e32 v32, 16, v33
	v_and_b32_e32 v33, 0xffff0000, v33
	v_pk_add_f32 v[24:25], v[24:25], v[30:31]
	v_pk_add_f32 v[22:23], v[22:23], v[36:37]
	v_pk_add_f32 v[30:31], v[20:21], v[32:33]
	v_pk_add_f32 v[32:33], v[18:19], v[38:39]
	v_mul_f32_e32 v18, v23, v23
	v_mul_f32_e32 v19, v25, v25
	v_mul_f32_e32 v20, v33, v33
	v_mul_f32_e32 v21, v31, v31
	v_fmac_f32_e32 v18, v22, v22
	v_fmac_f32_e32 v19, v24, v24
	v_fmac_f32_e32 v20, v32, v32
	v_fmac_f32_e32 v21, v30, v30
	v_add_f32_e32 v18, v18, v19
	v_add_f32_e32 v19, v20, v21
	v_add_f32_e32 v18, v18, v19
	v_add_f32_e32 v18, v44, v18
	ds_bpermute_b32 v19, v122, v18
	v_cvt_pk_bf16_f32 v20, v22, v23
	v_cvt_pk_bf16_f32 v21, v24, v25
	v_cvt_pk_bf16_f32 v22, v32, v33
	v_cvt_pk_bf16_f32 v23, v30, v31
	s_waitcnt lgkmcnt(0)
	v_add_f32_e32 v18, v18, v19
	ds_bpermute_b32 v19, v114, v18
	flat_store_dwordx4 v[42:43], v[20:23] offset:256 sc1
	s_and_saveexec_b64 s[48:49], s[2:3]
	s_cbranch_execz .LBB0_534
	s_waitcnt lgkmcnt(0)
	v_add_f32_e32 v18, v18, v19
	ds_write_b32 v154, v18 offset:2560
.LBB0_534:
	s_or_b64 exec, exec, s[48:49]
	v_add_co_u32_e32 v22, vcc, 0xb0000, v34
	v_lshl_add_u64 v[24:25], v[34:35], 0, s[38:39]
	s_nop 0
	v_addc_co_u32_e32 v23, vcc, 0, v35, vcc
	s_waitcnt lgkmcnt(0)
	flat_load_dwordx4 v[18:21], v[22:23]
	s_waitcnt vmcnt(0) lgkmcnt(0)
	v_lshlrev_b32_e32 v26, 16, v18
	v_and_b32_e32 v27, 0xffff0000, v18
	v_lshlrev_b32_e32 v18, 16, v19
	v_and_b32_e32 v19, 0xffff0000, v19
	v_lshlrev_b32_e32 v28, 16, v20
	v_and_b32_e32 v29, 0xffff0000, v20
	v_lshlrev_b32_e32 v20, 16, v21
	v_and_b32_e32 v21, 0xffff0000, v21
	v_pk_add_f32 v[18:19], v[16:17], v[18:19]
	v_pk_add_f32 v[26:27], v[14:15], v[26:27]
	v_pk_add_f32 v[20:21], v[12:13], v[20:21]
	v_pk_add_f32 v[28:29], v[10:11], v[28:29]
	v_cvt_pk_bf16_f32 v10, v26, v27
	v_cvt_pk_bf16_f32 v11, v18, v19
	v_mul_f32_e32 v27, v27, v27
	v_cvt_pk_bf16_f32 v12, v28, v29
	v_cvt_pk_bf16_f32 v13, v20, v21
	flat_load_dwordx4 v[14:17], v[24:25] offset:256
	v_mul_f32_e32 v19, v19, v19
	v_mul_f32_e32 v29, v29, v29
	v_mul_f32_e32 v21, v21, v21
	v_fmac_f32_e32 v27, v26, v26
	v_fmac_f32_e32 v19, v18, v18
	v_fmac_f32_e32 v29, v28, v28
	v_fmac_f32_e32 v21, v20, v20
	v_add_f32_e32 v18, v27, v19
	v_add_f32_e32 v19, v29, v21
	v_add_f32_e32 v26, v18, v19
	flat_store_dwordx4 v[22:23], v[10:13] sc1
	s_waitcnt vmcnt(0) lgkmcnt(0)
	v_lshlrev_b32_e32 v18, 16, v14
	v_and_b32_e32 v19, 0xffff0000, v14
	v_lshlrev_b32_e32 v14, 16, v15
	v_and_b32_e32 v15, 0xffff0000, v15
	v_lshlrev_b32_e32 v20, 16, v16
	v_and_b32_e32 v21, 0xffff0000, v16
	v_lshlrev_b32_e32 v16, 16, v17
	v_and_b32_e32 v17, 0xffff0000, v17
	v_pk_add_f32 v[8:9], v[8:9], v[14:15]
	v_pk_add_f32 v[6:7], v[6:7], v[18:19]
	v_pk_add_f32 v[14:15], v[4:5], v[16:17]
	v_pk_add_f32 v[16:17], v[2:3], v[20:21]
	v_mul_f32_e32 v2, v7, v7
	v_mul_f32_e32 v3, v9, v9
	v_mul_f32_e32 v4, v17, v17
	v_mul_f32_e32 v5, v15, v15
	v_fmac_f32_e32 v2, v6, v6
	v_fmac_f32_e32 v3, v8, v8
	v_fmac_f32_e32 v4, v16, v16
	v_fmac_f32_e32 v5, v14, v14
	v_add_f32_e32 v2, v2, v3
	v_add_f32_e32 v3, v4, v5
	v_add_f32_e32 v2, v2, v3
	v_add_f32_e32 v2, v26, v2
	ds_bpermute_b32 v3, v122, v2
	v_cvt_pk_bf16_f32 v4, v6, v7
	v_cvt_pk_bf16_f32 v5, v8, v9
	v_cvt_pk_bf16_f32 v6, v16, v17
	v_cvt_pk_bf16_f32 v7, v14, v15
	s_waitcnt lgkmcnt(0)
	v_add_f32_e32 v2, v2, v3
	ds_bpermute_b32 v3, v114, v2
	flat_store_dwordx4 v[24:25], v[4:7] offset:256 sc1
	s_and_saveexec_b64 s[48:49], s[2:3]
	s_cbranch_execz .LBB0_536
	s_waitcnt lgkmcnt(0)
	v_add_f32_e32 v2, v2, v3
	ds_write_b32 v154, v2 offset:2816
.LBB0_536:
	s_or_b64 exec, exec, s[48:49]
	s_waitcnt lgkmcnt(0)
	s_barrier
	s_and_saveexec_b64 s[48:49], s[4:5]
	s_cbranch_execz .LBB0_538
	v_add_u32_e32 v2, 0, v150
	v_add_u32_e32 v2, 0x20000, v2
	s_waitcnt lgkmcnt(0)
	ds_read_b128 v[2:5], v2
	v_or_b32_e32 v6, s13, v200
	v_ashrrev_i32_e32 v7, 31, v6
	s_ashr_i32 s13, s12, 31
	s_waitcnt lgkmcnt(0)
	v_mov_b32_e32 v8, v3
	v_mov_b32_e32 v9, v4
	v_mov_b32_e32 v3, v5
	v_pk_add_f32 v[2:3], v[8:9], v[2:3]
	s_nop 0
	v_add_f32_e32 v4, v2, v3
	v_lshlrev_b64 v[2:3], 5, v[6:7]
	v_lshl_add_u64 v[2:3], s[20:21], 0, v[2:3]
	v_lshl_add_u64 v[2:3], s[12:13], 2, v[2:3]
	flat_store_dword v[2:3], v4 sc1
